# all six gemm2 K-loops (phases 2,4,6a,6b,7b,9) replaced by the hand-written 8-phase LDS-DMA core; epilogues unchanged
# speedup vs baseline: 1.1104x; 1.0917x over previous
.LBB0_224:
	s_add_u32 s12, s90, s2
	s_addc_u32 s37, s91, s3
	s_ashr_i32 s35, s34, 31
	s_lshl_b64 s[6:7], s[34:35], 18
	s_lshl_b64 s[2:3], s[34:35], 19
	s_add_u32 s2, s12, s2
	s_addc_u32 s3, s37, s3
	s_mov_b32 s56, s2
	s_mov_b32 s57, s3
	s_ashr_i32 s37, s36, 31
	s_lshl_b64 s[2:3], s[36:37], 19
	s_add_u32 s2, s90, s2
	s_addc_u32 s3, s91, s3
	s_mov_b32 s58, s2
	s_mov_b32 s59, s3
	s_movk_i32 s2, 0x100
	s_mov_b32 s3, -2
	v_lshrrev_b32_e32 v232, 6, v208
	v_and_b32_e32 v233, 63, v208
	v_readfirstlane_b32 s98, v232
	v_and_b32_e32 v234, 3, v233
	v_bfe_u32 v235, v233, 2, 1
	v_lshl_or_b32 v234, v235, 3, v234
	v_bfe_u32 v235, v233, 3, 1
	v_lshl_or_b32 v234, v235, 2, v234
	s_and_b32 s55, s98, 1
	s_lshr_b32 s100, s98, 2
	s_lshl_b32 s99, s98, 10
	v_lshrrev_b32_e32 v235, 4, v233
	v_bfe_u32 v236, v234, 1, 3
	v_xor_b32_e32 v236, v235, v236
	v_lshlrev_b32_e32 v236, 4, v236
	v_lshl_add_u32 v234, s55, 6, v234
	v_lshl_add_u32 v170, v234, 7, v236
	v_xor_b32_e32 v197, 64, v170
	v_add_u32_e32 v196, 0x10000, v170
	v_add_u32_e32 v198, 0x10000, v197
	v_bfe_u32 v236, v233, 1, 3
	v_xor_b32_e32 v236, v235, v236
	v_lshlrev_b32_e32 v236, 4, v236
	v_and_b32_e32 v234, 15, v233
	s_lshr_b32 s101, s98, 1
	v_lshl_add_u32 v234, s101, 5, v234
	v_lshl_add_u32 v199, v234, 7, v236
	v_add_u32_e32 v199, 0x8000, v199
	v_xor_b32_e32 v201, 64, v199
	v_add_u32_e32 v200, 0x10000, v199
	v_add_u32_e32 v202, 0x10000, v201
	v_lshl_add_u32 v236, s55, 2, v235
	v_and_b32_e32 v234, 7, v233
	v_xor_b32_e32 v236, v234, v236
	v_lshlrev_b32_e32 v236, 4, v236
	v_lshrrev_b32_e32 v234, 3, v233
	v_lshl_add_u32 v235, s98, 3, v234
	v_lshl_add_u32 v203, v235, 11, v236
	v_add_u32_e32 v204, 0x40000, v203
	v_add_u32_e32 v205, 0x20000, v203
	v_add_u32_e32 v206, 0x60000, v203
	s_and_b32 s101, s98, 3
	s_lshl_b32 s101, s101, 3
	s_lshl_b32 s55, s100, 6
	s_add_u32 s101, s101, s55
	v_add_u32_e32 v235, s101, v234
	v_lshl_add_u32 v207, v235, 11, v236
	v_add_u32_e32 v229, 0x40000, v207
	v_add_u32_e32 v230, 0x10000, v207
	v_add_u32_e32 v231, 0x50000, v207
	v_mov_b32_e32 v112, 0
	v_mov_b32_e32 v113, 0
	v_mov_b32_e32 v114, 0
	v_mov_b32_e32 v115, 0
	v_mov_b32_e32 v116, 0
	v_mov_b32_e32 v117, 0
	v_mov_b32_e32 v118, 0
	v_mov_b32_e32 v119, 0
	v_mov_b32_e32 v120, 0
	v_mov_b32_e32 v121, 0
	v_mov_b32_e32 v122, 0
	v_mov_b32_e32 v123, 0
	v_mov_b32_e32 v124, 0
	v_mov_b32_e32 v125, 0
	v_mov_b32_e32 v126, 0
	v_mov_b32_e32 v127, 0
	v_mov_b32_e32 v80, 0
	v_mov_b32_e32 v81, 0
	v_mov_b32_e32 v82, 0
	v_mov_b32_e32 v83, 0
	v_mov_b32_e32 v84, 0
	v_mov_b32_e32 v85, 0
	v_mov_b32_e32 v86, 0
	v_mov_b32_e32 v87, 0
	v_mov_b32_e32 v88, 0
	v_mov_b32_e32 v89, 0
	v_mov_b32_e32 v90, 0
	v_mov_b32_e32 v91, 0
	v_mov_b32_e32 v92, 0
	v_mov_b32_e32 v93, 0
	v_mov_b32_e32 v94, 0
	v_mov_b32_e32 v95, 0
	v_mov_b32_e32 v96, 0
	v_mov_b32_e32 v97, 0
	v_mov_b32_e32 v98, 0
	v_mov_b32_e32 v99, 0
	v_mov_b32_e32 v100, 0
	v_mov_b32_e32 v101, 0
	v_mov_b32_e32 v102, 0
	v_mov_b32_e32 v103, 0
	v_mov_b32_e32 v104, 0
	v_mov_b32_e32 v105, 0
	v_mov_b32_e32 v106, 0
	v_mov_b32_e32 v107, 0
	v_mov_b32_e32 v108, 0
	v_mov_b32_e32 v109, 0
	v_mov_b32_e32 v110, 0
	v_mov_b32_e32 v111, 0
	v_mov_b32_e32 v64, 0
	v_mov_b32_e32 v65, 0
	v_mov_b32_e32 v66, 0
	v_mov_b32_e32 v67, 0
	v_mov_b32_e32 v68, 0
	v_mov_b32_e32 v69, 0
	v_mov_b32_e32 v70, 0
	v_mov_b32_e32 v71, 0
	v_mov_b32_e32 v72, 0
	v_mov_b32_e32 v73, 0
	v_mov_b32_e32 v74, 0
	v_mov_b32_e32 v75, 0
	v_mov_b32_e32 v76, 0
	v_mov_b32_e32 v77, 0
	v_mov_b32_e32 v78, 0
	v_mov_b32_e32 v79, 0
	v_mov_b32_e32 v48, 0
	v_mov_b32_e32 v49, 0
	v_mov_b32_e32 v50, 0
	v_mov_b32_e32 v51, 0
	v_mov_b32_e32 v52, 0
	v_mov_b32_e32 v53, 0
	v_mov_b32_e32 v54, 0
	v_mov_b32_e32 v55, 0
	v_mov_b32_e32 v56, 0
	v_mov_b32_e32 v57, 0
	v_mov_b32_e32 v58, 0
	v_mov_b32_e32 v59, 0
	v_mov_b32_e32 v60, 0
	v_mov_b32_e32 v61, 0
	v_mov_b32_e32 v62, 0
	v_mov_b32_e32 v63, 0
	v_mov_b32_e32 v16, 0
	v_mov_b32_e32 v17, 0
	v_mov_b32_e32 v18, 0
	v_mov_b32_e32 v19, 0
	v_mov_b32_e32 v20, 0
	v_mov_b32_e32 v21, 0
	v_mov_b32_e32 v22, 0
	v_mov_b32_e32 v23, 0
	v_mov_b32_e32 v24, 0
	v_mov_b32_e32 v25, 0
	v_mov_b32_e32 v26, 0
	v_mov_b32_e32 v27, 0
	v_mov_b32_e32 v28, 0
	v_mov_b32_e32 v29, 0
	v_mov_b32_e32 v30, 0
	v_mov_b32_e32 v31, 0
	v_mov_b32_e32 v32, 0
	v_mov_b32_e32 v33, 0
	v_mov_b32_e32 v34, 0
	v_mov_b32_e32 v35, 0
	v_mov_b32_e32 v36, 0
	v_mov_b32_e32 v37, 0
	v_mov_b32_e32 v38, 0
	v_mov_b32_e32 v39, 0
	v_mov_b32_e32 v40, 0
	v_mov_b32_e32 v41, 0
	v_mov_b32_e32 v42, 0
	v_mov_b32_e32 v43, 0
	v_mov_b32_e32 v44, 0
	v_mov_b32_e32 v45, 0
	v_mov_b32_e32 v46, 0
	v_mov_b32_e32 v47, 0
	v_mov_b32_e32 v0, 0
	v_mov_b32_e32 v1, 0
	v_mov_b32_e32 v2, 0
	v_mov_b32_e32 v3, 0
	v_mov_b32_e32 v4, 0
	v_mov_b32_e32 v5, 0
	v_mov_b32_e32 v6, 0
	v_mov_b32_e32 v7, 0
	v_mov_b32_e32 v8, 0
	v_mov_b32_e32 v9, 0
	v_mov_b32_e32 v10, 0
	v_mov_b32_e32 v11, 0
	v_mov_b32_e32 v12, 0
	v_mov_b32_e32 v13, 0
	v_mov_b32_e32 v14, 0
	v_mov_b32_e32 v15, 0
	s_add_u32 m0, s99, 0x8000
	s_nop 0
	global_load_lds_dwordx4 v207, s[56:57]
	s_add_u32 m0, s99, 0xa000
	s_nop 0
	global_load_lds_dwordx4 v229, s[56:57]
	s_add_u32 m0, s99, 0x0
	s_nop 0
	global_load_lds_dwordx4 v203, s[58:59]
	s_add_u32 m0, s99, 0x2000
	s_nop 0
	global_load_lds_dwordx4 v204, s[58:59]
	s_add_u32 m0, s99, 0xc000
	s_nop 0
	global_load_lds_dwordx4 v230, s[56:57]
	s_add_u32 m0, s99, 0xe000
	s_nop 0
	global_load_lds_dwordx4 v231, s[56:57]
	s_add_u32 s56, s56, 0x80
	s_addc_u32 s57, s57, 0
	s_add_u32 m0, s99, 0x4000
	s_nop 0
	global_load_lds_dwordx4 v205, s[58:59]
	s_add_u32 m0, s99, 0x6000
	s_nop 0
	global_load_lds_dwordx4 v206, s[58:59]
	s_add_u32 s58, s58, 0x80
	s_addc_u32 s59, s59, 0
	s_cmp_eq_u32 s100, 0
	s_cbranch_scc1 .Lg8_p2_pg0
	s_barrier
.Lg8_p2_pg0:
	s_waitcnt vmcnt(4)
	s_barrier
	s_add_u32 m0, s99, 0x18000
	s_nop 0
	global_load_lds_dwordx4 v207, s[56:57]
	s_add_u32 m0, s99, 0x1a000
	s_nop 0
	global_load_lds_dwordx4 v229, s[56:57]
	s_add_u32 m0, s99, 0x10000
	s_nop 0
	global_load_lds_dwordx4 v203, s[58:59]
	s_add_u32 m0, s99, 0x12000
	s_nop 0
	global_load_lds_dwordx4 v204, s[58:59]
	s_add_u32 m0, s99, 0x1c000
	s_nop 0
	global_load_lds_dwordx4 v230, s[56:57]
	s_add_u32 m0, s99, 0x1e000
	s_nop 0
	global_load_lds_dwordx4 v231, s[56:57]
	s_add_u32 s56, s56, 0x80
	s_addc_u32 s57, s57, 0
	s_waitcnt vmcnt(6)
	s_barrier
	s_mov_b32 s101, 7
.Lg8_p2_loop:
	ds_read_b128 v[160:163], v199 offset:0
	ds_read_b128 v[164:167], v201 offset:0
	ds_read_b128 v[172:175], v199 offset:2048
	ds_read_b128 v[176:179], v201 offset:2048
	ds_read_b128 v[128:131], v170 offset:0
	ds_read_b128 v[132:135], v197 offset:0
	ds_read_b128 v[136:139], v170 offset:2048
	ds_read_b128 v[140:143], v197 offset:2048
	ds_read_b128 v[144:147], v170 offset:4096
	ds_read_b128 v[148:151], v197 offset:4096
	ds_read_b128 v[152:155], v170 offset:6144
	ds_read_b128 v[156:159], v197 offset:6144
	s_add_u32 m0, s99, 0x14000
	s_nop 0
	global_load_lds_dwordx4 v205, s[58:59]
	s_add_u32 m0, s99, 0x16000
	s_nop 0
	global_load_lds_dwordx4 v206, s[58:59]
	s_add_u32 s58, s58, 0x80
	s_addc_u32 s59, s59, 0
	s_waitcnt lgkmcnt(8)
	s_barrier
	s_waitcnt lgkmcnt(0)
	s_setprio 1
	v_mfma_f32_16x16x32_bf16 v[112:115], v[128:131], v[160:163], v[112:115]
	v_mfma_f32_16x16x32_bf16 v[112:115], v[132:135], v[164:167], v[112:115]
	v_mfma_f32_16x16x32_bf16 v[116:119], v[128:131], v[172:175], v[116:119]
	v_mfma_f32_16x16x32_bf16 v[116:119], v[132:135], v[176:179], v[116:119]
	v_mfma_f32_16x16x32_bf16 v[120:123], v[136:139], v[160:163], v[120:123]
	v_mfma_f32_16x16x32_bf16 v[120:123], v[140:143], v[164:167], v[120:123]
	v_mfma_f32_16x16x32_bf16 v[124:127], v[136:139], v[172:175], v[124:127]
	v_mfma_f32_16x16x32_bf16 v[124:127], v[140:143], v[176:179], v[124:127]
	v_mfma_f32_16x16x32_bf16 v[80:83], v[144:147], v[160:163], v[80:83]
	v_mfma_f32_16x16x32_bf16 v[80:83], v[148:151], v[164:167], v[80:83]
	v_mfma_f32_16x16x32_bf16 v[84:87], v[144:147], v[172:175], v[84:87]
	v_mfma_f32_16x16x32_bf16 v[84:87], v[148:151], v[176:179], v[84:87]
	v_mfma_f32_16x16x32_bf16 v[88:91], v[152:155], v[160:163], v[88:91]
	v_mfma_f32_16x16x32_bf16 v[88:91], v[156:159], v[164:167], v[88:91]
	v_mfma_f32_16x16x32_bf16 v[92:95], v[152:155], v[172:175], v[92:95]
	v_mfma_f32_16x16x32_bf16 v[92:95], v[156:159], v[176:179], v[92:95]
	s_setprio 0
	s_barrier
	ds_read_b128 v[180:183], v199 offset:16384
	ds_read_b128 v[184:187], v201 offset:16384
	ds_read_b128 v[188:191], v199 offset:18432
	ds_read_b128 v[192:195], v201 offset:18432
	s_add_u32 m0, s99, 0x8000
	s_nop 0
	global_load_lds_dwordx4 v207, s[56:57]
	s_add_u32 m0, s99, 0xa000
	s_nop 0
	global_load_lds_dwordx4 v229, s[56:57]
	s_barrier
	s_waitcnt lgkmcnt(0)
	s_setprio 1
	v_mfma_f32_16x16x32_bf16 v[48:51], v[128:131], v[180:183], v[48:51]
	v_mfma_f32_16x16x32_bf16 v[48:51], v[132:135], v[184:187], v[48:51]
	v_mfma_f32_16x16x32_bf16 v[52:55], v[128:131], v[188:191], v[52:55]
	v_mfma_f32_16x16x32_bf16 v[52:55], v[132:135], v[192:195], v[52:55]
	v_mfma_f32_16x16x32_bf16 v[56:59], v[136:139], v[180:183], v[56:59]
	v_mfma_f32_16x16x32_bf16 v[56:59], v[140:143], v[184:187], v[56:59]
	v_mfma_f32_16x16x32_bf16 v[60:63], v[136:139], v[188:191], v[60:63]
	v_mfma_f32_16x16x32_bf16 v[60:63], v[140:143], v[192:195], v[60:63]
	v_mfma_f32_16x16x32_bf16 v[16:19], v[144:147], v[180:183], v[16:19]
	v_mfma_f32_16x16x32_bf16 v[16:19], v[148:151], v[184:187], v[16:19]
	v_mfma_f32_16x16x32_bf16 v[20:23], v[144:147], v[188:191], v[20:23]
	v_mfma_f32_16x16x32_bf16 v[20:23], v[148:151], v[192:195], v[20:23]
	v_mfma_f32_16x16x32_bf16 v[24:27], v[152:155], v[180:183], v[24:27]
	v_mfma_f32_16x16x32_bf16 v[24:27], v[156:159], v[184:187], v[24:27]
	v_mfma_f32_16x16x32_bf16 v[28:31], v[152:155], v[188:191], v[28:31]
	v_mfma_f32_16x16x32_bf16 v[28:31], v[156:159], v[192:195], v[28:31]
	s_setprio 0
	s_barrier
	ds_read_b128 v[128:131], v170 offset:16384
	ds_read_b128 v[132:135], v197 offset:16384
	ds_read_b128 v[136:139], v170 offset:18432
	ds_read_b128 v[140:143], v197 offset:18432
	ds_read_b128 v[144:147], v170 offset:20480
	ds_read_b128 v[148:151], v197 offset:20480
	ds_read_b128 v[152:155], v170 offset:22528
	ds_read_b128 v[156:159], v197 offset:22528
	s_add_u32 m0, s99, 0x0
	s_nop 0
	global_load_lds_dwordx4 v203, s[58:59]
	s_add_u32 m0, s99, 0x2000
	s_nop 0
	global_load_lds_dwordx4 v204, s[58:59]
	s_barrier
	s_waitcnt lgkmcnt(0)
	s_setprio 1
	v_mfma_f32_16x16x32_bf16 v[96:99], v[128:131], v[160:163], v[96:99]
	v_mfma_f32_16x16x32_bf16 v[96:99], v[132:135], v[164:167], v[96:99]
	v_mfma_f32_16x16x32_bf16 v[100:103], v[128:131], v[172:175], v[100:103]
	v_mfma_f32_16x16x32_bf16 v[100:103], v[132:135], v[176:179], v[100:103]
	v_mfma_f32_16x16x32_bf16 v[104:107], v[136:139], v[160:163], v[104:107]
	v_mfma_f32_16x16x32_bf16 v[104:107], v[140:143], v[164:167], v[104:107]
	v_mfma_f32_16x16x32_bf16 v[108:111], v[136:139], v[172:175], v[108:111]
	v_mfma_f32_16x16x32_bf16 v[108:111], v[140:143], v[176:179], v[108:111]
	v_mfma_f32_16x16x32_bf16 v[64:67], v[144:147], v[160:163], v[64:67]
	v_mfma_f32_16x16x32_bf16 v[64:67], v[148:151], v[164:167], v[64:67]
	v_mfma_f32_16x16x32_bf16 v[68:71], v[144:147], v[172:175], v[68:71]
	v_mfma_f32_16x16x32_bf16 v[68:71], v[148:151], v[176:179], v[68:71]
	v_mfma_f32_16x16x32_bf16 v[72:75], v[152:155], v[160:163], v[72:75]
	v_mfma_f32_16x16x32_bf16 v[72:75], v[156:159], v[164:167], v[72:75]
	v_mfma_f32_16x16x32_bf16 v[76:79], v[152:155], v[172:175], v[76:79]
	v_mfma_f32_16x16x32_bf16 v[76:79], v[156:159], v[176:179], v[76:79]
	s_setprio 0
	s_barrier
	s_add_u32 m0, s99, 0xc000
	s_nop 0
	global_load_lds_dwordx4 v230, s[56:57]
	s_add_u32 m0, s99, 0xe000
	s_nop 0
	global_load_lds_dwordx4 v231, s[56:57]
	s_add_u32 s56, s56, 0x80
	s_addc_u32 s57, s57, 0
	s_waitcnt vmcnt(6)
	s_barrier
	s_setprio 1
	v_mfma_f32_16x16x32_bf16 v[32:35], v[128:131], v[180:183], v[32:35]
	v_mfma_f32_16x16x32_bf16 v[32:35], v[132:135], v[184:187], v[32:35]
	v_mfma_f32_16x16x32_bf16 v[36:39], v[128:131], v[188:191], v[36:39]
	v_mfma_f32_16x16x32_bf16 v[36:39], v[132:135], v[192:195], v[36:39]
	v_mfma_f32_16x16x32_bf16 v[40:43], v[136:139], v[180:183], v[40:43]
	v_mfma_f32_16x16x32_bf16 v[40:43], v[140:143], v[184:187], v[40:43]
	v_mfma_f32_16x16x32_bf16 v[44:47], v[136:139], v[188:191], v[44:47]
	v_mfma_f32_16x16x32_bf16 v[44:47], v[140:143], v[192:195], v[44:47]
	v_mfma_f32_16x16x32_bf16 v[0:3], v[144:147], v[180:183], v[0:3]
	v_mfma_f32_16x16x32_bf16 v[0:3], v[148:151], v[184:187], v[0:3]
	v_mfma_f32_16x16x32_bf16 v[4:7], v[144:147], v[188:191], v[4:7]
	v_mfma_f32_16x16x32_bf16 v[4:7], v[148:151], v[192:195], v[4:7]
	v_mfma_f32_16x16x32_bf16 v[8:11], v[152:155], v[180:183], v[8:11]
	v_mfma_f32_16x16x32_bf16 v[8:11], v[156:159], v[184:187], v[8:11]
	v_mfma_f32_16x16x32_bf16 v[12:15], v[152:155], v[188:191], v[12:15]
	v_mfma_f32_16x16x32_bf16 v[12:15], v[156:159], v[192:195], v[12:15]
	s_setprio 0
	s_barrier
	ds_read_b128 v[160:163], v200 offset:0
	ds_read_b128 v[164:167], v202 offset:0
	ds_read_b128 v[172:175], v200 offset:2048
	ds_read_b128 v[176:179], v202 offset:2048
	ds_read_b128 v[128:131], v196 offset:0
	ds_read_b128 v[132:135], v198 offset:0
	ds_read_b128 v[136:139], v196 offset:2048
	ds_read_b128 v[140:143], v198 offset:2048
	ds_read_b128 v[144:147], v196 offset:4096
	ds_read_b128 v[148:151], v198 offset:4096
	ds_read_b128 v[152:155], v196 offset:6144
	ds_read_b128 v[156:159], v198 offset:6144
	s_add_u32 m0, s99, 0x4000
	s_nop 0
	global_load_lds_dwordx4 v205, s[58:59]
	s_add_u32 m0, s99, 0x6000
	s_nop 0
	global_load_lds_dwordx4 v206, s[58:59]
	s_add_u32 s58, s58, 0x80
	s_addc_u32 s59, s59, 0
	s_waitcnt lgkmcnt(8)
	s_barrier
	s_waitcnt lgkmcnt(0)
	s_setprio 1
	v_mfma_f32_16x16x32_bf16 v[112:115], v[128:131], v[160:163], v[112:115]
	v_mfma_f32_16x16x32_bf16 v[112:115], v[132:135], v[164:167], v[112:115]
	v_mfma_f32_16x16x32_bf16 v[116:119], v[128:131], v[172:175], v[116:119]
	v_mfma_f32_16x16x32_bf16 v[116:119], v[132:135], v[176:179], v[116:119]
	v_mfma_f32_16x16x32_bf16 v[120:123], v[136:139], v[160:163], v[120:123]
	v_mfma_f32_16x16x32_bf16 v[120:123], v[140:143], v[164:167], v[120:123]
	v_mfma_f32_16x16x32_bf16 v[124:127], v[136:139], v[172:175], v[124:127]
	v_mfma_f32_16x16x32_bf16 v[124:127], v[140:143], v[176:179], v[124:127]
	v_mfma_f32_16x16x32_bf16 v[80:83], v[144:147], v[160:163], v[80:83]
	v_mfma_f32_16x16x32_bf16 v[80:83], v[148:151], v[164:167], v[80:83]
	v_mfma_f32_16x16x32_bf16 v[84:87], v[144:147], v[172:175], v[84:87]
	v_mfma_f32_16x16x32_bf16 v[84:87], v[148:151], v[176:179], v[84:87]
	v_mfma_f32_16x16x32_bf16 v[88:91], v[152:155], v[160:163], v[88:91]
	v_mfma_f32_16x16x32_bf16 v[88:91], v[156:159], v[164:167], v[88:91]
	v_mfma_f32_16x16x32_bf16 v[92:95], v[152:155], v[172:175], v[92:95]
	v_mfma_f32_16x16x32_bf16 v[92:95], v[156:159], v[176:179], v[92:95]
	s_setprio 0
	s_barrier
	ds_read_b128 v[180:183], v200 offset:16384
	ds_read_b128 v[184:187], v202 offset:16384
	ds_read_b128 v[188:191], v200 offset:18432
	ds_read_b128 v[192:195], v202 offset:18432
	s_add_u32 m0, s99, 0x18000
	s_nop 0
	global_load_lds_dwordx4 v207, s[56:57]
	s_add_u32 m0, s99, 0x1a000
	s_nop 0
	global_load_lds_dwordx4 v229, s[56:57]
	s_barrier
	s_waitcnt lgkmcnt(0)
	s_setprio 1
	v_mfma_f32_16x16x32_bf16 v[48:51], v[128:131], v[180:183], v[48:51]
	v_mfma_f32_16x16x32_bf16 v[48:51], v[132:135], v[184:187], v[48:51]
	v_mfma_f32_16x16x32_bf16 v[52:55], v[128:131], v[188:191], v[52:55]
	v_mfma_f32_16x16x32_bf16 v[52:55], v[132:135], v[192:195], v[52:55]
	v_mfma_f32_16x16x32_bf16 v[56:59], v[136:139], v[180:183], v[56:59]
	v_mfma_f32_16x16x32_bf16 v[56:59], v[140:143], v[184:187], v[56:59]
	v_mfma_f32_16x16x32_bf16 v[60:63], v[136:139], v[188:191], v[60:63]
	v_mfma_f32_16x16x32_bf16 v[60:63], v[140:143], v[192:195], v[60:63]
	v_mfma_f32_16x16x32_bf16 v[16:19], v[144:147], v[180:183], v[16:19]
	v_mfma_f32_16x16x32_bf16 v[16:19], v[148:151], v[184:187], v[16:19]
	v_mfma_f32_16x16x32_bf16 v[20:23], v[144:147], v[188:191], v[20:23]
	v_mfma_f32_16x16x32_bf16 v[20:23], v[148:151], v[192:195], v[20:23]
	v_mfma_f32_16x16x32_bf16 v[24:27], v[152:155], v[180:183], v[24:27]
	v_mfma_f32_16x16x32_bf16 v[24:27], v[156:159], v[184:187], v[24:27]
	v_mfma_f32_16x16x32_bf16 v[28:31], v[152:155], v[188:191], v[28:31]
	v_mfma_f32_16x16x32_bf16 v[28:31], v[156:159], v[192:195], v[28:31]
	s_setprio 0
	s_barrier
	ds_read_b128 v[128:131], v196 offset:16384
	ds_read_b128 v[132:135], v198 offset:16384
	ds_read_b128 v[136:139], v196 offset:18432
	ds_read_b128 v[140:143], v198 offset:18432
	ds_read_b128 v[144:147], v196 offset:20480
	ds_read_b128 v[148:151], v198 offset:20480
	ds_read_b128 v[152:155], v196 offset:22528
	ds_read_b128 v[156:159], v198 offset:22528
	s_add_u32 m0, s99, 0x10000
	s_nop 0
	global_load_lds_dwordx4 v203, s[58:59]
	s_add_u32 m0, s99, 0x12000
	s_nop 0
	global_load_lds_dwordx4 v204, s[58:59]
	s_barrier
	s_waitcnt lgkmcnt(0)
	s_setprio 1
	v_mfma_f32_16x16x32_bf16 v[96:99], v[128:131], v[160:163], v[96:99]
	v_mfma_f32_16x16x32_bf16 v[96:99], v[132:135], v[164:167], v[96:99]
	v_mfma_f32_16x16x32_bf16 v[100:103], v[128:131], v[172:175], v[100:103]
	v_mfma_f32_16x16x32_bf16 v[100:103], v[132:135], v[176:179], v[100:103]
	v_mfma_f32_16x16x32_bf16 v[104:107], v[136:139], v[160:163], v[104:107]
	v_mfma_f32_16x16x32_bf16 v[104:107], v[140:143], v[164:167], v[104:107]
	v_mfma_f32_16x16x32_bf16 v[108:111], v[136:139], v[172:175], v[108:111]
	v_mfma_f32_16x16x32_bf16 v[108:111], v[140:143], v[176:179], v[108:111]
	v_mfma_f32_16x16x32_bf16 v[64:67], v[144:147], v[160:163], v[64:67]
	v_mfma_f32_16x16x32_bf16 v[64:67], v[148:151], v[164:167], v[64:67]
	v_mfma_f32_16x16x32_bf16 v[68:71], v[144:147], v[172:175], v[68:71]
	v_mfma_f32_16x16x32_bf16 v[68:71], v[148:151], v[176:179], v[68:71]
	v_mfma_f32_16x16x32_bf16 v[72:75], v[152:155], v[160:163], v[72:75]
	v_mfma_f32_16x16x32_bf16 v[72:75], v[156:159], v[164:167], v[72:75]
	v_mfma_f32_16x16x32_bf16 v[76:79], v[152:155], v[172:175], v[76:79]
	v_mfma_f32_16x16x32_bf16 v[76:79], v[156:159], v[176:179], v[76:79]
	s_setprio 0
	s_barrier
	s_add_u32 m0, s99, 0x1c000
	s_nop 0
	global_load_lds_dwordx4 v230, s[56:57]
	s_add_u32 m0, s99, 0x1e000
	s_nop 0
	global_load_lds_dwordx4 v231, s[56:57]
	s_add_u32 s56, s56, 0x80
	s_addc_u32 s57, s57, 0
	s_waitcnt vmcnt(6)
	s_barrier
	s_setprio 1
	v_mfma_f32_16x16x32_bf16 v[32:35], v[128:131], v[180:183], v[32:35]
	v_mfma_f32_16x16x32_bf16 v[32:35], v[132:135], v[184:187], v[32:35]
	v_mfma_f32_16x16x32_bf16 v[36:39], v[128:131], v[188:191], v[36:39]
	v_mfma_f32_16x16x32_bf16 v[36:39], v[132:135], v[192:195], v[36:39]
	v_mfma_f32_16x16x32_bf16 v[40:43], v[136:139], v[180:183], v[40:43]
	v_mfma_f32_16x16x32_bf16 v[40:43], v[140:143], v[184:187], v[40:43]
	v_mfma_f32_16x16x32_bf16 v[44:47], v[136:139], v[188:191], v[44:47]
	v_mfma_f32_16x16x32_bf16 v[44:47], v[140:143], v[192:195], v[44:47]
	v_mfma_f32_16x16x32_bf16 v[0:3], v[144:147], v[180:183], v[0:3]
	v_mfma_f32_16x16x32_bf16 v[0:3], v[148:151], v[184:187], v[0:3]
	v_mfma_f32_16x16x32_bf16 v[4:7], v[144:147], v[188:191], v[4:7]
	v_mfma_f32_16x16x32_bf16 v[4:7], v[148:151], v[192:195], v[4:7]
	v_mfma_f32_16x16x32_bf16 v[8:11], v[152:155], v[180:183], v[8:11]
	v_mfma_f32_16x16x32_bf16 v[8:11], v[156:159], v[184:187], v[8:11]
	v_mfma_f32_16x16x32_bf16 v[12:15], v[152:155], v[188:191], v[12:15]
	v_mfma_f32_16x16x32_bf16 v[12:15], v[156:159], v[192:195], v[12:15]
	s_setprio 0
	s_barrier
	s_sub_u32 s101, s101, 1
	s_cmp_lg_u32 s101, 0
	s_cbranch_scc1 .Lg8_p2_loop
	ds_read_b128 v[160:163], v199 offset:0
	ds_read_b128 v[164:167], v201 offset:0
	ds_read_b128 v[172:175], v199 offset:2048
	ds_read_b128 v[176:179], v201 offset:2048
	ds_read_b128 v[128:131], v170 offset:0
	ds_read_b128 v[132:135], v197 offset:0
	ds_read_b128 v[136:139], v170 offset:2048
	ds_read_b128 v[140:143], v197 offset:2048
	ds_read_b128 v[144:147], v170 offset:4096
	ds_read_b128 v[148:151], v197 offset:4096
	ds_read_b128 v[152:155], v170 offset:6144
	ds_read_b128 v[156:159], v197 offset:6144
	s_add_u32 m0, s99, 0x14000
	s_nop 0
	global_load_lds_dwordx4 v205, s[58:59]
	s_add_u32 m0, s99, 0x16000
	s_nop 0
	global_load_lds_dwordx4 v206, s[58:59]
	s_add_u32 s58, s58, 0x80
	s_addc_u32 s59, s59, 0
	s_barrier
	s_waitcnt lgkmcnt(0)
	s_setprio 1
	v_mfma_f32_16x16x32_bf16 v[112:115], v[128:131], v[160:163], v[112:115]
	v_mfma_f32_16x16x32_bf16 v[112:115], v[132:135], v[164:167], v[112:115]
	v_mfma_f32_16x16x32_bf16 v[116:119], v[128:131], v[172:175], v[116:119]
	v_mfma_f32_16x16x32_bf16 v[116:119], v[132:135], v[176:179], v[116:119]
	v_mfma_f32_16x16x32_bf16 v[120:123], v[136:139], v[160:163], v[120:123]
	v_mfma_f32_16x16x32_bf16 v[120:123], v[140:143], v[164:167], v[120:123]
	v_mfma_f32_16x16x32_bf16 v[124:127], v[136:139], v[172:175], v[124:127]
	v_mfma_f32_16x16x32_bf16 v[124:127], v[140:143], v[176:179], v[124:127]
	v_mfma_f32_16x16x32_bf16 v[80:83], v[144:147], v[160:163], v[80:83]
	v_mfma_f32_16x16x32_bf16 v[80:83], v[148:151], v[164:167], v[80:83]
	v_mfma_f32_16x16x32_bf16 v[84:87], v[144:147], v[172:175], v[84:87]
	v_mfma_f32_16x16x32_bf16 v[84:87], v[148:151], v[176:179], v[84:87]
	v_mfma_f32_16x16x32_bf16 v[88:91], v[152:155], v[160:163], v[88:91]
	v_mfma_f32_16x16x32_bf16 v[88:91], v[156:159], v[164:167], v[88:91]
	v_mfma_f32_16x16x32_bf16 v[92:95], v[152:155], v[172:175], v[92:95]
	v_mfma_f32_16x16x32_bf16 v[92:95], v[156:159], v[176:179], v[92:95]
	s_setprio 0
	s_barrier
	ds_read_b128 v[180:183], v199 offset:16384
	ds_read_b128 v[184:187], v201 offset:16384
	ds_read_b128 v[188:191], v199 offset:18432
	ds_read_b128 v[192:195], v201 offset:18432
	s_barrier
	s_waitcnt lgkmcnt(0)
	s_setprio 1
	v_mfma_f32_16x16x32_bf16 v[48:51], v[128:131], v[180:183], v[48:51]
	v_mfma_f32_16x16x32_bf16 v[48:51], v[132:135], v[184:187], v[48:51]
	v_mfma_f32_16x16x32_bf16 v[52:55], v[128:131], v[188:191], v[52:55]
	v_mfma_f32_16x16x32_bf16 v[52:55], v[132:135], v[192:195], v[52:55]
	v_mfma_f32_16x16x32_bf16 v[56:59], v[136:139], v[180:183], v[56:59]
	v_mfma_f32_16x16x32_bf16 v[56:59], v[140:143], v[184:187], v[56:59]
	v_mfma_f32_16x16x32_bf16 v[60:63], v[136:139], v[188:191], v[60:63]
	v_mfma_f32_16x16x32_bf16 v[60:63], v[140:143], v[192:195], v[60:63]
	v_mfma_f32_16x16x32_bf16 v[16:19], v[144:147], v[180:183], v[16:19]
	v_mfma_f32_16x16x32_bf16 v[16:19], v[148:151], v[184:187], v[16:19]
	v_mfma_f32_16x16x32_bf16 v[20:23], v[144:147], v[188:191], v[20:23]
	v_mfma_f32_16x16x32_bf16 v[20:23], v[148:151], v[192:195], v[20:23]
	v_mfma_f32_16x16x32_bf16 v[24:27], v[152:155], v[180:183], v[24:27]
	v_mfma_f32_16x16x32_bf16 v[24:27], v[156:159], v[184:187], v[24:27]
	v_mfma_f32_16x16x32_bf16 v[28:31], v[152:155], v[188:191], v[28:31]
	v_mfma_f32_16x16x32_bf16 v[28:31], v[156:159], v[192:195], v[28:31]
	s_setprio 0
	s_barrier
	ds_read_b128 v[128:131], v170 offset:16384
	ds_read_b128 v[132:135], v197 offset:16384
	ds_read_b128 v[136:139], v170 offset:18432
	ds_read_b128 v[140:143], v197 offset:18432
	ds_read_b128 v[144:147], v170 offset:20480
	ds_read_b128 v[148:151], v197 offset:20480
	ds_read_b128 v[152:155], v170 offset:22528
	ds_read_b128 v[156:159], v197 offset:22528
	s_waitcnt vmcnt(4)
	s_barrier
	s_waitcnt lgkmcnt(0)
	s_setprio 1
	v_mfma_f32_16x16x32_bf16 v[96:99], v[128:131], v[160:163], v[96:99]
	v_mfma_f32_16x16x32_bf16 v[96:99], v[132:135], v[164:167], v[96:99]
	v_mfma_f32_16x16x32_bf16 v[100:103], v[128:131], v[172:175], v[100:103]
	v_mfma_f32_16x16x32_bf16 v[100:103], v[132:135], v[176:179], v[100:103]
	v_mfma_f32_16x16x32_bf16 v[104:107], v[136:139], v[160:163], v[104:107]
	v_mfma_f32_16x16x32_bf16 v[104:107], v[140:143], v[164:167], v[104:107]
	v_mfma_f32_16x16x32_bf16 v[108:111], v[136:139], v[172:175], v[108:111]
	v_mfma_f32_16x16x32_bf16 v[108:111], v[140:143], v[176:179], v[108:111]
	v_mfma_f32_16x16x32_bf16 v[64:67], v[144:147], v[160:163], v[64:67]
	v_mfma_f32_16x16x32_bf16 v[64:67], v[148:151], v[164:167], v[64:67]
	v_mfma_f32_16x16x32_bf16 v[68:71], v[144:147], v[172:175], v[68:71]
	v_mfma_f32_16x16x32_bf16 v[68:71], v[148:151], v[176:179], v[68:71]
	v_mfma_f32_16x16x32_bf16 v[72:75], v[152:155], v[160:163], v[72:75]
	v_mfma_f32_16x16x32_bf16 v[72:75], v[156:159], v[164:167], v[72:75]
	v_mfma_f32_16x16x32_bf16 v[76:79], v[152:155], v[172:175], v[76:79]
	v_mfma_f32_16x16x32_bf16 v[76:79], v[156:159], v[176:179], v[76:79]
	s_setprio 0
	s_setprio 1
	v_mfma_f32_16x16x32_bf16 v[32:35], v[128:131], v[180:183], v[32:35]
	v_mfma_f32_16x16x32_bf16 v[32:35], v[132:135], v[184:187], v[32:35]
	v_mfma_f32_16x16x32_bf16 v[36:39], v[128:131], v[188:191], v[36:39]
	v_mfma_f32_16x16x32_bf16 v[36:39], v[132:135], v[192:195], v[36:39]
	v_mfma_f32_16x16x32_bf16 v[40:43], v[136:139], v[180:183], v[40:43]
	v_mfma_f32_16x16x32_bf16 v[40:43], v[140:143], v[184:187], v[40:43]
	v_mfma_f32_16x16x32_bf16 v[44:47], v[136:139], v[188:191], v[44:47]
	v_mfma_f32_16x16x32_bf16 v[44:47], v[140:143], v[192:195], v[44:47]
	v_mfma_f32_16x16x32_bf16 v[0:3], v[144:147], v[180:183], v[0:3]
	v_mfma_f32_16x16x32_bf16 v[0:3], v[148:151], v[184:187], v[0:3]
	v_mfma_f32_16x16x32_bf16 v[4:7], v[144:147], v[188:191], v[4:7]
	v_mfma_f32_16x16x32_bf16 v[4:7], v[148:151], v[192:195], v[4:7]
	v_mfma_f32_16x16x32_bf16 v[8:11], v[152:155], v[180:183], v[8:11]
	v_mfma_f32_16x16x32_bf16 v[8:11], v[156:159], v[184:187], v[8:11]
	v_mfma_f32_16x16x32_bf16 v[12:15], v[152:155], v[188:191], v[12:15]
	v_mfma_f32_16x16x32_bf16 v[12:15], v[156:159], v[192:195], v[12:15]
	s_setprio 0
	s_barrier
	ds_read_b128 v[160:163], v200 offset:0
	ds_read_b128 v[164:167], v202 offset:0
	ds_read_b128 v[172:175], v200 offset:2048
	ds_read_b128 v[176:179], v202 offset:2048
	ds_read_b128 v[128:131], v196 offset:0
	ds_read_b128 v[132:135], v198 offset:0
	ds_read_b128 v[136:139], v196 offset:2048
	ds_read_b128 v[140:143], v198 offset:2048
	ds_read_b128 v[144:147], v196 offset:4096
	ds_read_b128 v[148:151], v198 offset:4096
	ds_read_b128 v[152:155], v196 offset:6144
	ds_read_b128 v[156:159], v198 offset:6144
	s_waitcnt vmcnt(2)
	s_barrier
	s_waitcnt lgkmcnt(0)
	s_setprio 1
	v_mfma_f32_16x16x32_bf16 v[112:115], v[128:131], v[160:163], v[112:115]
	v_mfma_f32_16x16x32_bf16 v[112:115], v[132:135], v[164:167], v[112:115]
	v_mfma_f32_16x16x32_bf16 v[116:119], v[128:131], v[172:175], v[116:119]
	v_mfma_f32_16x16x32_bf16 v[116:119], v[132:135], v[176:179], v[116:119]
	v_mfma_f32_16x16x32_bf16 v[120:123], v[136:139], v[160:163], v[120:123]
	v_mfma_f32_16x16x32_bf16 v[120:123], v[140:143], v[164:167], v[120:123]
	v_mfma_f32_16x16x32_bf16 v[124:127], v[136:139], v[172:175], v[124:127]
	v_mfma_f32_16x16x32_bf16 v[124:127], v[140:143], v[176:179], v[124:127]
	v_mfma_f32_16x16x32_bf16 v[80:83], v[144:147], v[160:163], v[80:83]
	v_mfma_f32_16x16x32_bf16 v[80:83], v[148:151], v[164:167], v[80:83]
	v_mfma_f32_16x16x32_bf16 v[84:87], v[144:147], v[172:175], v[84:87]
	v_mfma_f32_16x16x32_bf16 v[84:87], v[148:151], v[176:179], v[84:87]
	v_mfma_f32_16x16x32_bf16 v[88:91], v[152:155], v[160:163], v[88:91]
	v_mfma_f32_16x16x32_bf16 v[88:91], v[156:159], v[164:167], v[88:91]
	v_mfma_f32_16x16x32_bf16 v[92:95], v[152:155], v[172:175], v[92:95]
	v_mfma_f32_16x16x32_bf16 v[92:95], v[156:159], v[176:179], v[92:95]
	s_setprio 0
	s_barrier
	ds_read_b128 v[180:183], v200 offset:16384
	ds_read_b128 v[184:187], v202 offset:16384
	ds_read_b128 v[188:191], v200 offset:18432
	ds_read_b128 v[192:195], v202 offset:18432
	s_waitcnt vmcnt(0)
	s_barrier
	s_waitcnt lgkmcnt(0)
	s_setprio 1
	v_mfma_f32_16x16x32_bf16 v[48:51], v[128:131], v[180:183], v[48:51]
	v_mfma_f32_16x16x32_bf16 v[48:51], v[132:135], v[184:187], v[48:51]
	v_mfma_f32_16x16x32_bf16 v[52:55], v[128:131], v[188:191], v[52:55]
	v_mfma_f32_16x16x32_bf16 v[52:55], v[132:135], v[192:195], v[52:55]
	v_mfma_f32_16x16x32_bf16 v[56:59], v[136:139], v[180:183], v[56:59]
	v_mfma_f32_16x16x32_bf16 v[56:59], v[140:143], v[184:187], v[56:59]
	v_mfma_f32_16x16x32_bf16 v[60:63], v[136:139], v[188:191], v[60:63]
	v_mfma_f32_16x16x32_bf16 v[60:63], v[140:143], v[192:195], v[60:63]
	v_mfma_f32_16x16x32_bf16 v[16:19], v[144:147], v[180:183], v[16:19]
	v_mfma_f32_16x16x32_bf16 v[16:19], v[148:151], v[184:187], v[16:19]
	v_mfma_f32_16x16x32_bf16 v[20:23], v[144:147], v[188:191], v[20:23]
	v_mfma_f32_16x16x32_bf16 v[20:23], v[148:151], v[192:195], v[20:23]
	v_mfma_f32_16x16x32_bf16 v[24:27], v[152:155], v[180:183], v[24:27]
	v_mfma_f32_16x16x32_bf16 v[24:27], v[156:159], v[184:187], v[24:27]
	v_mfma_f32_16x16x32_bf16 v[28:31], v[152:155], v[188:191], v[28:31]
	v_mfma_f32_16x16x32_bf16 v[28:31], v[156:159], v[192:195], v[28:31]
	s_setprio 0
	s_barrier
	ds_read_b128 v[128:131], v196 offset:16384
	ds_read_b128 v[132:135], v198 offset:16384
	ds_read_b128 v[136:139], v196 offset:18432
	ds_read_b128 v[140:143], v198 offset:18432
	ds_read_b128 v[144:147], v196 offset:20480
	ds_read_b128 v[148:151], v198 offset:20480
	ds_read_b128 v[152:155], v196 offset:22528
	ds_read_b128 v[156:159], v198 offset:22528
	s_barrier
	s_waitcnt lgkmcnt(0)
	s_setprio 1
	v_mfma_f32_16x16x32_bf16 v[96:99], v[128:131], v[160:163], v[96:99]
	v_mfma_f32_16x16x32_bf16 v[96:99], v[132:135], v[164:167], v[96:99]
	v_mfma_f32_16x16x32_bf16 v[100:103], v[128:131], v[172:175], v[100:103]
	v_mfma_f32_16x16x32_bf16 v[100:103], v[132:135], v[176:179], v[100:103]
	v_mfma_f32_16x16x32_bf16 v[104:107], v[136:139], v[160:163], v[104:107]
	v_mfma_f32_16x16x32_bf16 v[104:107], v[140:143], v[164:167], v[104:107]
	v_mfma_f32_16x16x32_bf16 v[108:111], v[136:139], v[172:175], v[108:111]
	v_mfma_f32_16x16x32_bf16 v[108:111], v[140:143], v[176:179], v[108:111]
	v_mfma_f32_16x16x32_bf16 v[64:67], v[144:147], v[160:163], v[64:67]
	v_mfma_f32_16x16x32_bf16 v[64:67], v[148:151], v[164:167], v[64:67]
	v_mfma_f32_16x16x32_bf16 v[68:71], v[144:147], v[172:175], v[68:71]
	v_mfma_f32_16x16x32_bf16 v[68:71], v[148:151], v[176:179], v[68:71]
	v_mfma_f32_16x16x32_bf16 v[72:75], v[152:155], v[160:163], v[72:75]
	v_mfma_f32_16x16x32_bf16 v[72:75], v[156:159], v[164:167], v[72:75]
	v_mfma_f32_16x16x32_bf16 v[76:79], v[152:155], v[172:175], v[76:79]
	v_mfma_f32_16x16x32_bf16 v[76:79], v[156:159], v[176:179], v[76:79]
	s_setprio 0
	s_setprio 1
	v_mfma_f32_16x16x32_bf16 v[32:35], v[128:131], v[180:183], v[32:35]
	v_mfma_f32_16x16x32_bf16 v[32:35], v[132:135], v[184:187], v[32:35]
	v_mfma_f32_16x16x32_bf16 v[36:39], v[128:131], v[188:191], v[36:39]
	v_mfma_f32_16x16x32_bf16 v[36:39], v[132:135], v[192:195], v[36:39]
	v_mfma_f32_16x16x32_bf16 v[40:43], v[136:139], v[180:183], v[40:43]
	v_mfma_f32_16x16x32_bf16 v[40:43], v[140:143], v[184:187], v[40:43]
	v_mfma_f32_16x16x32_bf16 v[44:47], v[136:139], v[188:191], v[44:47]
	v_mfma_f32_16x16x32_bf16 v[44:47], v[140:143], v[192:195], v[44:47]
	v_mfma_f32_16x16x32_bf16 v[0:3], v[144:147], v[180:183], v[0:3]
	v_mfma_f32_16x16x32_bf16 v[0:3], v[148:151], v[184:187], v[0:3]
	v_mfma_f32_16x16x32_bf16 v[4:7], v[144:147], v[188:191], v[4:7]
	v_mfma_f32_16x16x32_bf16 v[4:7], v[148:151], v[192:195], v[4:7]
	v_mfma_f32_16x16x32_bf16 v[8:11], v[152:155], v[180:183], v[8:11]
	v_mfma_f32_16x16x32_bf16 v[8:11], v[156:159], v[184:187], v[8:11]
	v_mfma_f32_16x16x32_bf16 v[12:15], v[152:155], v[188:191], v[12:15]
	v_mfma_f32_16x16x32_bf16 v[12:15], v[156:159], v[192:195], v[12:15]
	s_setprio 0
	s_barrier
	s_cmp_lg_u32 s100, 0
	s_cbranch_scc1 .Lg8_p2_eg1
	s_barrier
.Lg8_p2_eg1:
	s_nop 7
	s_nop 7
	v_permlane16_swap_b32_e32 v112, v116
	v_permlane16_swap_b32_e32 v113, v117
	v_permlane16_swap_b32_e32 v114, v118
	v_permlane16_swap_b32_e32 v115, v119
	v_permlane16_swap_b32_e32 v120, v124
	v_permlane16_swap_b32_e32 v121, v125
	v_permlane16_swap_b32_e32 v122, v126
	v_permlane16_swap_b32_e32 v123, v127
	v_permlane16_swap_b32_e32 v80, v84
	v_permlane16_swap_b32_e32 v81, v85
	v_permlane16_swap_b32_e32 v82, v86
	v_permlane16_swap_b32_e32 v83, v87
	v_permlane16_swap_b32_e32 v88, v92
	v_permlane16_swap_b32_e32 v89, v93
	v_permlane16_swap_b32_e32 v90, v94
	v_permlane16_swap_b32_e32 v91, v95
	v_permlane16_swap_b32_e32 v96, v100
	v_permlane16_swap_b32_e32 v97, v101
	v_permlane16_swap_b32_e32 v98, v102
	v_permlane16_swap_b32_e32 v99, v103
	v_permlane16_swap_b32_e32 v104, v108
	v_permlane16_swap_b32_e32 v105, v109
	v_permlane16_swap_b32_e32 v106, v110
	v_permlane16_swap_b32_e32 v107, v111
	v_permlane16_swap_b32_e32 v64, v68
	v_permlane16_swap_b32_e32 v65, v69
	v_permlane16_swap_b32_e32 v66, v70
	v_permlane16_swap_b32_e32 v67, v71
	v_permlane16_swap_b32_e32 v72, v76
	v_permlane16_swap_b32_e32 v73, v77
	v_permlane16_swap_b32_e32 v74, v78
	v_permlane16_swap_b32_e32 v75, v79
	v_permlane16_swap_b32_e32 v48, v52
	v_permlane16_swap_b32_e32 v49, v53
	v_permlane16_swap_b32_e32 v50, v54
	v_permlane16_swap_b32_e32 v51, v55
	v_permlane16_swap_b32_e32 v56, v60
	v_permlane16_swap_b32_e32 v57, v61
	v_permlane16_swap_b32_e32 v58, v62
	v_permlane16_swap_b32_e32 v59, v63
	v_permlane16_swap_b32_e32 v16, v20
	v_permlane16_swap_b32_e32 v17, v21
	v_permlane16_swap_b32_e32 v18, v22
	v_permlane16_swap_b32_e32 v19, v23
	v_permlane16_swap_b32_e32 v24, v28
	v_permlane16_swap_b32_e32 v25, v29
	v_permlane16_swap_b32_e32 v26, v30
	v_permlane16_swap_b32_e32 v27, v31
	v_permlane16_swap_b32_e32 v32, v36
	v_permlane16_swap_b32_e32 v33, v37
	v_permlane16_swap_b32_e32 v34, v38
	v_permlane16_swap_b32_e32 v35, v39
	v_permlane16_swap_b32_e32 v40, v44
	v_permlane16_swap_b32_e32 v41, v45
	v_permlane16_swap_b32_e32 v42, v46
	v_permlane16_swap_b32_e32 v43, v47
	v_permlane16_swap_b32_e32 v0, v4
	v_permlane16_swap_b32_e32 v1, v5
	v_permlane16_swap_b32_e32 v2, v6
	v_permlane16_swap_b32_e32 v3, v7
	v_permlane16_swap_b32_e32 v8, v12
	v_permlane16_swap_b32_e32 v9, v13
	v_permlane16_swap_b32_e32 v10, v14
	v_permlane16_swap_b32_e32 v11, v15
	s_nop 1
	s_cmp_gt_i32 s36, 4
	s_mov_b64 s[2:3], -1
	s_cbranch_scc0 .LBB0_240
	s_cmp_lg_u32 s36, 5
	s_cbranch_scc0 .LBB0_233
	s_cmp_gt_u32 s36, 13
	s_cbranch_scc0 .LBB0_230
	s_waitcnt vmcnt(1)
	v_mov_b32_e32 v128, v208
	v_mul_f32_e32 v131, 0xbfb8aa3b, v115
	v_and_b32_e32 v129, 31, v128
	v_lshrrev_b32_e32 v130, 1, v128
	s_waitcnt vmcnt(0)
	v_and_or_b32 v132, v130, s45, v129
	v_mul_f32_e32 v129, 0xbfb8aa3b, v112
	v_mul_f32_e32 v130, 0xbfb8aa3b, v113
	v_exp_f32_e32 v129, v129
	v_exp_f32_e32 v130, v130
	v_lshlrev_b32_e32 v133, 1, v128
	v_lshrrev_b32_e32 v128, 3, v128
	v_and_b32_e32 v134, 4, v128
	v_add_f32_e32 v128, 1.0, v129
	v_add_f32_e32 v129, 1.0, v130
	v_rcp_f32_e32 v128, v128
	v_rcp_f32_e32 v129, v129
	v_mul_lo_u32 v139, v132, s43
	v_mul_f32_e32 v132, 0xbfb8aa3b, v116
	v_and_or_b32 v138, v133, s46, v134
	v_exp_f32_e32 v133, v132
	v_pk_mul_f32 v[128:129], v[112:113], v[128:129]
	v_mul_f32_e32 v132, 0xbfb8aa3b, v117
	v_mul_f32_e32 v130, 0xbfb8aa3b, v114
	v_exp_f32_e32 v135, v132
	v_cvt_pk_bf16_f32 v132, v128, v129
	v_mul_f32_e32 v129, 0xbfb8aa3b, v118
	v_exp_f32_e32 v130, v130
	v_exp_f32_e32 v131, v131
	v_add_f32_e32 v128, 1.0, v133
	v_exp_f32_e32 v129, v129
	v_mul_f32_e32 v133, 0xbfb8aa3b, v119
	v_exp_f32_e32 v133, v133
	v_rcp_f32_e32 v134, v128
	v_add_f32_e32 v128, 1.0, v135
	v_add_f32_e32 v130, 1.0, v130
	v_add_f32_e32 v131, 1.0, v131
	v_rcp_f32_e32 v135, v128
	v_add_f32_e32 v128, 1.0, v129
	v_rcp_f32_e32 v130, v130
	v_rcp_f32_e32 v131, v131
	v_rcp_f32_e32 v136, v128
	v_add_f32_e32 v128, 1.0, v133
	v_rcp_f32_e32 v137, v128
	v_pk_mul_f32 v[130:131], v[114:115], v[130:131]
	v_mul_f32_e32 v129, 0xbfb8aa3b, v120
	v_cvt_pk_bf16_f32 v133, v130, v131
	v_pk_mul_f32 v[130:131], v[116:117], v[134:135]
	v_pk_mul_f32 v[134:135], v[118:119], v[136:137]
	v_cvt_pk_bf16_f32 v130, v130, v131
	v_cvt_pk_bf16_f32 v131, v134, v135
	v_exp_f32_e32 v129, v129
	v_mul_f32_e32 v134, 0xbfb8aa3b, v121
	v_exp_f32_e32 v134, v134
	v_lshl_add_u32 v128, v138, 1, v139
	v_add_f32_e32 v129, 1.0, v129
	ds_write2_b64 v128, v[132:133], v[130:131] offset1:2
	v_rcp_f32_e32 v130, v129
	v_add_f32_e32 v129, 1.0, v134
	v_rcp_f32_e32 v131, v129
	v_mul_f32_e32 v129, 0xbfb8aa3b, v122
	v_exp_f32_e32 v129, v129
	v_mul_f32_e32 v132, 0xbfb8aa3b, v123
	v_exp_f32_e32 v133, v132
	v_mul_f32_e32 v134, 0xbfb8aa3b, v125
	v_add_f32_e32 v129, 1.0, v129
	v_rcp_f32_e32 v132, v129
	v_add_f32_e32 v129, 1.0, v133
	v_rcp_f32_e32 v133, v129
	v_mul_f32_e32 v129, 0xbfb8aa3b, v124
	v_exp_f32_e32 v129, v129
	v_exp_f32_e32 v135, v134
	v_pk_mul_f32 v[130:131], v[120:121], v[130:131]
	v_pk_mul_f32 v[132:133], v[122:123], v[132:133]
	v_add_f32_e32 v129, 1.0, v129
	v_rcp_f32_e32 v134, v129
	v_add_f32_e32 v129, 1.0, v135
	v_mul_f32_e32 v135, 0xbfb8aa3b, v126
	v_exp_f32_e32 v136, v135
	v_mul_f32_e32 v135, 0xbfb8aa3b, v127
	v_exp_f32_e32 v137, v135
	v_rcp_f32_e32 v135, v129
	v_add_f32_e32 v129, 1.0, v136
	v_rcp_f32_e32 v136, v129
	v_add_f32_e32 v129, 1.0, v137
	v_rcp_f32_e32 v137, v129
	v_cvt_pk_bf16_f32 v130, v130, v131
	v_cvt_pk_bf16_f32 v131, v132, v133
	v_pk_mul_f32 v[132:133], v[124:125], v[134:135]
	v_pk_mul_f32 v[134:135], v[126:127], v[136:137]
	v_mul_f32_e32 v129, 0xbfb8aa3b, v80
	v_cvt_pk_bf16_f32 v132, v132, v133
	v_cvt_pk_bf16_f32 v133, v134, v135
	v_exp_f32_e32 v129, v129
	v_mul_f32_e32 v134, 0xbfb8aa3b, v81
	v_exp_f32_e32 v134, v134
	ds_write2_b64 v128, v[130:131], v[132:133] offset0:4 offset1:6
	v_add_f32_e32 v129, 1.0, v129
	v_rcp_f32_e32 v130, v129
	v_add_f32_e32 v129, 1.0, v134
	v_rcp_f32_e32 v131, v129
	v_mul_f32_e32 v129, 0xbfb8aa3b, v82
	v_exp_f32_e32 v129, v129
	v_mul_f32_e32 v132, 0xbfb8aa3b, v83
	v_exp_f32_e32 v133, v132
	v_mul_f32_e32 v134, 0xbfb8aa3b, v85
	v_add_f32_e32 v129, 1.0, v129
	v_rcp_f32_e32 v132, v129
	v_add_f32_e32 v129, 1.0, v133
	v_rcp_f32_e32 v133, v129
	v_mul_f32_e32 v129, 0xbfb8aa3b, v84
	v_exp_f32_e32 v129, v129
	v_exp_f32_e32 v135, v134
	v_pk_mul_f32 v[130:131], v[80:81], v[130:131]
	v_pk_mul_f32 v[132:133], v[82:83], v[132:133]
	v_add_f32_e32 v129, 1.0, v129
	v_rcp_f32_e32 v134, v129
	v_add_f32_e32 v129, 1.0, v135
	v_mul_f32_e32 v135, 0xbfb8aa3b, v86
	v_exp_f32_e32 v136, v135
	v_mul_f32_e32 v135, 0xbfb8aa3b, v87
	v_exp_f32_e32 v137, v135
	v_rcp_f32_e32 v135, v129
	v_add_f32_e32 v129, 1.0, v136
	v_rcp_f32_e32 v136, v129
	v_add_f32_e32 v129, 1.0, v137
	v_rcp_f32_e32 v137, v129
	v_cvt_pk_bf16_f32 v130, v130, v131
	v_cvt_pk_bf16_f32 v131, v132, v133
	v_pk_mul_f32 v[132:133], v[84:85], v[134:135]
	v_pk_mul_f32 v[134:135], v[86:87], v[136:137]
	v_mul_f32_e32 v129, 0xbfb8aa3b, v88
	v_cvt_pk_bf16_f32 v132, v132, v133
	v_cvt_pk_bf16_f32 v133, v134, v135
	v_exp_f32_e32 v129, v129
	v_mul_f32_e32 v134, 0xbfb8aa3b, v89
	v_exp_f32_e32 v134, v134
	ds_write2_b64 v128, v[130:131], v[132:133] offset0:8 offset1:10
	v_add_f32_e32 v129, 1.0, v129
	v_rcp_f32_e32 v130, v129
	v_add_f32_e32 v129, 1.0, v134
	v_rcp_f32_e32 v131, v129
	v_mul_f32_e32 v129, 0xbfb8aa3b, v90
	v_exp_f32_e32 v129, v129
	v_mul_f32_e32 v132, 0xbfb8aa3b, v91
	v_exp_f32_e32 v133, v132
	v_mul_f32_e32 v134, 0xbfb8aa3b, v93
	v_add_f32_e32 v129, 1.0, v129
	v_rcp_f32_e32 v132, v129
	v_add_f32_e32 v129, 1.0, v133
	v_rcp_f32_e32 v133, v129
	v_mul_f32_e32 v129, 0xbfb8aa3b, v92
	v_exp_f32_e32 v129, v129
	v_exp_f32_e32 v135, v134
	v_pk_mul_f32 v[130:131], v[88:89], v[130:131]
	v_pk_mul_f32 v[132:133], v[90:91], v[132:133]
	v_add_f32_e32 v129, 1.0, v129
	v_rcp_f32_e32 v134, v129
	v_add_f32_e32 v129, 1.0, v135
	v_mul_f32_e32 v135, 0xbfb8aa3b, v94
	v_exp_f32_e32 v136, v135
	v_mul_f32_e32 v135, 0xbfb8aa3b, v95
	v_exp_f32_e32 v137, v135
	v_rcp_f32_e32 v135, v129
	v_add_f32_e32 v129, 1.0, v136
	v_rcp_f32_e32 v136, v129
	v_add_f32_e32 v129, 1.0, v137
	v_rcp_f32_e32 v137, v129
	v_cvt_pk_bf16_f32 v130, v130, v131
	v_cvt_pk_bf16_f32 v131, v132, v133
	v_pk_mul_f32 v[132:133], v[92:93], v[134:135]
	v_pk_mul_f32 v[134:135], v[94:95], v[136:137]
	v_mul_f32_e32 v129, 0xbfb8aa3b, v96
	v_cvt_pk_bf16_f32 v132, v132, v133
	v_cvt_pk_bf16_f32 v133, v134, v135
	v_exp_f32_e32 v129, v129
	v_mul_f32_e32 v134, 0xbfb8aa3b, v97
	v_exp_f32_e32 v134, v134
	ds_write2_b64 v128, v[130:131], v[132:133] offset0:12 offset1:14
	v_add_f32_e32 v129, 1.0, v129
	v_rcp_f32_e32 v130, v129
	v_add_f32_e32 v129, 1.0, v134
	v_rcp_f32_e32 v131, v129
	v_mul_f32_e32 v129, 0xbfb8aa3b, v98
	v_exp_f32_e32 v129, v129
	v_mul_f32_e32 v132, 0xbfb8aa3b, v99
	v_exp_f32_e32 v133, v132
	v_mul_f32_e32 v134, 0xbfb8aa3b, v101
	v_add_f32_e32 v129, 1.0, v129
	v_rcp_f32_e32 v132, v129
	v_add_f32_e32 v129, 1.0, v133
	v_rcp_f32_e32 v133, v129
	v_mul_f32_e32 v129, 0xbfb8aa3b, v100
	v_exp_f32_e32 v129, v129
	v_exp_f32_e32 v135, v134
	v_pk_mul_f32 v[130:131], v[96:97], v[130:131]
	v_pk_mul_f32 v[132:133], v[98:99], v[132:133]
	v_add_f32_e32 v129, 1.0, v129
	v_rcp_f32_e32 v134, v129
	v_add_f32_e32 v129, 1.0, v135
	v_mul_f32_e32 v135, 0xbfb8aa3b, v102
	v_exp_f32_e32 v136, v135
	v_mul_f32_e32 v135, 0xbfb8aa3b, v103
	v_exp_f32_e32 v137, v135
	v_rcp_f32_e32 v135, v129
	v_add_f32_e32 v129, 1.0, v136
	v_rcp_f32_e32 v136, v129
	v_add_f32_e32 v129, 1.0, v137
	v_rcp_f32_e32 v137, v129
	v_cvt_pk_bf16_f32 v130, v130, v131
	v_cvt_pk_bf16_f32 v131, v132, v133
	v_pk_mul_f32 v[132:133], v[100:101], v[134:135]
	v_pk_mul_f32 v[134:135], v[102:103], v[136:137]
	v_mul_f32_e32 v129, 0xbfb8aa3b, v104
	v_cvt_pk_bf16_f32 v132, v132, v133
	v_cvt_pk_bf16_f32 v133, v134, v135
	v_exp_f32_e32 v129, v129
	v_mul_f32_e32 v134, 0xbfb8aa3b, v105
	v_exp_f32_e32 v134, v134
	ds_write2_b64 v128, v[130:131], v[132:133] offset0:16 offset1:18
	v_add_f32_e32 v129, 1.0, v129
	v_rcp_f32_e32 v130, v129
	v_add_f32_e32 v129, 1.0, v134
	v_rcp_f32_e32 v131, v129
	v_mul_f32_e32 v129, 0xbfb8aa3b, v106
	v_exp_f32_e32 v129, v129
	v_mul_f32_e32 v132, 0xbfb8aa3b, v107
	v_exp_f32_e32 v133, v132
	v_mul_f32_e32 v134, 0xbfb8aa3b, v109
	v_add_f32_e32 v129, 1.0, v129
	v_rcp_f32_e32 v132, v129
	v_add_f32_e32 v129, 1.0, v133
	v_rcp_f32_e32 v133, v129
	v_mul_f32_e32 v129, 0xbfb8aa3b, v108
	v_exp_f32_e32 v129, v129
	v_exp_f32_e32 v135, v134
	v_pk_mul_f32 v[130:131], v[104:105], v[130:131]
	v_pk_mul_f32 v[132:133], v[106:107], v[132:133]
	v_add_f32_e32 v129, 1.0, v129
	v_rcp_f32_e32 v134, v129
	v_add_f32_e32 v129, 1.0, v135
	v_mul_f32_e32 v135, 0xbfb8aa3b, v110
	v_exp_f32_e32 v136, v135
	v_mul_f32_e32 v135, 0xbfb8aa3b, v111
	v_exp_f32_e32 v137, v135
	v_rcp_f32_e32 v135, v129
	v_add_f32_e32 v129, 1.0, v136
	v_rcp_f32_e32 v136, v129
	v_add_f32_e32 v129, 1.0, v137
	v_rcp_f32_e32 v137, v129
	v_cvt_pk_bf16_f32 v130, v130, v131
	v_cvt_pk_bf16_f32 v131, v132, v133
	v_pk_mul_f32 v[132:133], v[108:109], v[134:135]
	v_pk_mul_f32 v[134:135], v[110:111], v[136:137]
	v_mul_f32_e32 v129, 0xbfb8aa3b, v64
	v_cvt_pk_bf16_f32 v132, v132, v133
	v_cvt_pk_bf16_f32 v133, v134, v135
	v_exp_f32_e32 v129, v129
	v_mul_f32_e32 v134, 0xbfb8aa3b, v65
	v_exp_f32_e32 v134, v134
	ds_write2_b64 v128, v[130:131], v[132:133] offset0:20 offset1:22
	v_add_f32_e32 v129, 1.0, v129
	v_rcp_f32_e32 v130, v129
	v_add_f32_e32 v129, 1.0, v134
	v_rcp_f32_e32 v131, v129
	v_mul_f32_e32 v129, 0xbfb8aa3b, v66
	v_exp_f32_e32 v129, v129
	v_mul_f32_e32 v132, 0xbfb8aa3b, v67
	v_exp_f32_e32 v133, v132
	v_mul_f32_e32 v134, 0xbfb8aa3b, v69
	v_add_f32_e32 v129, 1.0, v129
	v_rcp_f32_e32 v132, v129
	v_add_f32_e32 v129, 1.0, v133
	v_rcp_f32_e32 v133, v129
	v_mul_f32_e32 v129, 0xbfb8aa3b, v68
	v_exp_f32_e32 v129, v129
	v_exp_f32_e32 v135, v134
	v_pk_mul_f32 v[130:131], v[64:65], v[130:131]
	v_pk_mul_f32 v[132:133], v[66:67], v[132:133]
	v_add_f32_e32 v129, 1.0, v129
	v_rcp_f32_e32 v134, v129
	v_add_f32_e32 v129, 1.0, v135
	v_mul_f32_e32 v135, 0xbfb8aa3b, v70
	v_exp_f32_e32 v136, v135
	v_mul_f32_e32 v135, 0xbfb8aa3b, v71
	v_exp_f32_e32 v137, v135
	v_rcp_f32_e32 v135, v129
	v_add_f32_e32 v129, 1.0, v136
	v_rcp_f32_e32 v136, v129
	v_add_f32_e32 v129, 1.0, v137
	v_rcp_f32_e32 v137, v129
	v_cvt_pk_bf16_f32 v130, v130, v131
	v_cvt_pk_bf16_f32 v131, v132, v133
	v_pk_mul_f32 v[132:133], v[68:69], v[134:135]
	v_pk_mul_f32 v[134:135], v[70:71], v[136:137]
	v_mul_f32_e32 v129, 0xbfb8aa3b, v72
	v_cvt_pk_bf16_f32 v132, v132, v133
	v_cvt_pk_bf16_f32 v133, v134, v135
	v_exp_f32_e32 v129, v129
	v_mul_f32_e32 v134, 0xbfb8aa3b, v73
	v_exp_f32_e32 v134, v134
	ds_write2_b64 v128, v[130:131], v[132:133] offset0:24 offset1:26
	v_add_f32_e32 v129, 1.0, v129
	v_rcp_f32_e32 v130, v129
	v_add_f32_e32 v129, 1.0, v134
	v_rcp_f32_e32 v131, v129
	v_mul_f32_e32 v129, 0xbfb8aa3b, v74
	v_exp_f32_e32 v129, v129
	v_mul_f32_e32 v132, 0xbfb8aa3b, v75
	v_exp_f32_e32 v133, v132
	v_mul_f32_e32 v134, 0xbfb8aa3b, v77
	v_add_f32_e32 v129, 1.0, v129
	v_rcp_f32_e32 v132, v129
	v_add_f32_e32 v129, 1.0, v133
	v_rcp_f32_e32 v133, v129
	v_mul_f32_e32 v129, 0xbfb8aa3b, v76
	v_exp_f32_e32 v129, v129
	v_exp_f32_e32 v135, v134
	v_pk_mul_f32 v[130:131], v[72:73], v[130:131]
	v_pk_mul_f32 v[132:133], v[74:75], v[132:133]
	v_add_f32_e32 v129, 1.0, v129
	v_rcp_f32_e32 v134, v129
	v_add_f32_e32 v129, 1.0, v135
	v_mul_f32_e32 v135, 0xbfb8aa3b, v78
	v_exp_f32_e32 v136, v135
	v_mul_f32_e32 v135, 0xbfb8aa3b, v79
	v_exp_f32_e32 v137, v135
	v_rcp_f32_e32 v135, v129
	v_add_f32_e32 v129, 1.0, v136
	v_rcp_f32_e32 v136, v129
	v_add_f32_e32 v129, 1.0, v137
	v_rcp_f32_e32 v137, v129
	v_cvt_pk_bf16_f32 v130, v130, v131
	v_cvt_pk_bf16_f32 v131, v132, v133
	v_pk_mul_f32 v[132:133], v[76:77], v[134:135]
	v_pk_mul_f32 v[134:135], v[78:79], v[136:137]
	v_mul_f32_e32 v129, 0xbfb8aa3b, v48
	v_cvt_pk_bf16_f32 v132, v132, v133
	v_cvt_pk_bf16_f32 v133, v134, v135
	v_exp_f32_e32 v129, v129
	v_mul_f32_e32 v134, 0xbfb8aa3b, v49
	v_exp_f32_e32 v134, v134
	ds_write2_b64 v128, v[130:131], v[132:133] offset0:28 offset1:30
	v_add_f32_e32 v129, 1.0, v129
	v_rcp_f32_e32 v130, v129
	v_add_f32_e32 v129, 1.0, v134
	v_rcp_f32_e32 v131, v129
	v_mul_f32_e32 v129, 0xbfb8aa3b, v50
	v_exp_f32_e32 v129, v129
	v_mul_f32_e32 v132, 0xbfb8aa3b, v51
	v_exp_f32_e32 v133, v132
	v_mul_f32_e32 v134, 0xbfb8aa3b, v53
	v_add_f32_e32 v129, 1.0, v129
	v_rcp_f32_e32 v132, v129
	v_add_f32_e32 v129, 1.0, v133
	v_rcp_f32_e32 v133, v129
	v_mul_f32_e32 v129, 0xbfb8aa3b, v52
	v_exp_f32_e32 v129, v129
	v_exp_f32_e32 v135, v134
	v_pk_mul_f32 v[130:131], v[48:49], v[130:131]
	v_pk_mul_f32 v[132:133], v[50:51], v[132:133]
	v_add_f32_e32 v129, 1.0, v129
	v_rcp_f32_e32 v134, v129
	v_add_f32_e32 v129, 1.0, v135
	v_mul_f32_e32 v135, 0xbfb8aa3b, v54
	v_exp_f32_e32 v136, v135
	v_mul_f32_e32 v135, 0xbfb8aa3b, v55
	v_exp_f32_e32 v137, v135
	v_rcp_f32_e32 v135, v129
	v_add_f32_e32 v129, 1.0, v136
	v_rcp_f32_e32 v136, v129
	v_add_f32_e32 v129, 1.0, v137
	v_rcp_f32_e32 v137, v129
	v_cvt_pk_bf16_f32 v130, v130, v131
	v_cvt_pk_bf16_f32 v131, v132, v133
	v_pk_mul_f32 v[132:133], v[52:53], v[134:135]
	v_pk_mul_f32 v[134:135], v[54:55], v[136:137]
	v_mul_f32_e32 v129, 0xbfb8aa3b, v56
	v_cvt_pk_bf16_f32 v132, v132, v133
	v_cvt_pk_bf16_f32 v133, v134, v135
	v_exp_f32_e32 v129, v129
	v_mul_f32_e32 v134, 0xbfb8aa3b, v57
	v_exp_f32_e32 v134, v134
	v_add_u32_e32 v128, 0x4000, v128
	v_add_f32_e32 v129, 1.0, v129
	ds_write2_b64 v128, v[130:131], v[132:133] offset0:64 offset1:66
	v_rcp_f32_e32 v130, v129
	v_add_f32_e32 v129, 1.0, v134
	v_rcp_f32_e32 v131, v129
	v_mul_f32_e32 v129, 0xbfb8aa3b, v58
	v_exp_f32_e32 v129, v129
	v_mul_f32_e32 v132, 0xbfb8aa3b, v59
	v_exp_f32_e32 v133, v132
	v_mul_f32_e32 v134, 0xbfb8aa3b, v61
	v_add_f32_e32 v129, 1.0, v129
	v_rcp_f32_e32 v132, v129
	v_add_f32_e32 v129, 1.0, v133
	v_rcp_f32_e32 v133, v129
	v_mul_f32_e32 v129, 0xbfb8aa3b, v60
	v_exp_f32_e32 v129, v129
	v_exp_f32_e32 v135, v134
	v_pk_mul_f32 v[130:131], v[56:57], v[130:131]
	v_pk_mul_f32 v[132:133], v[58:59], v[132:133]
	v_add_f32_e32 v129, 1.0, v129
	v_rcp_f32_e32 v134, v129
	v_add_f32_e32 v129, 1.0, v135
	v_mul_f32_e32 v135, 0xbfb8aa3b, v62
	v_exp_f32_e32 v136, v135
	v_mul_f32_e32 v135, 0xbfb8aa3b, v63
	v_exp_f32_e32 v137, v135
	v_rcp_f32_e32 v135, v129
	v_add_f32_e32 v129, 1.0, v136
	v_rcp_f32_e32 v136, v129
	v_add_f32_e32 v129, 1.0, v137
	v_rcp_f32_e32 v137, v129
	v_cvt_pk_bf16_f32 v130, v130, v131
	v_cvt_pk_bf16_f32 v131, v132, v133
	v_pk_mul_f32 v[132:133], v[60:61], v[134:135]
	v_pk_mul_f32 v[134:135], v[62:63], v[136:137]
	v_mul_f32_e32 v129, 0xbfb8aa3b, v16
	v_cvt_pk_bf16_f32 v132, v132, v133
	v_cvt_pk_bf16_f32 v133, v134, v135
	v_exp_f32_e32 v129, v129
	v_mul_f32_e32 v134, 0xbfb8aa3b, v17
	v_exp_f32_e32 v134, v134
	ds_write2_b64 v128, v[130:131], v[132:133] offset0:68 offset1:70
	v_add_f32_e32 v129, 1.0, v129
	v_rcp_f32_e32 v130, v129
	v_add_f32_e32 v129, 1.0, v134
	v_rcp_f32_e32 v131, v129
	v_mul_f32_e32 v129, 0xbfb8aa3b, v18
	v_exp_f32_e32 v129, v129
	v_mul_f32_e32 v132, 0xbfb8aa3b, v19
	v_exp_f32_e32 v133, v132
	v_mul_f32_e32 v134, 0xbfb8aa3b, v21
	v_add_f32_e32 v129, 1.0, v129
	v_rcp_f32_e32 v132, v129
	v_add_f32_e32 v129, 1.0, v133
	v_rcp_f32_e32 v133, v129
	v_mul_f32_e32 v129, 0xbfb8aa3b, v20
	v_exp_f32_e32 v129, v129
	v_exp_f32_e32 v135, v134
	v_pk_mul_f32 v[130:131], v[16:17], v[130:131]
	v_pk_mul_f32 v[132:133], v[18:19], v[132:133]
	v_add_f32_e32 v129, 1.0, v129
	v_rcp_f32_e32 v134, v129
	v_add_f32_e32 v129, 1.0, v135
	v_mul_f32_e32 v135, 0xbfb8aa3b, v22
	v_exp_f32_e32 v136, v135
	v_mul_f32_e32 v135, 0xbfb8aa3b, v23
	v_exp_f32_e32 v137, v135
	v_rcp_f32_e32 v135, v129
	v_add_f32_e32 v129, 1.0, v136
	v_rcp_f32_e32 v136, v129
	v_add_f32_e32 v129, 1.0, v137
	v_rcp_f32_e32 v137, v129
	v_cvt_pk_bf16_f32 v130, v130, v131
	v_cvt_pk_bf16_f32 v131, v132, v133
	v_pk_mul_f32 v[132:133], v[20:21], v[134:135]
	v_pk_mul_f32 v[134:135], v[22:23], v[136:137]
	v_mul_f32_e32 v129, 0xbfb8aa3b, v24
	v_cvt_pk_bf16_f32 v132, v132, v133
	v_cvt_pk_bf16_f32 v133, v134, v135
	v_exp_f32_e32 v129, v129
	v_mul_f32_e32 v134, 0xbfb8aa3b, v25
	v_exp_f32_e32 v134, v134
	ds_write2_b64 v128, v[130:131], v[132:133] offset0:72 offset1:74
	v_add_f32_e32 v129, 1.0, v129
	v_rcp_f32_e32 v130, v129
	v_add_f32_e32 v129, 1.0, v134
	v_rcp_f32_e32 v131, v129
	v_mul_f32_e32 v129, 0xbfb8aa3b, v26
	v_exp_f32_e32 v129, v129
	v_mul_f32_e32 v132, 0xbfb8aa3b, v27
	v_exp_f32_e32 v133, v132
	v_mul_f32_e32 v134, 0xbfb8aa3b, v29
	v_add_f32_e32 v129, 1.0, v129
	v_rcp_f32_e32 v132, v129
	v_add_f32_e32 v129, 1.0, v133
	v_rcp_f32_e32 v133, v129
	v_mul_f32_e32 v129, 0xbfb8aa3b, v28
	v_exp_f32_e32 v129, v129
	v_exp_f32_e32 v135, v134
	v_pk_mul_f32 v[130:131], v[24:25], v[130:131]
	v_pk_mul_f32 v[132:133], v[26:27], v[132:133]
	v_add_f32_e32 v129, 1.0, v129
	v_rcp_f32_e32 v134, v129
	v_add_f32_e32 v129, 1.0, v135
	v_mul_f32_e32 v135, 0xbfb8aa3b, v30
	v_exp_f32_e32 v136, v135
	v_mul_f32_e32 v135, 0xbfb8aa3b, v31
	v_exp_f32_e32 v137, v135
	v_rcp_f32_e32 v135, v129
	v_add_f32_e32 v129, 1.0, v136
	v_rcp_f32_e32 v136, v129
	v_add_f32_e32 v129, 1.0, v137
	v_rcp_f32_e32 v137, v129
	v_cvt_pk_bf16_f32 v130, v130, v131
	v_cvt_pk_bf16_f32 v131, v132, v133
	v_pk_mul_f32 v[132:133], v[28:29], v[134:135]
	v_pk_mul_f32 v[134:135], v[30:31], v[136:137]
	v_mul_f32_e32 v129, 0xbfb8aa3b, v32
	v_cvt_pk_bf16_f32 v132, v132, v133
	v_cvt_pk_bf16_f32 v133, v134, v135
	v_exp_f32_e32 v129, v129
	v_mul_f32_e32 v134, 0xbfb8aa3b, v33
	v_exp_f32_e32 v134, v134
	ds_write2_b64 v128, v[130:131], v[132:133] offset0:76 offset1:78
	v_add_f32_e32 v129, 1.0, v129
	v_rcp_f32_e32 v130, v129
	v_add_f32_e32 v129, 1.0, v134
	v_rcp_f32_e32 v131, v129
	v_mul_f32_e32 v129, 0xbfb8aa3b, v34
	v_exp_f32_e32 v129, v129
	v_mul_f32_e32 v132, 0xbfb8aa3b, v35
	v_exp_f32_e32 v133, v132
	v_mul_f32_e32 v134, 0xbfb8aa3b, v37
	v_add_f32_e32 v129, 1.0, v129
	v_rcp_f32_e32 v132, v129
	v_add_f32_e32 v129, 1.0, v133
	v_rcp_f32_e32 v133, v129
	v_mul_f32_e32 v129, 0xbfb8aa3b, v36
	v_exp_f32_e32 v129, v129
	v_exp_f32_e32 v135, v134
	v_pk_mul_f32 v[130:131], v[32:33], v[130:131]
	v_pk_mul_f32 v[132:133], v[34:35], v[132:133]
	v_add_f32_e32 v129, 1.0, v129
	v_rcp_f32_e32 v134, v129
	v_add_f32_e32 v129, 1.0, v135
	v_mul_f32_e32 v135, 0xbfb8aa3b, v38
	v_exp_f32_e32 v136, v135
	v_mul_f32_e32 v135, 0xbfb8aa3b, v39
	v_exp_f32_e32 v137, v135
	v_rcp_f32_e32 v135, v129
	v_add_f32_e32 v129, 1.0, v136
	v_rcp_f32_e32 v136, v129
	v_add_f32_e32 v129, 1.0, v137
	v_rcp_f32_e32 v137, v129
	v_cvt_pk_bf16_f32 v130, v130, v131
	v_cvt_pk_bf16_f32 v131, v132, v133
	v_pk_mul_f32 v[132:133], v[36:37], v[134:135]
	v_pk_mul_f32 v[134:135], v[38:39], v[136:137]
	v_mul_f32_e32 v129, 0xbfb8aa3b, v40
	v_cvt_pk_bf16_f32 v132, v132, v133
	v_cvt_pk_bf16_f32 v133, v134, v135
	v_exp_f32_e32 v129, v129
	v_mul_f32_e32 v134, 0xbfb8aa3b, v41
	v_exp_f32_e32 v134, v134
	ds_write2_b64 v128, v[130:131], v[132:133] offset0:80 offset1:82
	v_add_f32_e32 v129, 1.0, v129
	v_rcp_f32_e32 v130, v129
	v_add_f32_e32 v129, 1.0, v134
	v_rcp_f32_e32 v131, v129
	v_mul_f32_e32 v129, 0xbfb8aa3b, v42
	v_exp_f32_e32 v129, v129
	v_mul_f32_e32 v132, 0xbfb8aa3b, v43
	v_exp_f32_e32 v133, v132
	v_mul_f32_e32 v134, 0xbfb8aa3b, v45
	v_add_f32_e32 v129, 1.0, v129
	v_rcp_f32_e32 v132, v129
	v_add_f32_e32 v129, 1.0, v133
	v_rcp_f32_e32 v133, v129
	v_mul_f32_e32 v129, 0xbfb8aa3b, v44
	v_exp_f32_e32 v129, v129
	v_exp_f32_e32 v135, v134
	v_pk_mul_f32 v[130:131], v[40:41], v[130:131]
	v_pk_mul_f32 v[132:133], v[42:43], v[132:133]
	v_add_f32_e32 v129, 1.0, v129
	v_rcp_f32_e32 v134, v129
	v_add_f32_e32 v129, 1.0, v135
	v_mul_f32_e32 v135, 0xbfb8aa3b, v46
	v_exp_f32_e32 v136, v135
	v_mul_f32_e32 v135, 0xbfb8aa3b, v47
	v_exp_f32_e32 v137, v135
	v_rcp_f32_e32 v135, v129
	v_add_f32_e32 v129, 1.0, v136
	v_rcp_f32_e32 v136, v129
	v_add_f32_e32 v129, 1.0, v137
	v_rcp_f32_e32 v137, v129
	v_cvt_pk_bf16_f32 v130, v130, v131
	v_cvt_pk_bf16_f32 v131, v132, v133
	v_pk_mul_f32 v[132:133], v[44:45], v[134:135]
	v_pk_mul_f32 v[134:135], v[46:47], v[136:137]
	v_mul_f32_e32 v129, 0xbfb8aa3b, v0
	v_cvt_pk_bf16_f32 v132, v132, v133
	v_cvt_pk_bf16_f32 v133, v134, v135
	v_exp_f32_e32 v129, v129
	v_mul_f32_e32 v134, 0xbfb8aa3b, v1
	v_exp_f32_e32 v134, v134
	ds_write2_b64 v128, v[130:131], v[132:133] offset0:84 offset1:86
	v_add_f32_e32 v129, 1.0, v129
	v_rcp_f32_e32 v130, v129
	v_add_f32_e32 v129, 1.0, v134
	v_rcp_f32_e32 v131, v129
	v_mul_f32_e32 v129, 0xbfb8aa3b, v2
	v_exp_f32_e32 v129, v129
	v_mul_f32_e32 v132, 0xbfb8aa3b, v3
	v_exp_f32_e32 v133, v132
	v_mul_f32_e32 v134, 0xbfb8aa3b, v5
	v_add_f32_e32 v129, 1.0, v129
	v_rcp_f32_e32 v132, v129
	v_add_f32_e32 v129, 1.0, v133
	v_rcp_f32_e32 v133, v129
	v_mul_f32_e32 v129, 0xbfb8aa3b, v4
	v_exp_f32_e32 v129, v129
	v_exp_f32_e32 v135, v134
	v_pk_mul_f32 v[130:131], v[0:1], v[130:131]
	v_pk_mul_f32 v[132:133], v[2:3], v[132:133]
	v_add_f32_e32 v129, 1.0, v129
	v_rcp_f32_e32 v134, v129
	v_add_f32_e32 v129, 1.0, v135
	v_mul_f32_e32 v135, 0xbfb8aa3b, v6
	v_exp_f32_e32 v136, v135
	v_mul_f32_e32 v135, 0xbfb8aa3b, v7
	v_exp_f32_e32 v137, v135
	v_rcp_f32_e32 v135, v129
	v_add_f32_e32 v129, 1.0, v136
	v_rcp_f32_e32 v136, v129
	v_add_f32_e32 v129, 1.0, v137
	v_rcp_f32_e32 v137, v129
	v_cvt_pk_bf16_f32 v130, v130, v131
	v_cvt_pk_bf16_f32 v131, v132, v133
	v_pk_mul_f32 v[132:133], v[4:5], v[134:135]
	v_pk_mul_f32 v[134:135], v[6:7], v[136:137]
	v_mul_f32_e32 v129, 0xbfb8aa3b, v8
	v_cvt_pk_bf16_f32 v132, v132, v133
	v_cvt_pk_bf16_f32 v133, v134, v135
	v_exp_f32_e32 v129, v129
	v_mul_f32_e32 v134, 0xbfb8aa3b, v9
	v_exp_f32_e32 v134, v134
	ds_write2_b64 v128, v[130:131], v[132:133] offset0:88 offset1:90
	v_add_f32_e32 v129, 1.0, v129
	v_rcp_f32_e32 v130, v129
	v_add_f32_e32 v129, 1.0, v134
	v_rcp_f32_e32 v131, v129
	v_mul_f32_e32 v129, 0xbfb8aa3b, v10
	v_exp_f32_e32 v129, v129
	v_mul_f32_e32 v132, 0xbfb8aa3b, v11
	v_exp_f32_e32 v133, v132
	v_mul_f32_e32 v134, 0xbfb8aa3b, v13
	v_add_f32_e32 v129, 1.0, v129
	v_rcp_f32_e32 v132, v129
	v_add_f32_e32 v129, 1.0, v133
	v_rcp_f32_e32 v133, v129
	v_mul_f32_e32 v129, 0xbfb8aa3b, v12
	v_exp_f32_e32 v129, v129
	v_exp_f32_e32 v135, v134
	s_add_i32 s12, s36, -14
	s_lshl_b64 s[2:3], s[12:13], 9
	v_add_f32_e32 v129, 1.0, v129
	v_rcp_f32_e32 v134, v129
	v_add_f32_e32 v129, 1.0, v135
	v_mul_f32_e32 v135, 0xbfb8aa3b, v14
	v_exp_f32_e32 v136, v135
	v_mul_f32_e32 v135, 0xbfb8aa3b, v15
	v_exp_f32_e32 v137, v135
	v_rcp_f32_e32 v135, v129
	v_add_f32_e32 v129, 1.0, v136
	v_rcp_f32_e32 v136, v129
	v_add_f32_e32 v129, 1.0, v137
	v_rcp_f32_e32 v137, v129
	v_pk_mul_f32 v[130:131], v[8:9], v[130:131]
	v_pk_mul_f32 v[132:133], v[10:11], v[132:133]
	s_add_u32 s12, s61, s2
	v_cvt_pk_bf16_f32 v130, v130, v131
	v_cvt_pk_bf16_f32 v131, v132, v133
	v_pk_mul_f32 v[132:133], v[12:13], v[134:135]
	v_pk_mul_f32 v[134:135], v[14:15], v[136:137]
	s_addc_u32 s37, s62, s3
	s_lshl_b64 s[2:3], s[34:35], 20
	v_cvt_pk_bf16_f32 v132, v132, v133
	v_cvt_pk_bf16_f32 v133, v134, v135
	v_mov_b32_e32 v142, v208
	s_add_u32 s2, s12, s2
	ds_write2_b64 v128, v[130:131], v[132:133] offset0:92 offset1:94
	s_addc_u32 s3, s37, s3
	v_lshlrev_b32_e32 v128, 4, v142
	v_ashrrev_i32_e32 v132, 5, v142
	v_and_b32_e32 v170, 0x1f0, v128
	v_ashrrev_i32_e32 v133, 31, v132
	v_lshl_add_u64 v[136:137], s[2:3], 0, v[170:171]
	v_mad_u64_u32 v[128:129], s[2:3], v132, s43, v[170:171]
	v_lshlrev_b64 v[132:133], 12, v[132:133]
	v_lshl_add_u64 v[138:139], v[136:137], 0, v[132:133]
	v_add_u32_e32 v132, 0x200, v142
	s_waitcnt lgkmcnt(0)
	s_barrier
	ds_read_b128 v[128:131], v128
	v_ashrrev_i32_e32 v140, 5, v132
	v_mad_u64_u32 v[132:133], s[2:3], v140, s43, v[170:171]
	ds_read_b128 v[132:135], v132
	v_ashrrev_i32_e32 v141, 31, v140
	s_waitcnt lgkmcnt(1)
	global_store_dwordx4 v[138:139], v[128:131], off
	s_nop 1
	v_lshlrev_b64 v[128:129], 12, v[140:141]
	v_lshl_add_u64 v[128:129], v[136:137], 0, v[128:129]
	s_waitcnt lgkmcnt(0)
	global_store_dwordx4 v[128:129], v[132:135], off
	v_add_u32_e32 v128, 0x400, v142
	s_nop 0
	v_ashrrev_i32_e32 v132, 5, v128
	v_ashrrev_i32_e32 v133, 31, v132
	v_mad_u64_u32 v[128:129], s[2:3], v132, s43, v[170:171]
	v_lshlrev_b64 v[132:133], 12, v[132:133]
	v_lshl_add_u64 v[138:139], v[136:137], 0, v[132:133]
	v_add_u32_e32 v132, 0x600, v142
	ds_read_b128 v[128:131], v128
	v_ashrrev_i32_e32 v140, 5, v132
	v_mad_u64_u32 v[132:133], s[2:3], v140, s43, v[170:171]
	ds_read_b128 v[132:135], v132
	v_ashrrev_i32_e32 v141, 31, v140
	s_waitcnt lgkmcnt(1)
	global_store_dwordx4 v[138:139], v[128:131], off
	s_nop 1
	v_lshlrev_b64 v[128:129], 12, v[140:141]
	v_lshl_add_u64 v[128:129], v[136:137], 0, v[128:129]
	s_waitcnt lgkmcnt(0)
	global_store_dwordx4 v[128:129], v[132:135], off
	v_add_u32_e32 v128, 0x800, v142
	s_nop 0
	v_ashrrev_i32_e32 v132, 5, v128
	v_ashrrev_i32_e32 v133, 31, v132
	v_mad_u64_u32 v[128:129], s[2:3], v132, s43, v[170:171]
	v_lshlrev_b64 v[132:133], 12, v[132:133]
	v_lshl_add_u64 v[138:139], v[136:137], 0, v[132:133]
	v_add_u32_e32 v132, 0xa00, v142
	ds_read_b128 v[128:131], v128
	v_ashrrev_i32_e32 v140, 5, v132
	v_mad_u64_u32 v[132:133], s[2:3], v140, s43, v[170:171]
	ds_read_b128 v[132:135], v132
	v_ashrrev_i32_e32 v141, 31, v140
	s_waitcnt lgkmcnt(1)
	global_store_dwordx4 v[138:139], v[128:131], off
	s_nop 1
	v_lshlrev_b64 v[128:129], 12, v[140:141]
	v_lshl_add_u64 v[128:129], v[136:137], 0, v[128:129]
	s_waitcnt lgkmcnt(0)
	global_store_dwordx4 v[128:129], v[132:135], off
	v_add_u32_e32 v128, 0xc00, v142
	s_nop 0
	v_ashrrev_i32_e32 v132, 5, v128
	v_ashrrev_i32_e32 v133, 31, v132
	v_mad_u64_u32 v[128:129], s[2:3], v132, s43, v[170:171]
	v_lshlrev_b64 v[132:133], 12, v[132:133]
	v_lshl_add_u64 v[138:139], v[136:137], 0, v[132:133]
	v_add_u32_e32 v132, 0xe00, v142
	ds_read_b128 v[128:131], v128
	v_ashrrev_i32_e32 v140, 5, v132
	v_mad_u64_u32 v[132:133], s[2:3], v140, s43, v[170:171]
	ds_read_b128 v[132:135], v132
	v_ashrrev_i32_e32 v141, 31, v140
	s_waitcnt lgkmcnt(1)
	global_store_dwordx4 v[138:139], v[128:131], off
	s_nop 1
	v_lshlrev_b64 v[128:129], 12, v[140:141]
	v_lshl_add_u64 v[128:129], v[136:137], 0, v[128:129]
	s_waitcnt lgkmcnt(0)
	global_store_dwordx4 v[128:129], v[132:135], off
	v_add_u32_e32 v128, 0x1000, v142
	s_nop 0
	v_ashrrev_i32_e32 v132, 5, v128
	v_ashrrev_i32_e32 v133, 31, v132
	v_mad_u64_u32 v[128:129], s[2:3], v132, s43, v[170:171]
	v_lshlrev_b64 v[132:133], 12, v[132:133]
	v_lshl_add_u64 v[138:139], v[136:137], 0, v[132:133]
	v_add_u32_e32 v132, 0x1200, v142
	ds_read_b128 v[128:131], v128
	v_ashrrev_i32_e32 v140, 5, v132
	v_mad_u64_u32 v[132:133], s[2:3], v140, s43, v[170:171]
	ds_read_b128 v[132:135], v132
	v_ashrrev_i32_e32 v141, 31, v140
	s_waitcnt lgkmcnt(1)
	global_store_dwordx4 v[138:139], v[128:131], off
	s_nop 1
	v_lshlrev_b64 v[128:129], 12, v[140:141]
	v_lshl_add_u64 v[128:129], v[136:137], 0, v[128:129]
	s_waitcnt lgkmcnt(0)
	global_store_dwordx4 v[128:129], v[132:135], off
	v_add_u32_e32 v128, 0x1400, v142
	s_nop 0
	v_ashrrev_i32_e32 v132, 5, v128
	v_ashrrev_i32_e32 v133, 31, v132
	v_mad_u64_u32 v[128:129], s[2:3], v132, s43, v[170:171]
	v_lshlrev_b64 v[132:133], 12, v[132:133]
	v_lshl_add_u64 v[138:139], v[136:137], 0, v[132:133]
	v_add_u32_e32 v132, 0x1600, v142
	ds_read_b128 v[128:131], v128
	v_ashrrev_i32_e32 v140, 5, v132
	v_mad_u64_u32 v[132:133], s[2:3], v140, s43, v[170:171]
	ds_read_b128 v[132:135], v132
	v_ashrrev_i32_e32 v141, 31, v140
	s_waitcnt lgkmcnt(1)
	global_store_dwordx4 v[138:139], v[128:131], off
	s_nop 1
	v_lshlrev_b64 v[128:129], 12, v[140:141]
	v_lshl_add_u64 v[128:129], v[136:137], 0, v[128:129]
	s_waitcnt lgkmcnt(0)
	global_store_dwordx4 v[128:129], v[132:135], off
	v_add_u32_e32 v128, 0x1800, v142
	s_nop 0
	v_ashrrev_i32_e32 v132, 5, v128
	v_ashrrev_i32_e32 v133, 31, v132
	v_mad_u64_u32 v[128:129], s[2:3], v132, s43, v[170:171]
	v_lshlrev_b64 v[132:133], 12, v[132:133]
	v_lshl_add_u64 v[138:139], v[136:137], 0, v[132:133]
	v_add_u32_e32 v132, 0x1a00, v142
	ds_read_b128 v[128:131], v128
	v_ashrrev_i32_e32 v140, 5, v132
	v_mad_u64_u32 v[132:133], s[2:3], v140, s43, v[170:171]
	ds_read_b128 v[132:135], v132
	v_ashrrev_i32_e32 v141, 31, v140
	s_waitcnt lgkmcnt(1)
	global_store_dwordx4 v[138:139], v[128:131], off
	s_nop 1
	v_lshlrev_b64 v[128:129], 12, v[140:141]
	v_lshl_add_u64 v[128:129], v[136:137], 0, v[128:129]
	s_waitcnt lgkmcnt(0)
	global_store_dwordx4 v[128:129], v[132:135], off
	v_add_u32_e32 v128, 0x1c00, v142
	s_nop 0
	v_ashrrev_i32_e32 v132, 5, v128
	v_ashrrev_i32_e32 v133, 31, v132
	v_mad_u64_u32 v[128:129], s[2:3], v132, s43, v[170:171]
	v_lshlrev_b64 v[132:133], 12, v[132:133]
	v_lshl_add_u64 v[138:139], v[136:137], 0, v[132:133]
	v_add_u32_e32 v132, 0x1e00, v142
	ds_read_b128 v[128:131], v128
	v_ashrrev_i32_e32 v140, 5, v132
	v_mad_u64_u32 v[132:133], s[2:3], v140, s43, v[170:171]
	ds_read_b128 v[132:135], v132
	v_ashrrev_i32_e32 v141, 31, v140
	s_waitcnt lgkmcnt(1)
	global_store_dwordx4 v[138:139], v[128:131], off
	s_mov_b64 s[2:3], 0
	s_nop 0
	v_lshlrev_b64 v[128:129], 12, v[140:141]
	v_lshl_add_u64 v[128:129], v[136:137], 0, v[128:129]
	s_waitcnt lgkmcnt(0)
	global_store_dwordx4 v[128:129], v[132:135], off
	s_barrier

.LBB0_628:
	s_cmpk_gt_i32 s83, 0x3ff
	s_mov_b64 s[2:3], -1
	s_cbranch_scc0 .LBB0_632
	s_add_i32 s2, s83, 0xfffffc00
	s_lshr_b32 s2, s2, 3
	s_mov_b32 s3, s15
	s_lshl_b64 s[6:7], s[2:3], 19
	s_add_u32 s6, s63, s6
	s_addc_u32 s7, s68, s7
	s_mov_b32 s56, s6
	s_mov_b32 s57, s7
	s_lshl_b32 s6, s83, 8
	s_and_b32 s6, s6, 0x700
	s_lshl_b32 s7, s6, 11
	s_add_u32 s54, s1, s7
	s_addc_u32 s55, s69, 0
	s_add_u32 s58, s54, 0x400000
	s_addc_u32 s59, s55, 0
	s_movk_i32 s7, 0x100
	s_mov_b32 s54, -2
	v_lshrrev_b32_e32 v212, 6, v208
	v_and_b32_e32 v213, 63, v208
	v_readfirstlane_b32 s98, v212
	v_and_b32_e32 v214, 3, v213
	v_bfe_u32 v215, v213, 2, 1
	v_lshl_or_b32 v214, v215, 3, v214
	v_bfe_u32 v215, v213, 3, 1
	v_lshl_or_b32 v214, v215, 2, v214
	s_and_b32 s14, s98, 1
	s_lshr_b32 s100, s98, 2
	s_lshl_b32 s99, s98, 10
	v_lshrrev_b32_e32 v215, 4, v213
	v_bfe_u32 v216, v214, 1, 3
	v_xor_b32_e32 v216, v215, v216
	v_lshlrev_b32_e32 v216, 4, v216
	v_lshl_add_u32 v214, s14, 6, v214
	v_lshl_add_u32 v168, v214, 7, v216
	v_xor_b32_e32 v171, 64, v168
	v_add_u32_e32 v170, 0x10000, v168
	v_add_u32_e32 v196, 0x10000, v171
	v_bfe_u32 v216, v213, 1, 3
	v_xor_b32_e32 v216, v215, v216
	v_lshlrev_b32_e32 v216, 4, v216
	v_and_b32_e32 v214, 15, v213
	s_lshr_b32 s101, s98, 1
	v_lshl_add_u32 v214, s101, 5, v214
	v_lshl_add_u32 v197, v214, 7, v216
	v_add_u32_e32 v197, 0x8000, v197
	v_xor_b32_e32 v199, 64, v197
	v_add_u32_e32 v198, 0x10000, v197
	v_add_u32_e32 v200, 0x10000, v199
	v_lshl_add_u32 v216, s14, 2, v215
	v_and_b32_e32 v214, 7, v213
	v_xor_b32_e32 v216, v214, v216
	v_lshlrev_b32_e32 v216, 4, v216
	v_lshrrev_b32_e32 v214, 3, v213
	v_lshl_add_u32 v215, s98, 3, v214
	v_lshl_add_u32 v201, v215, 11, v216
	v_add_u32_e32 v202, 0x40000, v201
	v_add_u32_e32 v203, 0x20000, v201
	v_add_u32_e32 v204, 0x60000, v201
	s_and_b32 s101, s98, 3
	s_lshl_b32 s101, s101, 3
	s_lshl_b32 s14, s100, 6
	s_add_u32 s101, s101, s14
	v_add_u32_e32 v215, s101, v214
	v_lshl_add_u32 v205, v215, 11, v216
	v_add_u32_e32 v206, 0x40000, v205
	v_add_u32_e32 v210, 0x10000, v205
	v_add_u32_e32 v211, 0x50000, v205
	v_mov_b32_e32 v112, 0
	v_mov_b32_e32 v113, 0
	v_mov_b32_e32 v114, 0
	v_mov_b32_e32 v115, 0
	v_mov_b32_e32 v116, 0
	v_mov_b32_e32 v117, 0
	v_mov_b32_e32 v118, 0
	v_mov_b32_e32 v119, 0
	v_mov_b32_e32 v120, 0
	v_mov_b32_e32 v121, 0
	v_mov_b32_e32 v122, 0
	v_mov_b32_e32 v123, 0
	v_mov_b32_e32 v124, 0
	v_mov_b32_e32 v125, 0
	v_mov_b32_e32 v126, 0
	v_mov_b32_e32 v127, 0
	v_mov_b32_e32 v96, 0
	v_mov_b32_e32 v97, 0
	v_mov_b32_e32 v98, 0
	v_mov_b32_e32 v99, 0
	v_mov_b32_e32 v100, 0
	v_mov_b32_e32 v101, 0
	v_mov_b32_e32 v102, 0
	v_mov_b32_e32 v103, 0
	v_mov_b32_e32 v104, 0
	v_mov_b32_e32 v105, 0
	v_mov_b32_e32 v106, 0
	v_mov_b32_e32 v107, 0
	v_mov_b32_e32 v108, 0
	v_mov_b32_e32 v109, 0
	v_mov_b32_e32 v110, 0
	v_mov_b32_e32 v111, 0
	v_mov_b32_e32 v80, 0
	v_mov_b32_e32 v81, 0
	v_mov_b32_e32 v82, 0
	v_mov_b32_e32 v83, 0
	v_mov_b32_e32 v84, 0
	v_mov_b32_e32 v85, 0
	v_mov_b32_e32 v86, 0
	v_mov_b32_e32 v87, 0
	v_mov_b32_e32 v88, 0
	v_mov_b32_e32 v89, 0
	v_mov_b32_e32 v90, 0
	v_mov_b32_e32 v91, 0
	v_mov_b32_e32 v92, 0
	v_mov_b32_e32 v93, 0
	v_mov_b32_e32 v94, 0
	v_mov_b32_e32 v95, 0
	v_mov_b32_e32 v64, 0
	v_mov_b32_e32 v65, 0
	v_mov_b32_e32 v66, 0
	v_mov_b32_e32 v67, 0
	v_mov_b32_e32 v68, 0
	v_mov_b32_e32 v69, 0
	v_mov_b32_e32 v70, 0
	v_mov_b32_e32 v71, 0
	v_mov_b32_e32 v72, 0
	v_mov_b32_e32 v73, 0
	v_mov_b32_e32 v74, 0
	v_mov_b32_e32 v75, 0
	v_mov_b32_e32 v76, 0
	v_mov_b32_e32 v77, 0
	v_mov_b32_e32 v78, 0
	v_mov_b32_e32 v79, 0
	v_mov_b32_e32 v48, 0
	v_mov_b32_e32 v49, 0
	v_mov_b32_e32 v50, 0
	v_mov_b32_e32 v51, 0
	v_mov_b32_e32 v52, 0
	v_mov_b32_e32 v53, 0
	v_mov_b32_e32 v54, 0
	v_mov_b32_e32 v55, 0
	v_mov_b32_e32 v56, 0
	v_mov_b32_e32 v57, 0
	v_mov_b32_e32 v58, 0
	v_mov_b32_e32 v59, 0
	v_mov_b32_e32 v60, 0
	v_mov_b32_e32 v61, 0
	v_mov_b32_e32 v62, 0
	v_mov_b32_e32 v63, 0
	v_mov_b32_e32 v32, 0
	v_mov_b32_e32 v33, 0
	v_mov_b32_e32 v34, 0
	v_mov_b32_e32 v35, 0
	v_mov_b32_e32 v36, 0
	v_mov_b32_e32 v37, 0
	v_mov_b32_e32 v38, 0
	v_mov_b32_e32 v39, 0
	v_mov_b32_e32 v40, 0
	v_mov_b32_e32 v41, 0
	v_mov_b32_e32 v42, 0
	v_mov_b32_e32 v43, 0
	v_mov_b32_e32 v44, 0
	v_mov_b32_e32 v45, 0
	v_mov_b32_e32 v46, 0
	v_mov_b32_e32 v47, 0
	v_mov_b32_e32 v16, 0
	v_mov_b32_e32 v17, 0
	v_mov_b32_e32 v18, 0
	v_mov_b32_e32 v19, 0
	v_mov_b32_e32 v20, 0
	v_mov_b32_e32 v21, 0
	v_mov_b32_e32 v22, 0
	v_mov_b32_e32 v23, 0
	v_mov_b32_e32 v24, 0
	v_mov_b32_e32 v25, 0
	v_mov_b32_e32 v26, 0
	v_mov_b32_e32 v27, 0
	v_mov_b32_e32 v28, 0
	v_mov_b32_e32 v29, 0
	v_mov_b32_e32 v30, 0
	v_mov_b32_e32 v31, 0
	v_mov_b32_e32 v0, 0
	v_mov_b32_e32 v1, 0
	v_mov_b32_e32 v2, 0
	v_mov_b32_e32 v3, 0
	v_mov_b32_e32 v4, 0
	v_mov_b32_e32 v5, 0
	v_mov_b32_e32 v6, 0
	v_mov_b32_e32 v7, 0
	v_mov_b32_e32 v8, 0
	v_mov_b32_e32 v9, 0
	v_mov_b32_e32 v10, 0
	v_mov_b32_e32 v11, 0
	v_mov_b32_e32 v12, 0
	v_mov_b32_e32 v13, 0
	v_mov_b32_e32 v14, 0
	v_mov_b32_e32 v15, 0
	s_add_u32 m0, s99, 0x8000
	s_nop 0
	global_load_lds_dwordx4 v205, s[56:57]
	s_add_u32 m0, s99, 0xa000
	s_nop 0
	global_load_lds_dwordx4 v206, s[56:57]
	s_add_u32 m0, s99, 0x0
	s_nop 0
	global_load_lds_dwordx4 v201, s[58:59]
	s_add_u32 m0, s99, 0x2000
	s_nop 0
	global_load_lds_dwordx4 v202, s[58:59]
	s_add_u32 m0, s99, 0xc000
	s_nop 0
	global_load_lds_dwordx4 v210, s[56:57]
	s_add_u32 m0, s99, 0xe000
	s_nop 0
	global_load_lds_dwordx4 v211, s[56:57]
	s_add_u32 s56, s56, 0x80
	s_addc_u32 s57, s57, 0
	s_add_u32 m0, s99, 0x4000
	s_nop 0
	global_load_lds_dwordx4 v203, s[58:59]
	s_add_u32 m0, s99, 0x6000
	s_nop 0
	global_load_lds_dwordx4 v204, s[58:59]
	s_add_u32 s58, s58, 0x80
	s_addc_u32 s59, s59, 0
	s_cmp_eq_u32 s100, 0
	s_cbranch_scc1 .Lg8_p6g_pg0
	s_barrier
.Lg8_p6g_pg0:
	s_waitcnt vmcnt(4)
	s_barrier
	s_add_u32 m0, s99, 0x18000
	s_nop 0
	global_load_lds_dwordx4 v205, s[56:57]
	s_add_u32 m0, s99, 0x1a000
	s_nop 0
	global_load_lds_dwordx4 v206, s[56:57]
	s_add_u32 m0, s99, 0x10000
	s_nop 0
	global_load_lds_dwordx4 v201, s[58:59]
	s_add_u32 m0, s99, 0x12000
	s_nop 0
	global_load_lds_dwordx4 v202, s[58:59]
	s_add_u32 m0, s99, 0x1c000
	s_nop 0
	global_load_lds_dwordx4 v210, s[56:57]
	s_add_u32 m0, s99, 0x1e000
	s_nop 0
	global_load_lds_dwordx4 v211, s[56:57]
	s_add_u32 s56, s56, 0x80
	s_addc_u32 s57, s57, 0
	s_waitcnt vmcnt(6)
	s_barrier
	s_mov_b32 s101, 7
.Lg8_p6g_loop:
	ds_read_b128 v[160:163], v197 offset:0
	ds_read_b128 v[164:167], v199 offset:0
	ds_read_b128 v[172:175], v197 offset:2048
	ds_read_b128 v[176:179], v199 offset:2048
	ds_read_b128 v[128:131], v168 offset:0
	ds_read_b128 v[132:135], v171 offset:0
	ds_read_b128 v[136:139], v168 offset:2048
	ds_read_b128 v[140:143], v171 offset:2048
	ds_read_b128 v[144:147], v168 offset:4096
	ds_read_b128 v[148:151], v171 offset:4096
	ds_read_b128 v[152:155], v168 offset:6144
	ds_read_b128 v[156:159], v171 offset:6144
	s_add_u32 m0, s99, 0x14000
	s_nop 0
	global_load_lds_dwordx4 v203, s[58:59]
	s_add_u32 m0, s99, 0x16000
	s_nop 0
	global_load_lds_dwordx4 v204, s[58:59]
	s_add_u32 s58, s58, 0x80
	s_addc_u32 s59, s59, 0
	s_waitcnt lgkmcnt(8)
	s_barrier
	s_waitcnt lgkmcnt(0)
	s_setprio 1
	v_mfma_f32_16x16x32_bf16 v[112:115], v[128:131], v[160:163], v[112:115]
	v_mfma_f32_16x16x32_bf16 v[112:115], v[132:135], v[164:167], v[112:115]
	v_mfma_f32_16x16x32_bf16 v[116:119], v[128:131], v[172:175], v[116:119]
	v_mfma_f32_16x16x32_bf16 v[116:119], v[132:135], v[176:179], v[116:119]
	v_mfma_f32_16x16x32_bf16 v[120:123], v[136:139], v[160:163], v[120:123]
	v_mfma_f32_16x16x32_bf16 v[120:123], v[140:143], v[164:167], v[120:123]
	v_mfma_f32_16x16x32_bf16 v[124:127], v[136:139], v[172:175], v[124:127]
	v_mfma_f32_16x16x32_bf16 v[124:127], v[140:143], v[176:179], v[124:127]
	v_mfma_f32_16x16x32_bf16 v[96:99], v[144:147], v[160:163], v[96:99]
	v_mfma_f32_16x16x32_bf16 v[96:99], v[148:151], v[164:167], v[96:99]
	v_mfma_f32_16x16x32_bf16 v[100:103], v[144:147], v[172:175], v[100:103]
	v_mfma_f32_16x16x32_bf16 v[100:103], v[148:151], v[176:179], v[100:103]
	v_mfma_f32_16x16x32_bf16 v[104:107], v[152:155], v[160:163], v[104:107]
	v_mfma_f32_16x16x32_bf16 v[104:107], v[156:159], v[164:167], v[104:107]
	v_mfma_f32_16x16x32_bf16 v[108:111], v[152:155], v[172:175], v[108:111]
	v_mfma_f32_16x16x32_bf16 v[108:111], v[156:159], v[176:179], v[108:111]
	s_setprio 0
	s_barrier
	ds_read_b128 v[180:183], v197 offset:16384
	ds_read_b128 v[184:187], v199 offset:16384
	ds_read_b128 v[188:191], v197 offset:18432
	ds_read_b128 v[192:195], v199 offset:18432
	s_add_u32 m0, s99, 0x8000
	s_nop 0
	global_load_lds_dwordx4 v205, s[56:57]
	s_add_u32 m0, s99, 0xa000
	s_nop 0
	global_load_lds_dwordx4 v206, s[56:57]
	s_barrier
	s_waitcnt lgkmcnt(0)
	s_setprio 1
	v_mfma_f32_16x16x32_bf16 v[48:51], v[128:131], v[180:183], v[48:51]
	v_mfma_f32_16x16x32_bf16 v[48:51], v[132:135], v[184:187], v[48:51]
	v_mfma_f32_16x16x32_bf16 v[52:55], v[128:131], v[188:191], v[52:55]
	v_mfma_f32_16x16x32_bf16 v[52:55], v[132:135], v[192:195], v[52:55]
	v_mfma_f32_16x16x32_bf16 v[56:59], v[136:139], v[180:183], v[56:59]
	v_mfma_f32_16x16x32_bf16 v[56:59], v[140:143], v[184:187], v[56:59]
	v_mfma_f32_16x16x32_bf16 v[60:63], v[136:139], v[188:191], v[60:63]
	v_mfma_f32_16x16x32_bf16 v[60:63], v[140:143], v[192:195], v[60:63]
	v_mfma_f32_16x16x32_bf16 v[32:35], v[144:147], v[180:183], v[32:35]
	v_mfma_f32_16x16x32_bf16 v[32:35], v[148:151], v[184:187], v[32:35]
	v_mfma_f32_16x16x32_bf16 v[36:39], v[144:147], v[188:191], v[36:39]
	v_mfma_f32_16x16x32_bf16 v[36:39], v[148:151], v[192:195], v[36:39]
	v_mfma_f32_16x16x32_bf16 v[40:43], v[152:155], v[180:183], v[40:43]
	v_mfma_f32_16x16x32_bf16 v[40:43], v[156:159], v[184:187], v[40:43]
	v_mfma_f32_16x16x32_bf16 v[44:47], v[152:155], v[188:191], v[44:47]
	v_mfma_f32_16x16x32_bf16 v[44:47], v[156:159], v[192:195], v[44:47]
	s_setprio 0
	s_barrier
	ds_read_b128 v[128:131], v168 offset:16384
	ds_read_b128 v[132:135], v171 offset:16384
	ds_read_b128 v[136:139], v168 offset:18432
	ds_read_b128 v[140:143], v171 offset:18432
	ds_read_b128 v[144:147], v168 offset:20480
	ds_read_b128 v[148:151], v171 offset:20480
	ds_read_b128 v[152:155], v168 offset:22528
	ds_read_b128 v[156:159], v171 offset:22528
	s_add_u32 m0, s99, 0x0
	s_nop 0
	global_load_lds_dwordx4 v201, s[58:59]
	s_add_u32 m0, s99, 0x2000
	s_nop 0
	global_load_lds_dwordx4 v202, s[58:59]
	s_barrier
	s_waitcnt lgkmcnt(0)
	s_setprio 1
	v_mfma_f32_16x16x32_bf16 v[80:83], v[128:131], v[160:163], v[80:83]
	v_mfma_f32_16x16x32_bf16 v[80:83], v[132:135], v[164:167], v[80:83]
	v_mfma_f32_16x16x32_bf16 v[84:87], v[128:131], v[172:175], v[84:87]
	v_mfma_f32_16x16x32_bf16 v[84:87], v[132:135], v[176:179], v[84:87]
	v_mfma_f32_16x16x32_bf16 v[88:91], v[136:139], v[160:163], v[88:91]
	v_mfma_f32_16x16x32_bf16 v[88:91], v[140:143], v[164:167], v[88:91]
	v_mfma_f32_16x16x32_bf16 v[92:95], v[136:139], v[172:175], v[92:95]
	v_mfma_f32_16x16x32_bf16 v[92:95], v[140:143], v[176:179], v[92:95]
	v_mfma_f32_16x16x32_bf16 v[64:67], v[144:147], v[160:163], v[64:67]
	v_mfma_f32_16x16x32_bf16 v[64:67], v[148:151], v[164:167], v[64:67]
	v_mfma_f32_16x16x32_bf16 v[68:71], v[144:147], v[172:175], v[68:71]
	v_mfma_f32_16x16x32_bf16 v[68:71], v[148:151], v[176:179], v[68:71]
	v_mfma_f32_16x16x32_bf16 v[72:75], v[152:155], v[160:163], v[72:75]
	v_mfma_f32_16x16x32_bf16 v[72:75], v[156:159], v[164:167], v[72:75]
	v_mfma_f32_16x16x32_bf16 v[76:79], v[152:155], v[172:175], v[76:79]
	v_mfma_f32_16x16x32_bf16 v[76:79], v[156:159], v[176:179], v[76:79]
	s_setprio 0
	s_barrier
	s_add_u32 m0, s99, 0xc000
	s_nop 0
	global_load_lds_dwordx4 v210, s[56:57]
	s_add_u32 m0, s99, 0xe000
	s_nop 0
	global_load_lds_dwordx4 v211, s[56:57]
	s_add_u32 s56, s56, 0x80
	s_addc_u32 s57, s57, 0
	s_waitcnt vmcnt(6)
	s_barrier
	s_setprio 1
	v_mfma_f32_16x16x32_bf16 v[16:19], v[128:131], v[180:183], v[16:19]
	v_mfma_f32_16x16x32_bf16 v[16:19], v[132:135], v[184:187], v[16:19]
	v_mfma_f32_16x16x32_bf16 v[20:23], v[128:131], v[188:191], v[20:23]
	v_mfma_f32_16x16x32_bf16 v[20:23], v[132:135], v[192:195], v[20:23]
	v_mfma_f32_16x16x32_bf16 v[24:27], v[136:139], v[180:183], v[24:27]
	v_mfma_f32_16x16x32_bf16 v[24:27], v[140:143], v[184:187], v[24:27]
	v_mfma_f32_16x16x32_bf16 v[28:31], v[136:139], v[188:191], v[28:31]
	v_mfma_f32_16x16x32_bf16 v[28:31], v[140:143], v[192:195], v[28:31]
	v_mfma_f32_16x16x32_bf16 v[0:3], v[144:147], v[180:183], v[0:3]
	v_mfma_f32_16x16x32_bf16 v[0:3], v[148:151], v[184:187], v[0:3]
	v_mfma_f32_16x16x32_bf16 v[4:7], v[144:147], v[188:191], v[4:7]
	v_mfma_f32_16x16x32_bf16 v[4:7], v[148:151], v[192:195], v[4:7]
	v_mfma_f32_16x16x32_bf16 v[8:11], v[152:155], v[180:183], v[8:11]
	v_mfma_f32_16x16x32_bf16 v[8:11], v[156:159], v[184:187], v[8:11]
	v_mfma_f32_16x16x32_bf16 v[12:15], v[152:155], v[188:191], v[12:15]
	v_mfma_f32_16x16x32_bf16 v[12:15], v[156:159], v[192:195], v[12:15]
	s_setprio 0
	s_barrier
	ds_read_b128 v[160:163], v198 offset:0
	ds_read_b128 v[164:167], v200 offset:0
	ds_read_b128 v[172:175], v198 offset:2048
	ds_read_b128 v[176:179], v200 offset:2048
	ds_read_b128 v[128:131], v170 offset:0
	ds_read_b128 v[132:135], v196 offset:0
	ds_read_b128 v[136:139], v170 offset:2048
	ds_read_b128 v[140:143], v196 offset:2048
	ds_read_b128 v[144:147], v170 offset:4096
	ds_read_b128 v[148:151], v196 offset:4096
	ds_read_b128 v[152:155], v170 offset:6144
	ds_read_b128 v[156:159], v196 offset:6144
	s_add_u32 m0, s99, 0x4000
	s_nop 0
	global_load_lds_dwordx4 v203, s[58:59]
	s_add_u32 m0, s99, 0x6000
	s_nop 0
	global_load_lds_dwordx4 v204, s[58:59]
	s_add_u32 s58, s58, 0x80
	s_addc_u32 s59, s59, 0
	s_waitcnt lgkmcnt(8)
	s_barrier
	s_waitcnt lgkmcnt(0)
	s_setprio 1
	v_mfma_f32_16x16x32_bf16 v[112:115], v[128:131], v[160:163], v[112:115]
	v_mfma_f32_16x16x32_bf16 v[112:115], v[132:135], v[164:167], v[112:115]
	v_mfma_f32_16x16x32_bf16 v[116:119], v[128:131], v[172:175], v[116:119]
	v_mfma_f32_16x16x32_bf16 v[116:119], v[132:135], v[176:179], v[116:119]
	v_mfma_f32_16x16x32_bf16 v[120:123], v[136:139], v[160:163], v[120:123]
	v_mfma_f32_16x16x32_bf16 v[120:123], v[140:143], v[164:167], v[120:123]
	v_mfma_f32_16x16x32_bf16 v[124:127], v[136:139], v[172:175], v[124:127]
	v_mfma_f32_16x16x32_bf16 v[124:127], v[140:143], v[176:179], v[124:127]
	v_mfma_f32_16x16x32_bf16 v[96:99], v[144:147], v[160:163], v[96:99]
	v_mfma_f32_16x16x32_bf16 v[96:99], v[148:151], v[164:167], v[96:99]
	v_mfma_f32_16x16x32_bf16 v[100:103], v[144:147], v[172:175], v[100:103]
	v_mfma_f32_16x16x32_bf16 v[100:103], v[148:151], v[176:179], v[100:103]
	v_mfma_f32_16x16x32_bf16 v[104:107], v[152:155], v[160:163], v[104:107]
	v_mfma_f32_16x16x32_bf16 v[104:107], v[156:159], v[164:167], v[104:107]
	v_mfma_f32_16x16x32_bf16 v[108:111], v[152:155], v[172:175], v[108:111]
	v_mfma_f32_16x16x32_bf16 v[108:111], v[156:159], v[176:179], v[108:111]
	s_setprio 0
	s_barrier
	ds_read_b128 v[180:183], v198 offset:16384
	ds_read_b128 v[184:187], v200 offset:16384
	ds_read_b128 v[188:191], v198 offset:18432
	ds_read_b128 v[192:195], v200 offset:18432
	s_add_u32 m0, s99, 0x18000
	s_nop 0
	global_load_lds_dwordx4 v205, s[56:57]
	s_add_u32 m0, s99, 0x1a000
	s_nop 0
	global_load_lds_dwordx4 v206, s[56:57]
	s_barrier
	s_waitcnt lgkmcnt(0)
	s_setprio 1
	v_mfma_f32_16x16x32_bf16 v[48:51], v[128:131], v[180:183], v[48:51]
	v_mfma_f32_16x16x32_bf16 v[48:51], v[132:135], v[184:187], v[48:51]
	v_mfma_f32_16x16x32_bf16 v[52:55], v[128:131], v[188:191], v[52:55]
	v_mfma_f32_16x16x32_bf16 v[52:55], v[132:135], v[192:195], v[52:55]
	v_mfma_f32_16x16x32_bf16 v[56:59], v[136:139], v[180:183], v[56:59]
	v_mfma_f32_16x16x32_bf16 v[56:59], v[140:143], v[184:187], v[56:59]
	v_mfma_f32_16x16x32_bf16 v[60:63], v[136:139], v[188:191], v[60:63]
	v_mfma_f32_16x16x32_bf16 v[60:63], v[140:143], v[192:195], v[60:63]
	v_mfma_f32_16x16x32_bf16 v[32:35], v[144:147], v[180:183], v[32:35]
	v_mfma_f32_16x16x32_bf16 v[32:35], v[148:151], v[184:187], v[32:35]
	v_mfma_f32_16x16x32_bf16 v[36:39], v[144:147], v[188:191], v[36:39]
	v_mfma_f32_16x16x32_bf16 v[36:39], v[148:151], v[192:195], v[36:39]
	v_mfma_f32_16x16x32_bf16 v[40:43], v[152:155], v[180:183], v[40:43]
	v_mfma_f32_16x16x32_bf16 v[40:43], v[156:159], v[184:187], v[40:43]
	v_mfma_f32_16x16x32_bf16 v[44:47], v[152:155], v[188:191], v[44:47]
	v_mfma_f32_16x16x32_bf16 v[44:47], v[156:159], v[192:195], v[44:47]
	s_setprio 0
	s_barrier
	ds_read_b128 v[128:131], v170 offset:16384
	ds_read_b128 v[132:135], v196 offset:16384
	ds_read_b128 v[136:139], v170 offset:18432
	ds_read_b128 v[140:143], v196 offset:18432
	ds_read_b128 v[144:147], v170 offset:20480
	ds_read_b128 v[148:151], v196 offset:20480
	ds_read_b128 v[152:155], v170 offset:22528
	ds_read_b128 v[156:159], v196 offset:22528
	s_add_u32 m0, s99, 0x10000
	s_nop 0
	global_load_lds_dwordx4 v201, s[58:59]
	s_add_u32 m0, s99, 0x12000
	s_nop 0
	global_load_lds_dwordx4 v202, s[58:59]
	s_barrier
	s_waitcnt lgkmcnt(0)
	s_setprio 1
	v_mfma_f32_16x16x32_bf16 v[80:83], v[128:131], v[160:163], v[80:83]
	v_mfma_f32_16x16x32_bf16 v[80:83], v[132:135], v[164:167], v[80:83]
	v_mfma_f32_16x16x32_bf16 v[84:87], v[128:131], v[172:175], v[84:87]
	v_mfma_f32_16x16x32_bf16 v[84:87], v[132:135], v[176:179], v[84:87]
	v_mfma_f32_16x16x32_bf16 v[88:91], v[136:139], v[160:163], v[88:91]
	v_mfma_f32_16x16x32_bf16 v[88:91], v[140:143], v[164:167], v[88:91]
	v_mfma_f32_16x16x32_bf16 v[92:95], v[136:139], v[172:175], v[92:95]
	v_mfma_f32_16x16x32_bf16 v[92:95], v[140:143], v[176:179], v[92:95]
	v_mfma_f32_16x16x32_bf16 v[64:67], v[144:147], v[160:163], v[64:67]
	v_mfma_f32_16x16x32_bf16 v[64:67], v[148:151], v[164:167], v[64:67]
	v_mfma_f32_16x16x32_bf16 v[68:71], v[144:147], v[172:175], v[68:71]
	v_mfma_f32_16x16x32_bf16 v[68:71], v[148:151], v[176:179], v[68:71]
	v_mfma_f32_16x16x32_bf16 v[72:75], v[152:155], v[160:163], v[72:75]
	v_mfma_f32_16x16x32_bf16 v[72:75], v[156:159], v[164:167], v[72:75]
	v_mfma_f32_16x16x32_bf16 v[76:79], v[152:155], v[172:175], v[76:79]
	v_mfma_f32_16x16x32_bf16 v[76:79], v[156:159], v[176:179], v[76:79]
	s_setprio 0
	s_barrier
	s_add_u32 m0, s99, 0x1c000
	s_nop 0
	global_load_lds_dwordx4 v210, s[56:57]
	s_add_u32 m0, s99, 0x1e000
	s_nop 0
	global_load_lds_dwordx4 v211, s[56:57]
	s_add_u32 s56, s56, 0x80
	s_addc_u32 s57, s57, 0
	s_waitcnt vmcnt(6)
	s_barrier
	s_setprio 1
	v_mfma_f32_16x16x32_bf16 v[16:19], v[128:131], v[180:183], v[16:19]
	v_mfma_f32_16x16x32_bf16 v[16:19], v[132:135], v[184:187], v[16:19]
	v_mfma_f32_16x16x32_bf16 v[20:23], v[128:131], v[188:191], v[20:23]
	v_mfma_f32_16x16x32_bf16 v[20:23], v[132:135], v[192:195], v[20:23]
	v_mfma_f32_16x16x32_bf16 v[24:27], v[136:139], v[180:183], v[24:27]
	v_mfma_f32_16x16x32_bf16 v[24:27], v[140:143], v[184:187], v[24:27]
	v_mfma_f32_16x16x32_bf16 v[28:31], v[136:139], v[188:191], v[28:31]
	v_mfma_f32_16x16x32_bf16 v[28:31], v[140:143], v[192:195], v[28:31]
	v_mfma_f32_16x16x32_bf16 v[0:3], v[144:147], v[180:183], v[0:3]
	v_mfma_f32_16x16x32_bf16 v[0:3], v[148:151], v[184:187], v[0:3]
	v_mfma_f32_16x16x32_bf16 v[4:7], v[144:147], v[188:191], v[4:7]
	v_mfma_f32_16x16x32_bf16 v[4:7], v[148:151], v[192:195], v[4:7]
	v_mfma_f32_16x16x32_bf16 v[8:11], v[152:155], v[180:183], v[8:11]
	v_mfma_f32_16x16x32_bf16 v[8:11], v[156:159], v[184:187], v[8:11]
	v_mfma_f32_16x16x32_bf16 v[12:15], v[152:155], v[188:191], v[12:15]
	v_mfma_f32_16x16x32_bf16 v[12:15], v[156:159], v[192:195], v[12:15]
	s_setprio 0
	s_barrier
	s_sub_u32 s101, s101, 1
	s_cmp_lg_u32 s101, 0
	s_cbranch_scc1 .Lg8_p6g_loop
	ds_read_b128 v[160:163], v197 offset:0
	ds_read_b128 v[164:167], v199 offset:0
	ds_read_b128 v[172:175], v197 offset:2048
	ds_read_b128 v[176:179], v199 offset:2048
	ds_read_b128 v[128:131], v168 offset:0
	ds_read_b128 v[132:135], v171 offset:0
	ds_read_b128 v[136:139], v168 offset:2048
	ds_read_b128 v[140:143], v171 offset:2048
	ds_read_b128 v[144:147], v168 offset:4096
	ds_read_b128 v[148:151], v171 offset:4096
	ds_read_b128 v[152:155], v168 offset:6144
	ds_read_b128 v[156:159], v171 offset:6144
	s_add_u32 m0, s99, 0x14000
	s_nop 0
	global_load_lds_dwordx4 v203, s[58:59]
	s_add_u32 m0, s99, 0x16000
	s_nop 0
	global_load_lds_dwordx4 v204, s[58:59]
	s_add_u32 s58, s58, 0x80
	s_addc_u32 s59, s59, 0
	s_barrier
	s_waitcnt lgkmcnt(0)
	s_setprio 1
	v_mfma_f32_16x16x32_bf16 v[112:115], v[128:131], v[160:163], v[112:115]
	v_mfma_f32_16x16x32_bf16 v[112:115], v[132:135], v[164:167], v[112:115]
	v_mfma_f32_16x16x32_bf16 v[116:119], v[128:131], v[172:175], v[116:119]
	v_mfma_f32_16x16x32_bf16 v[116:119], v[132:135], v[176:179], v[116:119]
	v_mfma_f32_16x16x32_bf16 v[120:123], v[136:139], v[160:163], v[120:123]
	v_mfma_f32_16x16x32_bf16 v[120:123], v[140:143], v[164:167], v[120:123]
	v_mfma_f32_16x16x32_bf16 v[124:127], v[136:139], v[172:175], v[124:127]
	v_mfma_f32_16x16x32_bf16 v[124:127], v[140:143], v[176:179], v[124:127]
	v_mfma_f32_16x16x32_bf16 v[96:99], v[144:147], v[160:163], v[96:99]
	v_mfma_f32_16x16x32_bf16 v[96:99], v[148:151], v[164:167], v[96:99]
	v_mfma_f32_16x16x32_bf16 v[100:103], v[144:147], v[172:175], v[100:103]
	v_mfma_f32_16x16x32_bf16 v[100:103], v[148:151], v[176:179], v[100:103]
	v_mfma_f32_16x16x32_bf16 v[104:107], v[152:155], v[160:163], v[104:107]
	v_mfma_f32_16x16x32_bf16 v[104:107], v[156:159], v[164:167], v[104:107]
	v_mfma_f32_16x16x32_bf16 v[108:111], v[152:155], v[172:175], v[108:111]
	v_mfma_f32_16x16x32_bf16 v[108:111], v[156:159], v[176:179], v[108:111]
	s_setprio 0
	s_barrier
	ds_read_b128 v[180:183], v197 offset:16384
	ds_read_b128 v[184:187], v199 offset:16384
	ds_read_b128 v[188:191], v197 offset:18432
	ds_read_b128 v[192:195], v199 offset:18432
	s_barrier
	s_waitcnt lgkmcnt(0)
	s_setprio 1
	v_mfma_f32_16x16x32_bf16 v[48:51], v[128:131], v[180:183], v[48:51]
	v_mfma_f32_16x16x32_bf16 v[48:51], v[132:135], v[184:187], v[48:51]
	v_mfma_f32_16x16x32_bf16 v[52:55], v[128:131], v[188:191], v[52:55]
	v_mfma_f32_16x16x32_bf16 v[52:55], v[132:135], v[192:195], v[52:55]
	v_mfma_f32_16x16x32_bf16 v[56:59], v[136:139], v[180:183], v[56:59]
	v_mfma_f32_16x16x32_bf16 v[56:59], v[140:143], v[184:187], v[56:59]
	v_mfma_f32_16x16x32_bf16 v[60:63], v[136:139], v[188:191], v[60:63]
	v_mfma_f32_16x16x32_bf16 v[60:63], v[140:143], v[192:195], v[60:63]
	v_mfma_f32_16x16x32_bf16 v[32:35], v[144:147], v[180:183], v[32:35]
	v_mfma_f32_16x16x32_bf16 v[32:35], v[148:151], v[184:187], v[32:35]
	v_mfma_f32_16x16x32_bf16 v[36:39], v[144:147], v[188:191], v[36:39]
	v_mfma_f32_16x16x32_bf16 v[36:39], v[148:151], v[192:195], v[36:39]
	v_mfma_f32_16x16x32_bf16 v[40:43], v[152:155], v[180:183], v[40:43]
	v_mfma_f32_16x16x32_bf16 v[40:43], v[156:159], v[184:187], v[40:43]
	v_mfma_f32_16x16x32_bf16 v[44:47], v[152:155], v[188:191], v[44:47]
	v_mfma_f32_16x16x32_bf16 v[44:47], v[156:159], v[192:195], v[44:47]
	s_setprio 0
	s_barrier
	ds_read_b128 v[128:131], v168 offset:16384
	ds_read_b128 v[132:135], v171 offset:16384
	ds_read_b128 v[136:139], v168 offset:18432
	ds_read_b128 v[140:143], v171 offset:18432
	ds_read_b128 v[144:147], v168 offset:20480
	ds_read_b128 v[148:151], v171 offset:20480
	ds_read_b128 v[152:155], v168 offset:22528
	ds_read_b128 v[156:159], v171 offset:22528
	s_waitcnt vmcnt(4)
	s_barrier
	s_waitcnt lgkmcnt(0)
	s_setprio 1
	v_mfma_f32_16x16x32_bf16 v[80:83], v[128:131], v[160:163], v[80:83]
	v_mfma_f32_16x16x32_bf16 v[80:83], v[132:135], v[164:167], v[80:83]
	v_mfma_f32_16x16x32_bf16 v[84:87], v[128:131], v[172:175], v[84:87]
	v_mfma_f32_16x16x32_bf16 v[84:87], v[132:135], v[176:179], v[84:87]
	v_mfma_f32_16x16x32_bf16 v[88:91], v[136:139], v[160:163], v[88:91]
	v_mfma_f32_16x16x32_bf16 v[88:91], v[140:143], v[164:167], v[88:91]
	v_mfma_f32_16x16x32_bf16 v[92:95], v[136:139], v[172:175], v[92:95]
	v_mfma_f32_16x16x32_bf16 v[92:95], v[140:143], v[176:179], v[92:95]
	v_mfma_f32_16x16x32_bf16 v[64:67], v[144:147], v[160:163], v[64:67]
	v_mfma_f32_16x16x32_bf16 v[64:67], v[148:151], v[164:167], v[64:67]
	v_mfma_f32_16x16x32_bf16 v[68:71], v[144:147], v[172:175], v[68:71]
	v_mfma_f32_16x16x32_bf16 v[68:71], v[148:151], v[176:179], v[68:71]
	v_mfma_f32_16x16x32_bf16 v[72:75], v[152:155], v[160:163], v[72:75]
	v_mfma_f32_16x16x32_bf16 v[72:75], v[156:159], v[164:167], v[72:75]
	v_mfma_f32_16x16x32_bf16 v[76:79], v[152:155], v[172:175], v[76:79]
	v_mfma_f32_16x16x32_bf16 v[76:79], v[156:159], v[176:179], v[76:79]
	s_setprio 0
	s_setprio 1
	v_mfma_f32_16x16x32_bf16 v[16:19], v[128:131], v[180:183], v[16:19]
	v_mfma_f32_16x16x32_bf16 v[16:19], v[132:135], v[184:187], v[16:19]
	v_mfma_f32_16x16x32_bf16 v[20:23], v[128:131], v[188:191], v[20:23]
	v_mfma_f32_16x16x32_bf16 v[20:23], v[132:135], v[192:195], v[20:23]
	v_mfma_f32_16x16x32_bf16 v[24:27], v[136:139], v[180:183], v[24:27]
	v_mfma_f32_16x16x32_bf16 v[24:27], v[140:143], v[184:187], v[24:27]
	v_mfma_f32_16x16x32_bf16 v[28:31], v[136:139], v[188:191], v[28:31]
	v_mfma_f32_16x16x32_bf16 v[28:31], v[140:143], v[192:195], v[28:31]
	v_mfma_f32_16x16x32_bf16 v[0:3], v[144:147], v[180:183], v[0:3]
	v_mfma_f32_16x16x32_bf16 v[0:3], v[148:151], v[184:187], v[0:3]
	v_mfma_f32_16x16x32_bf16 v[4:7], v[144:147], v[188:191], v[4:7]
	v_mfma_f32_16x16x32_bf16 v[4:7], v[148:151], v[192:195], v[4:7]
	v_mfma_f32_16x16x32_bf16 v[8:11], v[152:155], v[180:183], v[8:11]
	v_mfma_f32_16x16x32_bf16 v[8:11], v[156:159], v[184:187], v[8:11]
	v_mfma_f32_16x16x32_bf16 v[12:15], v[152:155], v[188:191], v[12:15]
	v_mfma_f32_16x16x32_bf16 v[12:15], v[156:159], v[192:195], v[12:15]
	s_setprio 0
	s_barrier
	ds_read_b128 v[160:163], v198 offset:0
	ds_read_b128 v[164:167], v200 offset:0
	ds_read_b128 v[172:175], v198 offset:2048
	ds_read_b128 v[176:179], v200 offset:2048
	ds_read_b128 v[128:131], v170 offset:0
	ds_read_b128 v[132:135], v196 offset:0
	ds_read_b128 v[136:139], v170 offset:2048
	ds_read_b128 v[140:143], v196 offset:2048
	ds_read_b128 v[144:147], v170 offset:4096
	ds_read_b128 v[148:151], v196 offset:4096
	ds_read_b128 v[152:155], v170 offset:6144
	ds_read_b128 v[156:159], v196 offset:6144
	s_waitcnt vmcnt(2)
	s_barrier
	s_waitcnt lgkmcnt(0)
	s_setprio 1
	v_mfma_f32_16x16x32_bf16 v[112:115], v[128:131], v[160:163], v[112:115]
	v_mfma_f32_16x16x32_bf16 v[112:115], v[132:135], v[164:167], v[112:115]
	v_mfma_f32_16x16x32_bf16 v[116:119], v[128:131], v[172:175], v[116:119]
	v_mfma_f32_16x16x32_bf16 v[116:119], v[132:135], v[176:179], v[116:119]
	v_mfma_f32_16x16x32_bf16 v[120:123], v[136:139], v[160:163], v[120:123]
	v_mfma_f32_16x16x32_bf16 v[120:123], v[140:143], v[164:167], v[120:123]
	v_mfma_f32_16x16x32_bf16 v[124:127], v[136:139], v[172:175], v[124:127]
	v_mfma_f32_16x16x32_bf16 v[124:127], v[140:143], v[176:179], v[124:127]
	v_mfma_f32_16x16x32_bf16 v[96:99], v[144:147], v[160:163], v[96:99]
	v_mfma_f32_16x16x32_bf16 v[96:99], v[148:151], v[164:167], v[96:99]
	v_mfma_f32_16x16x32_bf16 v[100:103], v[144:147], v[172:175], v[100:103]
	v_mfma_f32_16x16x32_bf16 v[100:103], v[148:151], v[176:179], v[100:103]
	v_mfma_f32_16x16x32_bf16 v[104:107], v[152:155], v[160:163], v[104:107]
	v_mfma_f32_16x16x32_bf16 v[104:107], v[156:159], v[164:167], v[104:107]
	v_mfma_f32_16x16x32_bf16 v[108:111], v[152:155], v[172:175], v[108:111]
	v_mfma_f32_16x16x32_bf16 v[108:111], v[156:159], v[176:179], v[108:111]
	s_setprio 0
	s_barrier
	ds_read_b128 v[180:183], v198 offset:16384
	ds_read_b128 v[184:187], v200 offset:16384
	ds_read_b128 v[188:191], v198 offset:18432
	ds_read_b128 v[192:195], v200 offset:18432
	s_waitcnt vmcnt(0)
	s_barrier
	s_waitcnt lgkmcnt(0)
	s_setprio 1
	v_mfma_f32_16x16x32_bf16 v[48:51], v[128:131], v[180:183], v[48:51]
	v_mfma_f32_16x16x32_bf16 v[48:51], v[132:135], v[184:187], v[48:51]
	v_mfma_f32_16x16x32_bf16 v[52:55], v[128:131], v[188:191], v[52:55]
	v_mfma_f32_16x16x32_bf16 v[52:55], v[132:135], v[192:195], v[52:55]
	v_mfma_f32_16x16x32_bf16 v[56:59], v[136:139], v[180:183], v[56:59]
	v_mfma_f32_16x16x32_bf16 v[56:59], v[140:143], v[184:187], v[56:59]
	v_mfma_f32_16x16x32_bf16 v[60:63], v[136:139], v[188:191], v[60:63]
	v_mfma_f32_16x16x32_bf16 v[60:63], v[140:143], v[192:195], v[60:63]
	v_mfma_f32_16x16x32_bf16 v[32:35], v[144:147], v[180:183], v[32:35]
	v_mfma_f32_16x16x32_bf16 v[32:35], v[148:151], v[184:187], v[32:35]
	v_mfma_f32_16x16x32_bf16 v[36:39], v[144:147], v[188:191], v[36:39]
	v_mfma_f32_16x16x32_bf16 v[36:39], v[148:151], v[192:195], v[36:39]
	v_mfma_f32_16x16x32_bf16 v[40:43], v[152:155], v[180:183], v[40:43]
	v_mfma_f32_16x16x32_bf16 v[40:43], v[156:159], v[184:187], v[40:43]
	v_mfma_f32_16x16x32_bf16 v[44:47], v[152:155], v[188:191], v[44:47]
	v_mfma_f32_16x16x32_bf16 v[44:47], v[156:159], v[192:195], v[44:47]
	s_setprio 0
	s_barrier
	ds_read_b128 v[128:131], v170 offset:16384
	ds_read_b128 v[132:135], v196 offset:16384
	ds_read_b128 v[136:139], v170 offset:18432
	ds_read_b128 v[140:143], v196 offset:18432
	ds_read_b128 v[144:147], v170 offset:20480
	ds_read_b128 v[148:151], v196 offset:20480
	ds_read_b128 v[152:155], v170 offset:22528
	ds_read_b128 v[156:159], v196 offset:22528
	s_barrier
	s_waitcnt lgkmcnt(0)
	s_setprio 1
	v_mfma_f32_16x16x32_bf16 v[80:83], v[128:131], v[160:163], v[80:83]
	v_mfma_f32_16x16x32_bf16 v[80:83], v[132:135], v[164:167], v[80:83]
	v_mfma_f32_16x16x32_bf16 v[84:87], v[128:131], v[172:175], v[84:87]
	v_mfma_f32_16x16x32_bf16 v[84:87], v[132:135], v[176:179], v[84:87]
	v_mfma_f32_16x16x32_bf16 v[88:91], v[136:139], v[160:163], v[88:91]
	v_mfma_f32_16x16x32_bf16 v[88:91], v[140:143], v[164:167], v[88:91]
	v_mfma_f32_16x16x32_bf16 v[92:95], v[136:139], v[172:175], v[92:95]
	v_mfma_f32_16x16x32_bf16 v[92:95], v[140:143], v[176:179], v[92:95]
	v_mfma_f32_16x16x32_bf16 v[64:67], v[144:147], v[160:163], v[64:67]
	v_mfma_f32_16x16x32_bf16 v[64:67], v[148:151], v[164:167], v[64:67]
	v_mfma_f32_16x16x32_bf16 v[68:71], v[144:147], v[172:175], v[68:71]
	v_mfma_f32_16x16x32_bf16 v[68:71], v[148:151], v[176:179], v[68:71]
	v_mfma_f32_16x16x32_bf16 v[72:75], v[152:155], v[160:163], v[72:75]
	v_mfma_f32_16x16x32_bf16 v[72:75], v[156:159], v[164:167], v[72:75]
	v_mfma_f32_16x16x32_bf16 v[76:79], v[152:155], v[172:175], v[76:79]
	v_mfma_f32_16x16x32_bf16 v[76:79], v[156:159], v[176:179], v[76:79]
	s_setprio 0
	s_setprio 1
	v_mfma_f32_16x16x32_bf16 v[16:19], v[128:131], v[180:183], v[16:19]
	v_mfma_f32_16x16x32_bf16 v[16:19], v[132:135], v[184:187], v[16:19]
	v_mfma_f32_16x16x32_bf16 v[20:23], v[128:131], v[188:191], v[20:23]
	v_mfma_f32_16x16x32_bf16 v[20:23], v[132:135], v[192:195], v[20:23]
	v_mfma_f32_16x16x32_bf16 v[24:27], v[136:139], v[180:183], v[24:27]
	v_mfma_f32_16x16x32_bf16 v[24:27], v[140:143], v[184:187], v[24:27]
	v_mfma_f32_16x16x32_bf16 v[28:31], v[136:139], v[188:191], v[28:31]
	v_mfma_f32_16x16x32_bf16 v[28:31], v[140:143], v[192:195], v[28:31]
	v_mfma_f32_16x16x32_bf16 v[0:3], v[144:147], v[180:183], v[0:3]
	v_mfma_f32_16x16x32_bf16 v[0:3], v[148:151], v[184:187], v[0:3]
	v_mfma_f32_16x16x32_bf16 v[4:7], v[144:147], v[188:191], v[4:7]
	v_mfma_f32_16x16x32_bf16 v[4:7], v[148:151], v[192:195], v[4:7]
	v_mfma_f32_16x16x32_bf16 v[8:11], v[152:155], v[180:183], v[8:11]
	v_mfma_f32_16x16x32_bf16 v[8:11], v[156:159], v[184:187], v[8:11]
	v_mfma_f32_16x16x32_bf16 v[12:15], v[152:155], v[188:191], v[12:15]
	v_mfma_f32_16x16x32_bf16 v[12:15], v[156:159], v[192:195], v[12:15]
	s_setprio 0
	s_barrier
	s_cmp_lg_u32 s100, 0
	s_cbranch_scc1 .Lg8_p6g_eg1
	s_barrier
.Lg8_p6g_eg1:
	s_nop 7
	s_nop 7
	v_permlane16_swap_b32_e32 v112, v116
	v_permlane16_swap_b32_e32 v113, v117
	v_permlane16_swap_b32_e32 v114, v118
	v_permlane16_swap_b32_e32 v115, v119
	v_permlane16_swap_b32_e32 v120, v124
	v_permlane16_swap_b32_e32 v121, v125
	v_permlane16_swap_b32_e32 v122, v126
	v_permlane16_swap_b32_e32 v123, v127
	v_permlane16_swap_b32_e32 v96, v100
	v_permlane16_swap_b32_e32 v97, v101
	v_permlane16_swap_b32_e32 v98, v102
	v_permlane16_swap_b32_e32 v99, v103
	v_permlane16_swap_b32_e32 v104, v108
	v_permlane16_swap_b32_e32 v105, v109
	v_permlane16_swap_b32_e32 v106, v110
	v_permlane16_swap_b32_e32 v107, v111
	v_permlane16_swap_b32_e32 v80, v84
	v_permlane16_swap_b32_e32 v81, v85
	v_permlane16_swap_b32_e32 v82, v86
	v_permlane16_swap_b32_e32 v83, v87
	v_permlane16_swap_b32_e32 v88, v92
	v_permlane16_swap_b32_e32 v89, v93
	v_permlane16_swap_b32_e32 v90, v94
	v_permlane16_swap_b32_e32 v91, v95
	v_permlane16_swap_b32_e32 v64, v68
	v_permlane16_swap_b32_e32 v65, v69
	v_permlane16_swap_b32_e32 v66, v70
	v_permlane16_swap_b32_e32 v67, v71
	v_permlane16_swap_b32_e32 v72, v76
	v_permlane16_swap_b32_e32 v73, v77
	v_permlane16_swap_b32_e32 v74, v78
	v_permlane16_swap_b32_e32 v75, v79
	v_permlane16_swap_b32_e32 v48, v52
	v_permlane16_swap_b32_e32 v49, v53
	v_permlane16_swap_b32_e32 v50, v54
	v_permlane16_swap_b32_e32 v51, v55
	v_permlane16_swap_b32_e32 v56, v60
	v_permlane16_swap_b32_e32 v57, v61
	v_permlane16_swap_b32_e32 v58, v62
	v_permlane16_swap_b32_e32 v59, v63
	v_permlane16_swap_b32_e32 v32, v36
	v_permlane16_swap_b32_e32 v33, v37
	v_permlane16_swap_b32_e32 v34, v38
	v_permlane16_swap_b32_e32 v35, v39
	v_permlane16_swap_b32_e32 v40, v44
	v_permlane16_swap_b32_e32 v41, v45
	v_permlane16_swap_b32_e32 v42, v46
	v_permlane16_swap_b32_e32 v43, v47
	v_permlane16_swap_b32_e32 v16, v20
	v_permlane16_swap_b32_e32 v17, v21
	v_permlane16_swap_b32_e32 v18, v22
	v_permlane16_swap_b32_e32 v19, v23
	v_permlane16_swap_b32_e32 v24, v28
	v_permlane16_swap_b32_e32 v25, v29
	v_permlane16_swap_b32_e32 v26, v30
	v_permlane16_swap_b32_e32 v27, v31
	v_permlane16_swap_b32_e32 v0, v4
	v_permlane16_swap_b32_e32 v1, v5
	v_permlane16_swap_b32_e32 v2, v6
	v_permlane16_swap_b32_e32 v3, v7
	v_permlane16_swap_b32_e32 v8, v12
	v_permlane16_swap_b32_e32 v9, v13
	v_permlane16_swap_b32_e32 v10, v14
	v_permlane16_swap_b32_e32 v11, v15
	s_nop 1
	s_waitcnt vmcnt(1)
	v_mov_b32_e32 v128, v208
	v_mul_f32_e32 v131, 0xbfb8aa3b, v115
	v_and_b32_e32 v129, 31, v128
	v_lshrrev_b32_e32 v130, 1, v128
	s_waitcnt vmcnt(0)
	v_and_or_b32 v132, v130, s71, v129
	v_mul_f32_e32 v129, 0xbfb8aa3b, v112
	v_mul_f32_e32 v130, 0xbfb8aa3b, v113
	v_exp_f32_e32 v129, v129
	v_exp_f32_e32 v130, v130
	v_lshlrev_b32_e32 v133, 1, v128
	v_lshrrev_b32_e32 v128, 3, v128
	v_and_b32_e32 v134, 4, v128
	v_add_f32_e32 v128, 1.0, v129
	v_add_f32_e32 v129, 1.0, v130
	v_mul_f32_e32 v130, 0xbfb8aa3b, v114
	v_exp_f32_e32 v130, v130
	v_exp_f32_e32 v131, v131
	v_rcp_f32_e32 v128, v128
	v_rcp_f32_e32 v129, v129
	v_add_f32_e32 v130, 1.0, v130
	v_add_f32_e32 v131, 1.0, v131
	v_rcp_f32_e32 v130, v130
	v_rcp_f32_e32 v131, v131
	v_pk_mul_f32 v[112:113], v[112:113], v[128:129]
	v_mul_f32_e32 v128, 0xbfb8aa3b, v116
	v_exp_f32_e32 v129, v128
	v_mul_f32_e32 v128, 0xbfb8aa3b, v117
	v_pk_mul_f32 v[114:115], v[114:115], v[130:131]
	v_exp_f32_e32 v131, v128
	v_cvt_pk_bf16_f32 v128, v112, v113
	v_mul_f32_e32 v113, 0xbfb8aa3b, v118
	v_add_f32_e32 v112, 1.0, v129
	v_exp_f32_e32 v113, v113
	v_mul_f32_e32 v129, 0xbfb8aa3b, v119
	v_exp_f32_e32 v129, v129
	v_rcp_f32_e32 v130, v112
	v_add_f32_e32 v112, 1.0, v131
	v_rcp_f32_e32 v131, v112
	v_add_f32_e32 v112, 1.0, v113
	v_mul_lo_u32 v135, v132, s80
	v_rcp_f32_e32 v132, v112
	v_add_f32_e32 v112, 1.0, v129
	v_and_or_b32 v134, v133, s72, v134
	v_rcp_f32_e32 v133, v112
	v_cvt_pk_bf16_f32 v129, v114, v115
	v_pk_mul_f32 v[114:115], v[116:117], v[130:131]
	v_mul_f32_e32 v113, 0xbfb8aa3b, v120
	v_pk_mul_f32 v[116:117], v[118:119], v[132:133]
	v_cvt_pk_bf16_f32 v114, v114, v115
	v_cvt_pk_bf16_f32 v115, v116, v117
	v_exp_f32_e32 v113, v113
	v_mul_f32_e32 v116, 0xbfb8aa3b, v121
	v_exp_f32_e32 v116, v116
	v_lshl_add_u32 v112, v134, 1, v135
	v_add_f32_e32 v113, 1.0, v113
	ds_write2_b64 v112, v[128:129], v[114:115] offset1:2
	v_rcp_f32_e32 v114, v113
	v_add_f32_e32 v113, 1.0, v116
	v_rcp_f32_e32 v115, v113
	v_mul_f32_e32 v113, 0xbfb8aa3b, v122
	v_exp_f32_e32 v113, v113
	v_mul_f32_e32 v116, 0xbfb8aa3b, v123
	v_exp_f32_e32 v117, v116
	v_mul_f32_e32 v118, 0xbfb8aa3b, v125
	v_add_f32_e32 v113, 1.0, v113
	v_rcp_f32_e32 v116, v113
	v_add_f32_e32 v113, 1.0, v117
	v_rcp_f32_e32 v117, v113
	v_mul_f32_e32 v113, 0xbfb8aa3b, v124
	v_exp_f32_e32 v113, v113
	v_exp_f32_e32 v119, v118
	v_pk_mul_f32 v[114:115], v[120:121], v[114:115]
	v_pk_mul_f32 v[116:117], v[122:123], v[116:117]
	v_add_f32_e32 v113, 1.0, v113
	v_rcp_f32_e32 v118, v113
	v_add_f32_e32 v113, 1.0, v119
	v_mul_f32_e32 v119, 0xbfb8aa3b, v126
	v_exp_f32_e32 v120, v119
	v_mul_f32_e32 v119, 0xbfb8aa3b, v127
	v_exp_f32_e32 v121, v119
	v_rcp_f32_e32 v119, v113
	v_add_f32_e32 v113, 1.0, v120
	v_rcp_f32_e32 v120, v113
	v_add_f32_e32 v113, 1.0, v121
	v_rcp_f32_e32 v121, v113
	v_cvt_pk_bf16_f32 v114, v114, v115
	v_cvt_pk_bf16_f32 v115, v116, v117
	v_pk_mul_f32 v[116:117], v[124:125], v[118:119]
	v_pk_mul_f32 v[118:119], v[126:127], v[120:121]
	v_mul_f32_e32 v113, 0xbfb8aa3b, v96
	v_cvt_pk_bf16_f32 v116, v116, v117
	v_cvt_pk_bf16_f32 v117, v118, v119
	v_exp_f32_e32 v113, v113
	v_mul_f32_e32 v118, 0xbfb8aa3b, v97
	v_exp_f32_e32 v118, v118
	ds_write2_b64 v112, v[114:115], v[116:117] offset0:4 offset1:6
	v_add_f32_e32 v113, 1.0, v113
	v_rcp_f32_e32 v114, v113
	v_add_f32_e32 v113, 1.0, v118
	v_rcp_f32_e32 v115, v113
	v_mul_f32_e32 v113, 0xbfb8aa3b, v98
	v_exp_f32_e32 v113, v113
	v_mul_f32_e32 v116, 0xbfb8aa3b, v99
	v_exp_f32_e32 v116, v116
	v_pk_mul_f32 v[96:97], v[96:97], v[114:115]
	v_add_f32_e32 v113, 1.0, v113
	v_rcp_f32_e32 v114, v113
	v_add_f32_e32 v113, 1.0, v116
	v_rcp_f32_e32 v115, v113
	v_mul_f32_e32 v113, 0xbfb8aa3b, v100
	v_exp_f32_e32 v113, v113
	v_mul_f32_e32 v116, 0xbfb8aa3b, v101
	v_exp_f32_e32 v116, v116
	v_pk_mul_f32 v[98:99], v[98:99], v[114:115]
	v_add_f32_e32 v113, 1.0, v113
	v_mul_f32_e32 v115, 0xbfb8aa3b, v102
	v_rcp_f32_e32 v114, v113
	v_add_f32_e32 v113, 1.0, v116
	v_exp_f32_e32 v116, v115
	v_mul_f32_e32 v115, 0xbfb8aa3b, v103
	v_exp_f32_e32 v117, v115
	v_rcp_f32_e32 v115, v113
	v_add_f32_e32 v113, 1.0, v116
	v_rcp_f32_e32 v116, v113
	v_add_f32_e32 v113, 1.0, v117
	v_rcp_f32_e32 v117, v113
	v_cvt_pk_bf16_f32 v96, v96, v97
	v_cvt_pk_bf16_f32 v97, v98, v99
	v_pk_mul_f32 v[98:99], v[100:101], v[114:115]
	v_pk_mul_f32 v[100:101], v[102:103], v[116:117]
	v_cvt_pk_bf16_f32 v98, v98, v99
	v_cvt_pk_bf16_f32 v99, v100, v101
	v_mul_f32_e32 v100, 0xbfb8aa3b, v104
	v_mul_f32_e32 v101, 0xbfb8aa3b, v105
	v_exp_f32_e32 v100, v100
	v_exp_f32_e32 v101, v101
	ds_write2_b64 v112, v[96:97], v[98:99] offset0:8 offset1:10
	v_mul_f32_e32 v98, 0xbfb8aa3b, v106
	v_mul_f32_e32 v99, 0xbfb8aa3b, v107
	v_add_f32_e32 v96, 1.0, v100
	v_add_f32_e32 v97, 1.0, v101
	v_exp_f32_e32 v98, v98
	v_exp_f32_e32 v99, v99
	v_mul_f32_e32 v100, 0xbfb8aa3b, v108
	v_mul_f32_e32 v101, 0xbfb8aa3b, v109
	v_mul_f32_e32 v102, 0xbfb8aa3b, v110
	v_mul_f32_e32 v103, 0xbfb8aa3b, v111
	v_exp_f32_e32 v100, v100
	v_exp_f32_e32 v101, v101
	v_exp_f32_e32 v102, v102
	v_exp_f32_e32 v103, v103
	v_add_f32_e32 v98, 1.0, v98
	v_add_f32_e32 v99, 1.0, v99
	v_rcp_f32_e32 v96, v96
	v_rcp_f32_e32 v97, v97
	v_rcp_f32_e32 v98, v98
	v_rcp_f32_e32 v99, v99
	v_add_f32_e32 v100, 1.0, v100
	v_add_f32_e32 v101, 1.0, v101
	v_add_f32_e32 v102, 1.0, v102
	v_add_f32_e32 v103, 1.0, v103
	v_rcp_f32_e32 v100, v100
	v_rcp_f32_e32 v101, v101
	v_rcp_f32_e32 v102, v102
	v_rcp_f32_e32 v103, v103
	v_pk_mul_f32 v[96:97], v[104:105], v[96:97]
	v_pk_mul_f32 v[98:99], v[106:107], v[98:99]
	v_cvt_pk_bf16_f32 v96, v96, v97
	v_cvt_pk_bf16_f32 v97, v98, v99
	v_pk_mul_f32 v[98:99], v[108:109], v[100:101]
	v_pk_mul_f32 v[100:101], v[110:111], v[102:103]
	v_cvt_pk_bf16_f32 v98, v98, v99
	v_cvt_pk_bf16_f32 v99, v100, v101
	v_mul_f32_e32 v100, 0xbfb8aa3b, v80
	v_mul_f32_e32 v101, 0xbfb8aa3b, v81
	v_exp_f32_e32 v100, v100
	v_exp_f32_e32 v101, v101
	ds_write2_b64 v112, v[96:97], v[98:99] offset0:12 offset1:14
	v_mul_f32_e32 v98, 0xbfb8aa3b, v82
	v_add_f32_e32 v96, 1.0, v100
	v_add_f32_e32 v97, 1.0, v101
	v_mul_f32_e32 v99, 0xbfb8aa3b, v83
	v_rcp_f32_e32 v96, v96
	v_rcp_f32_e32 v97, v97
	v_exp_f32_e32 v98, v98
	v_exp_f32_e32 v99, v99
	s_lshl_b64 s[2:3], s[2:3], 20
	v_pk_mul_f32 v[80:81], v[80:81], v[96:97]
	v_add_f32_e32 v96, 1.0, v98
	v_add_f32_e32 v97, 1.0, v99
	v_mul_f32_e32 v98, 0xbfb8aa3b, v84
	v_mul_f32_e32 v99, 0xbfb8aa3b, v85
	v_rcp_f32_e32 v96, v96
	v_rcp_f32_e32 v97, v97
	v_exp_f32_e32 v98, v98
	v_exp_f32_e32 v99, v99
	v_cvt_pk_bf16_f32 v80, v80, v81
	v_pk_mul_f32 v[82:83], v[82:83], v[96:97]
	v_add_f32_e32 v96, 1.0, v98
	v_add_f32_e32 v97, 1.0, v99
	v_mul_f32_e32 v98, 0xbfb8aa3b, v86
	v_mul_f32_e32 v99, 0xbfb8aa3b, v87
	v_exp_f32_e32 v98, v98
	v_exp_f32_e32 v99, v99
	v_rcp_f32_e32 v96, v96
	v_rcp_f32_e32 v97, v97
	v_add_f32_e32 v98, 1.0, v98
	v_add_f32_e32 v99, 1.0, v99
	v_rcp_f32_e32 v98, v98
	v_rcp_f32_e32 v99, v99
	v_cvt_pk_bf16_f32 v81, v82, v83
	v_pk_mul_f32 v[82:83], v[84:85], v[96:97]
	s_add_u32 s2, s61, s2
	v_pk_mul_f32 v[84:85], v[86:87], v[98:99]
	v_cvt_pk_bf16_f32 v82, v82, v83
	v_cvt_pk_bf16_f32 v83, v84, v85
	v_mul_f32_e32 v84, 0xbfb8aa3b, v88
	v_mul_f32_e32 v85, 0xbfb8aa3b, v89
	v_exp_f32_e32 v84, v84
	v_exp_f32_e32 v85, v85
	ds_write2_b64 v112, v[80:81], v[82:83] offset0:16 offset1:18
	v_mul_f32_e32 v82, 0xbfb8aa3b, v90
	v_mul_f32_e32 v83, 0xbfb8aa3b, v91
	v_add_f32_e32 v80, 1.0, v84
	v_add_f32_e32 v81, 1.0, v85
	v_exp_f32_e32 v82, v82
	v_exp_f32_e32 v83, v83
	v_mul_f32_e32 v84, 0xbfb8aa3b, v92
	v_mul_f32_e32 v85, 0xbfb8aa3b, v93
	v_mul_f32_e32 v86, 0xbfb8aa3b, v94
	v_mul_f32_e32 v87, 0xbfb8aa3b, v95
	v_exp_f32_e32 v84, v84
	v_exp_f32_e32 v85, v85
	v_exp_f32_e32 v86, v86
	v_exp_f32_e32 v87, v87
	v_add_f32_e32 v82, 1.0, v82
	v_add_f32_e32 v83, 1.0, v83
	v_rcp_f32_e32 v80, v80
	v_rcp_f32_e32 v81, v81
	v_rcp_f32_e32 v82, v82
	v_rcp_f32_e32 v83, v83
	v_add_f32_e32 v84, 1.0, v84
	v_add_f32_e32 v85, 1.0, v85
	v_add_f32_e32 v86, 1.0, v86
	v_add_f32_e32 v87, 1.0, v87
	v_rcp_f32_e32 v84, v84
	v_rcp_f32_e32 v85, v85
	v_rcp_f32_e32 v86, v86
	v_rcp_f32_e32 v87, v87
	v_pk_mul_f32 v[80:81], v[88:89], v[80:81]
	v_pk_mul_f32 v[82:83], v[90:91], v[82:83]
	v_cvt_pk_bf16_f32 v80, v80, v81
	v_cvt_pk_bf16_f32 v81, v82, v83
	v_pk_mul_f32 v[82:83], v[92:93], v[84:85]
	v_pk_mul_f32 v[84:85], v[94:95], v[86:87]
	v_cvt_pk_bf16_f32 v82, v82, v83
	v_cvt_pk_bf16_f32 v83, v84, v85
	v_mul_f32_e32 v84, 0xbfb8aa3b, v64
	v_mul_f32_e32 v85, 0xbfb8aa3b, v65
	v_exp_f32_e32 v84, v84
	v_exp_f32_e32 v85, v85
	ds_write2_b64 v112, v[80:81], v[82:83] offset0:20 offset1:22
	v_mul_f32_e32 v82, 0xbfb8aa3b, v66
	v_add_f32_e32 v80, 1.0, v84
	v_add_f32_e32 v81, 1.0, v85
	v_mul_f32_e32 v83, 0xbfb8aa3b, v67
	v_rcp_f32_e32 v80, v80
	v_rcp_f32_e32 v81, v81
	v_exp_f32_e32 v82, v82
	v_exp_f32_e32 v83, v83
	s_addc_u32 s3, s62, s3
	v_pk_mul_f32 v[64:65], v[64:65], v[80:81]
	v_add_f32_e32 v80, 1.0, v82
	v_add_f32_e32 v81, 1.0, v83
	v_mul_f32_e32 v82, 0xbfb8aa3b, v68
	v_mul_f32_e32 v83, 0xbfb8aa3b, v69
	v_rcp_f32_e32 v80, v80
	v_rcp_f32_e32 v81, v81
	v_exp_f32_e32 v82, v82
	v_exp_f32_e32 v83, v83
	v_cvt_pk_bf16_f32 v64, v64, v65
	v_pk_mul_f32 v[66:67], v[66:67], v[80:81]
	v_add_f32_e32 v80, 1.0, v82
	v_add_f32_e32 v81, 1.0, v83
	v_mul_f32_e32 v82, 0xbfb8aa3b, v70
	v_mul_f32_e32 v83, 0xbfb8aa3b, v71
	v_exp_f32_e32 v82, v82
	v_exp_f32_e32 v83, v83
	v_rcp_f32_e32 v80, v80
	v_rcp_f32_e32 v81, v81
	v_add_f32_e32 v82, 1.0, v82
	v_add_f32_e32 v83, 1.0, v83
	v_rcp_f32_e32 v82, v82
	v_rcp_f32_e32 v83, v83
	v_cvt_pk_bf16_f32 v65, v66, v67
	v_pk_mul_f32 v[66:67], v[68:69], v[80:81]
	s_lshl_b32 s6, s6, 1
	v_pk_mul_f32 v[68:69], v[70:71], v[82:83]
	v_cvt_pk_bf16_f32 v66, v66, v67
	v_cvt_pk_bf16_f32 v67, v68, v69
	v_mul_f32_e32 v68, 0xbfb8aa3b, v72
	v_mul_f32_e32 v69, 0xbfb8aa3b, v73
	v_exp_f32_e32 v68, v68
	v_exp_f32_e32 v69, v69
	ds_write2_b64 v112, v[64:65], v[66:67] offset0:24 offset1:26
	v_mul_f32_e32 v66, 0xbfb8aa3b, v74
	v_mul_f32_e32 v67, 0xbfb8aa3b, v75
	v_add_f32_e32 v64, 1.0, v68
	v_add_f32_e32 v65, 1.0, v69
	v_exp_f32_e32 v66, v66
	v_exp_f32_e32 v67, v67
	v_mul_f32_e32 v68, 0xbfb8aa3b, v76
	v_mul_f32_e32 v69, 0xbfb8aa3b, v77
	v_mul_f32_e32 v70, 0xbfb8aa3b, v78
	v_mul_f32_e32 v71, 0xbfb8aa3b, v79
	v_exp_f32_e32 v68, v68
	v_exp_f32_e32 v69, v69
	v_exp_f32_e32 v70, v70
	v_exp_f32_e32 v71, v71
	v_add_f32_e32 v66, 1.0, v66
	v_add_f32_e32 v67, 1.0, v67
	v_rcp_f32_e32 v64, v64
	v_rcp_f32_e32 v65, v65
	v_rcp_f32_e32 v66, v66
	v_rcp_f32_e32 v67, v67
	v_add_f32_e32 v68, 1.0, v68
	v_add_f32_e32 v69, 1.0, v69
	v_add_f32_e32 v70, 1.0, v70
	v_add_f32_e32 v71, 1.0, v71
	v_rcp_f32_e32 v68, v68
	v_rcp_f32_e32 v69, v69
	v_rcp_f32_e32 v70, v70
	v_rcp_f32_e32 v71, v71
	v_pk_mul_f32 v[64:65], v[72:73], v[64:65]
	v_pk_mul_f32 v[66:67], v[74:75], v[66:67]
	v_cvt_pk_bf16_f32 v64, v64, v65
	v_cvt_pk_bf16_f32 v65, v66, v67
	v_pk_mul_f32 v[66:67], v[76:77], v[68:69]
	v_pk_mul_f32 v[68:69], v[78:79], v[70:71]
	v_cvt_pk_bf16_f32 v66, v66, v67
	v_cvt_pk_bf16_f32 v67, v68, v69
	v_mul_f32_e32 v68, 0xbfb8aa3b, v48
	v_mul_f32_e32 v69, 0xbfb8aa3b, v49
	v_exp_f32_e32 v68, v68
	v_exp_f32_e32 v69, v69
	ds_write2_b64 v112, v[64:65], v[66:67] offset0:28 offset1:30
	v_mul_f32_e32 v66, 0xbfb8aa3b, v50
	v_add_f32_e32 v64, 1.0, v68
	v_add_f32_e32 v65, 1.0, v69
	v_mul_f32_e32 v67, 0xbfb8aa3b, v51
	v_rcp_f32_e32 v64, v64
	v_rcp_f32_e32 v65, v65
	v_exp_f32_e32 v66, v66
	v_exp_f32_e32 v67, v67
	s_add_u32 s2, s2, s6
	v_pk_mul_f32 v[48:49], v[48:49], v[64:65]
	v_add_f32_e32 v64, 1.0, v66
	v_add_f32_e32 v65, 1.0, v67
	v_mul_f32_e32 v66, 0xbfb8aa3b, v52
	v_mul_f32_e32 v67, 0xbfb8aa3b, v53
	v_rcp_f32_e32 v64, v64
	v_rcp_f32_e32 v65, v65
	v_exp_f32_e32 v66, v66
	v_exp_f32_e32 v67, v67
	v_cvt_pk_bf16_f32 v68, v48, v49
	v_pk_mul_f32 v[50:51], v[50:51], v[64:65]
	v_add_f32_e32 v64, 1.0, v66
	v_add_f32_e32 v65, 1.0, v67
	v_mul_f32_e32 v66, 0xbfb8aa3b, v54
	v_mul_f32_e32 v67, 0xbfb8aa3b, v55
	v_exp_f32_e32 v66, v66
	v_exp_f32_e32 v67, v67
	v_rcp_f32_e32 v64, v64
	v_rcp_f32_e32 v65, v65
	v_add_f32_e32 v66, 1.0, v66
	v_add_f32_e32 v67, 1.0, v67
	v_rcp_f32_e32 v66, v66
	v_rcp_f32_e32 v67, v67
	v_pk_mul_f32 v[48:49], v[52:53], v[64:65]
	v_cvt_pk_bf16_f32 v69, v50, v51
	v_cvt_pk_bf16_f32 v52, v48, v49
	v_pk_mul_f32 v[50:51], v[54:55], v[66:67]
	v_mul_f32_e32 v49, 0xbfb8aa3b, v56
	v_cvt_pk_bf16_f32 v53, v50, v51
	v_exp_f32_e32 v49, v49
	v_mul_f32_e32 v50, 0xbfb8aa3b, v57
	v_exp_f32_e32 v51, v50
	v_add_u32_e32 v48, 0x4000, v112
	v_add_f32_e32 v49, 1.0, v49
	v_rcp_f32_e32 v50, v49
	v_add_f32_e32 v49, 1.0, v51
	v_rcp_f32_e32 v51, v49
	v_mul_f32_e32 v49, 0xbfb8aa3b, v58
	ds_write2_b64 v48, v[68:69], v[52:53] offset0:64 offset1:66
	v_exp_f32_e32 v49, v49
	v_mul_f32_e32 v52, 0xbfb8aa3b, v59
	v_exp_f32_e32 v53, v52
	v_mul_f32_e32 v54, 0xbfb8aa3b, v61
	v_add_f32_e32 v49, 1.0, v49
	v_rcp_f32_e32 v52, v49
	v_add_f32_e32 v49, 1.0, v53
	v_rcp_f32_e32 v53, v49
	v_mul_f32_e32 v49, 0xbfb8aa3b, v60
	v_exp_f32_e32 v49, v49
	v_exp_f32_e32 v55, v54
	v_pk_mul_f32 v[50:51], v[56:57], v[50:51]
	v_pk_mul_f32 v[52:53], v[58:59], v[52:53]
	v_add_f32_e32 v49, 1.0, v49
	v_rcp_f32_e32 v54, v49
	v_add_f32_e32 v49, 1.0, v55
	v_mul_f32_e32 v55, 0xbfb8aa3b, v62
	v_exp_f32_e32 v56, v55
	v_mul_f32_e32 v55, 0xbfb8aa3b, v63
	v_exp_f32_e32 v57, v55
	v_rcp_f32_e32 v55, v49
	v_add_f32_e32 v49, 1.0, v56
	v_rcp_f32_e32 v56, v49
	v_add_f32_e32 v49, 1.0, v57
	v_rcp_f32_e32 v57, v49
	v_cvt_pk_bf16_f32 v50, v50, v51
	v_cvt_pk_bf16_f32 v51, v52, v53
	v_pk_mul_f32 v[52:53], v[60:61], v[54:55]
	v_pk_mul_f32 v[54:55], v[62:63], v[56:57]
	v_mul_f32_e32 v49, 0xbfb8aa3b, v32
	v_cvt_pk_bf16_f32 v52, v52, v53
	v_cvt_pk_bf16_f32 v53, v54, v55
	v_exp_f32_e32 v49, v49
	v_mul_f32_e32 v54, 0xbfb8aa3b, v33
	v_exp_f32_e32 v54, v54
	ds_write2_b64 v48, v[50:51], v[52:53] offset0:68 offset1:70
	v_add_f32_e32 v49, 1.0, v49
	v_rcp_f32_e32 v50, v49
	v_add_f32_e32 v49, 1.0, v54
	v_rcp_f32_e32 v51, v49
	v_mul_f32_e32 v49, 0xbfb8aa3b, v34
	v_exp_f32_e32 v49, v49
	v_mul_f32_e32 v52, 0xbfb8aa3b, v35
	v_exp_f32_e32 v52, v52
	v_pk_mul_f32 v[32:33], v[32:33], v[50:51]
	v_add_f32_e32 v49, 1.0, v49
	v_rcp_f32_e32 v50, v49
	v_add_f32_e32 v49, 1.0, v52
	v_rcp_f32_e32 v51, v49
	v_mul_f32_e32 v49, 0xbfb8aa3b, v36
	v_exp_f32_e32 v49, v49
	v_mul_f32_e32 v52, 0xbfb8aa3b, v37
	v_exp_f32_e32 v52, v52
	v_pk_mul_f32 v[34:35], v[34:35], v[50:51]
	v_add_f32_e32 v49, 1.0, v49
	v_mul_f32_e32 v51, 0xbfb8aa3b, v38
	v_rcp_f32_e32 v50, v49
	v_add_f32_e32 v49, 1.0, v52
	v_exp_f32_e32 v52, v51
	v_mul_f32_e32 v51, 0xbfb8aa3b, v39
	v_exp_f32_e32 v53, v51
	v_rcp_f32_e32 v51, v49
	v_add_f32_e32 v49, 1.0, v52
	v_rcp_f32_e32 v52, v49
	v_add_f32_e32 v49, 1.0, v53
	v_rcp_f32_e32 v53, v49
	v_cvt_pk_bf16_f32 v32, v32, v33
	v_cvt_pk_bf16_f32 v33, v34, v35
	v_pk_mul_f32 v[34:35], v[36:37], v[50:51]
	v_pk_mul_f32 v[36:37], v[38:39], v[52:53]
	v_cvt_pk_bf16_f32 v34, v34, v35
	v_cvt_pk_bf16_f32 v35, v36, v37
	v_mul_f32_e32 v36, 0xbfb8aa3b, v40
	v_mul_f32_e32 v37, 0xbfb8aa3b, v41
	v_exp_f32_e32 v36, v36
	v_exp_f32_e32 v37, v37
	ds_write2_b64 v48, v[32:33], v[34:35] offset0:72 offset1:74
	v_mul_f32_e32 v34, 0xbfb8aa3b, v42
	v_mul_f32_e32 v35, 0xbfb8aa3b, v43
	v_add_f32_e32 v32, 1.0, v36
	v_add_f32_e32 v33, 1.0, v37
	v_exp_f32_e32 v34, v34
	v_exp_f32_e32 v35, v35
	v_mul_f32_e32 v36, 0xbfb8aa3b, v44
	v_mul_f32_e32 v37, 0xbfb8aa3b, v45
	v_mul_f32_e32 v38, 0xbfb8aa3b, v46
	v_mul_f32_e32 v39, 0xbfb8aa3b, v47
	v_exp_f32_e32 v36, v36
	v_exp_f32_e32 v37, v37
	v_exp_f32_e32 v38, v38
	v_exp_f32_e32 v39, v39
	v_add_f32_e32 v34, 1.0, v34
	v_add_f32_e32 v35, 1.0, v35
	v_rcp_f32_e32 v32, v32
	v_rcp_f32_e32 v33, v33
	v_rcp_f32_e32 v34, v34
	v_rcp_f32_e32 v35, v35
	v_add_f32_e32 v36, 1.0, v36
	v_add_f32_e32 v37, 1.0, v37
	v_add_f32_e32 v38, 1.0, v38
	v_add_f32_e32 v39, 1.0, v39
	v_rcp_f32_e32 v36, v36
	v_rcp_f32_e32 v37, v37
	v_rcp_f32_e32 v38, v38
	v_rcp_f32_e32 v39, v39
	v_pk_mul_f32 v[32:33], v[40:41], v[32:33]
	v_pk_mul_f32 v[34:35], v[42:43], v[34:35]
	v_cvt_pk_bf16_f32 v32, v32, v33
	v_cvt_pk_bf16_f32 v33, v34, v35
	v_pk_mul_f32 v[34:35], v[44:45], v[36:37]
	v_pk_mul_f32 v[36:37], v[46:47], v[38:39]
	v_cvt_pk_bf16_f32 v34, v34, v35
	v_cvt_pk_bf16_f32 v35, v36, v37
	v_mul_f32_e32 v36, 0xbfb8aa3b, v16
	v_mul_f32_e32 v37, 0xbfb8aa3b, v17
	v_exp_f32_e32 v36, v36
	v_exp_f32_e32 v37, v37
	ds_write2_b64 v48, v[32:33], v[34:35] offset0:76 offset1:78
	v_mul_f32_e32 v34, 0xbfb8aa3b, v18
	v_add_f32_e32 v32, 1.0, v36
	v_add_f32_e32 v33, 1.0, v37
	v_mul_f32_e32 v35, 0xbfb8aa3b, v19
	v_rcp_f32_e32 v32, v32
	v_rcp_f32_e32 v33, v33
	v_exp_f32_e32 v34, v34
	v_exp_f32_e32 v35, v35
	s_addc_u32 s3, s3, 0
	v_pk_mul_f32 v[16:17], v[16:17], v[32:33]
	v_add_f32_e32 v32, 1.0, v34
	v_add_f32_e32 v33, 1.0, v35
	v_mul_f32_e32 v34, 0xbfb8aa3b, v20
	v_mul_f32_e32 v35, 0xbfb8aa3b, v21
	v_rcp_f32_e32 v32, v32
	v_rcp_f32_e32 v33, v33
	v_exp_f32_e32 v34, v34
	v_exp_f32_e32 v35, v35
	v_cvt_pk_bf16_f32 v16, v16, v17
	v_pk_mul_f32 v[18:19], v[18:19], v[32:33]
	v_add_f32_e32 v32, 1.0, v34
	v_add_f32_e32 v33, 1.0, v35
	v_mul_f32_e32 v34, 0xbfb8aa3b, v22
	v_mul_f32_e32 v35, 0xbfb8aa3b, v23
	v_exp_f32_e32 v34, v34
	v_exp_f32_e32 v35, v35
	v_rcp_f32_e32 v32, v32
	v_rcp_f32_e32 v33, v33
	v_add_f32_e32 v34, 1.0, v34
	v_add_f32_e32 v35, 1.0, v35
	v_rcp_f32_e32 v34, v34
	v_rcp_f32_e32 v35, v35
	v_cvt_pk_bf16_f32 v17, v18, v19
	v_pk_mul_f32 v[18:19], v[20:21], v[32:33]
	v_pk_mul_f32 v[20:21], v[22:23], v[34:35]
	v_cvt_pk_bf16_f32 v18, v18, v19
	v_cvt_pk_bf16_f32 v19, v20, v21
	v_mul_f32_e32 v20, 0xbfb8aa3b, v24
	v_mul_f32_e32 v21, 0xbfb8aa3b, v25
	v_exp_f32_e32 v20, v20
	v_exp_f32_e32 v21, v21
	ds_write2_b64 v48, v[16:17], v[18:19] offset0:80 offset1:82
	v_mul_f32_e32 v18, 0xbfb8aa3b, v26
	v_mul_f32_e32 v19, 0xbfb8aa3b, v27
	v_add_f32_e32 v16, 1.0, v20
	v_add_f32_e32 v17, 1.0, v21
	v_exp_f32_e32 v18, v18
	v_exp_f32_e32 v19, v19
	v_mul_f32_e32 v20, 0xbfb8aa3b, v28
	v_mul_f32_e32 v21, 0xbfb8aa3b, v29
	v_mul_f32_e32 v22, 0xbfb8aa3b, v30
	v_mul_f32_e32 v23, 0xbfb8aa3b, v31
	v_exp_f32_e32 v20, v20
	v_exp_f32_e32 v21, v21
	v_exp_f32_e32 v22, v22
	v_exp_f32_e32 v23, v23
	v_add_f32_e32 v18, 1.0, v18
	v_add_f32_e32 v19, 1.0, v19
	v_rcp_f32_e32 v16, v16
	v_rcp_f32_e32 v17, v17
	v_rcp_f32_e32 v18, v18
	v_rcp_f32_e32 v19, v19
	v_add_f32_e32 v20, 1.0, v20
	v_add_f32_e32 v21, 1.0, v21
	v_add_f32_e32 v22, 1.0, v22
	v_add_f32_e32 v23, 1.0, v23
	v_rcp_f32_e32 v20, v20
	v_rcp_f32_e32 v21, v21
	v_rcp_f32_e32 v22, v22
	v_rcp_f32_e32 v23, v23
	v_pk_mul_f32 v[16:17], v[24:25], v[16:17]
	v_pk_mul_f32 v[18:19], v[26:27], v[18:19]
	v_cvt_pk_bf16_f32 v16, v16, v17
	v_cvt_pk_bf16_f32 v17, v18, v19
	v_pk_mul_f32 v[18:19], v[28:29], v[20:21]
	v_pk_mul_f32 v[20:21], v[30:31], v[22:23]
	v_cvt_pk_bf16_f32 v18, v18, v19
	v_cvt_pk_bf16_f32 v19, v20, v21
	v_mul_f32_e32 v20, 0xbfb8aa3b, v0
	v_mul_f32_e32 v21, 0xbfb8aa3b, v1
	v_exp_f32_e32 v20, v20
	v_exp_f32_e32 v21, v21
	ds_write2_b64 v48, v[16:17], v[18:19] offset0:84 offset1:86
	v_mul_f32_e32 v18, 0xbfb8aa3b, v2
	v_add_f32_e32 v16, 1.0, v20
	v_add_f32_e32 v17, 1.0, v21
	v_mul_f32_e32 v19, 0xbfb8aa3b, v3
	v_rcp_f32_e32 v16, v16
	v_rcp_f32_e32 v17, v17
	v_exp_f32_e32 v18, v18
	v_exp_f32_e32 v19, v19
	v_pk_mul_f32 v[0:1], v[0:1], v[16:17]
	v_add_f32_e32 v16, 1.0, v18
	v_add_f32_e32 v17, 1.0, v19
	v_mul_f32_e32 v18, 0xbfb8aa3b, v4
	v_mul_f32_e32 v19, 0xbfb8aa3b, v5
	v_rcp_f32_e32 v16, v16
	v_rcp_f32_e32 v17, v17
	v_exp_f32_e32 v18, v18
	v_exp_f32_e32 v19, v19
	v_cvt_pk_bf16_f32 v0, v0, v1
	v_pk_mul_f32 v[2:3], v[2:3], v[16:17]
	v_add_f32_e32 v16, 1.0, v18
	v_add_f32_e32 v17, 1.0, v19
	v_mul_f32_e32 v18, 0xbfb8aa3b, v6
	v_mul_f32_e32 v19, 0xbfb8aa3b, v7
	v_exp_f32_e32 v18, v18
	v_exp_f32_e32 v19, v19
	v_rcp_f32_e32 v16, v16
	v_rcp_f32_e32 v17, v17
	v_add_f32_e32 v18, 1.0, v18
	v_add_f32_e32 v19, 1.0, v19
	v_rcp_f32_e32 v18, v18
	v_rcp_f32_e32 v19, v19
	v_cvt_pk_bf16_f32 v1, v2, v3
	v_pk_mul_f32 v[2:3], v[4:5], v[16:17]
	v_pk_mul_f32 v[4:5], v[6:7], v[18:19]
	v_cvt_pk_bf16_f32 v2, v2, v3
	v_cvt_pk_bf16_f32 v3, v4, v5
	v_mul_f32_e32 v4, 0xbfb8aa3b, v8
	v_mul_f32_e32 v5, 0xbfb8aa3b, v9
	v_exp_f32_e32 v4, v4
	v_exp_f32_e32 v5, v5
	ds_write2_b64 v48, v[0:1], v[2:3] offset0:88 offset1:90
	v_mul_f32_e32 v2, 0xbfb8aa3b, v10
	v_mul_f32_e32 v3, 0xbfb8aa3b, v11
	v_add_f32_e32 v0, 1.0, v4
	v_add_f32_e32 v1, 1.0, v5
	v_exp_f32_e32 v2, v2
	v_exp_f32_e32 v3, v3
	v_mul_f32_e32 v4, 0xbfb8aa3b, v12
	v_mul_f32_e32 v5, 0xbfb8aa3b, v13
	v_mul_f32_e32 v6, 0xbfb8aa3b, v14
	v_mul_f32_e32 v7, 0xbfb8aa3b, v15
	v_exp_f32_e32 v4, v4
	v_exp_f32_e32 v5, v5
	v_exp_f32_e32 v6, v6
	v_exp_f32_e32 v7, v7
	v_add_f32_e32 v2, 1.0, v2
	v_add_f32_e32 v3, 1.0, v3
	v_rcp_f32_e32 v0, v0
	v_rcp_f32_e32 v1, v1
	v_rcp_f32_e32 v2, v2
	v_rcp_f32_e32 v3, v3
	v_add_f32_e32 v4, 1.0, v4
	v_add_f32_e32 v5, 1.0, v5
	v_add_f32_e32 v6, 1.0, v6
	v_add_f32_e32 v7, 1.0, v7
	v_rcp_f32_e32 v4, v4
	v_rcp_f32_e32 v5, v5
	v_rcp_f32_e32 v6, v6
	v_rcp_f32_e32 v7, v7
	v_pk_mul_f32 v[0:1], v[8:9], v[0:1]
	v_pk_mul_f32 v[2:3], v[10:11], v[2:3]
	v_cvt_pk_bf16_f32 v0, v0, v1
	v_cvt_pk_bf16_f32 v1, v2, v3
	v_pk_mul_f32 v[2:3], v[12:13], v[4:5]
	v_pk_mul_f32 v[4:5], v[14:15], v[6:7]
	v_cvt_pk_bf16_f32 v2, v2, v3
	v_cvt_pk_bf16_f32 v3, v4, v5
	v_mov_b32_e32 v14, v208
	ds_write2_b64 v48, v[0:1], v[2:3] offset0:92 offset1:94
	s_waitcnt lgkmcnt(0)
	v_lshlrev_b32_e32 v0, 4, v14
	v_ashrrev_i32_e32 v4, 5, v14
	v_and_b32_e32 v168, 0x1f0, v0
	v_ashrrev_i32_e32 v5, 31, v4
	v_lshl_add_u64 v[8:9], s[2:3], 0, v[168:169]
	v_mad_u64_u32 v[0:1], s[2:3], v4, s80, v[168:169]
	v_lshlrev_b64 v[4:5], 12, v[4:5]
	v_lshl_add_u64 v[10:11], v[8:9], 0, v[4:5]
	v_add_u32_e32 v4, 0x200, v14
	s_barrier
	ds_read_b128 v[0:3], v0
	v_ashrrev_i32_e32 v12, 5, v4
	v_mad_u64_u32 v[4:5], s[2:3], v12, s80, v[168:169]
	ds_read_b128 v[4:7], v4
	v_ashrrev_i32_e32 v13, 31, v12
	s_waitcnt lgkmcnt(1)
	global_store_dwordx4 v[10:11], v[0:3], off
	s_nop 1
	v_lshlrev_b64 v[0:1], 12, v[12:13]
	v_lshl_add_u64 v[0:1], v[8:9], 0, v[0:1]
	s_waitcnt lgkmcnt(0)
	global_store_dwordx4 v[0:1], v[4:7], off
	v_add_u32_e32 v0, 0x400, v14
	s_nop 0
	v_ashrrev_i32_e32 v4, 5, v0
	v_ashrrev_i32_e32 v5, 31, v4
	v_mad_u64_u32 v[0:1], s[2:3], v4, s80, v[168:169]
	v_lshlrev_b64 v[4:5], 12, v[4:5]
	v_lshl_add_u64 v[10:11], v[8:9], 0, v[4:5]
	v_add_u32_e32 v4, 0x600, v14
	ds_read_b128 v[0:3], v0
	v_ashrrev_i32_e32 v12, 5, v4
	v_mad_u64_u32 v[4:5], s[2:3], v12, s80, v[168:169]
	ds_read_b128 v[4:7], v4
	v_ashrrev_i32_e32 v13, 31, v12
	s_waitcnt lgkmcnt(1)
	global_store_dwordx4 v[10:11], v[0:3], off
	s_nop 1
	v_lshlrev_b64 v[0:1], 12, v[12:13]
	v_lshl_add_u64 v[0:1], v[8:9], 0, v[0:1]
	s_waitcnt lgkmcnt(0)
	global_store_dwordx4 v[0:1], v[4:7], off
	v_add_u32_e32 v0, 0x800, v14
	s_nop 0
	v_ashrrev_i32_e32 v4, 5, v0
	v_ashrrev_i32_e32 v5, 31, v4
	v_mad_u64_u32 v[0:1], s[2:3], v4, s80, v[168:169]
	v_lshlrev_b64 v[4:5], 12, v[4:5]
	v_lshl_add_u64 v[10:11], v[8:9], 0, v[4:5]
	v_add_u32_e32 v4, 0xa00, v14
	ds_read_b128 v[0:3], v0
	v_ashrrev_i32_e32 v12, 5, v4
	v_mad_u64_u32 v[4:5], s[2:3], v12, s80, v[168:169]
	ds_read_b128 v[4:7], v4
	v_ashrrev_i32_e32 v13, 31, v12
	s_waitcnt lgkmcnt(1)
	global_store_dwordx4 v[10:11], v[0:3], off
	s_nop 1
	v_lshlrev_b64 v[0:1], 12, v[12:13]
	v_lshl_add_u64 v[0:1], v[8:9], 0, v[0:1]
	s_waitcnt lgkmcnt(0)
	global_store_dwordx4 v[0:1], v[4:7], off
	v_add_u32_e32 v0, 0xc00, v14
	s_nop 0
	v_ashrrev_i32_e32 v4, 5, v0
	v_ashrrev_i32_e32 v5, 31, v4
	v_mad_u64_u32 v[0:1], s[2:3], v4, s80, v[168:169]
	v_lshlrev_b64 v[4:5], 12, v[4:5]
	v_lshl_add_u64 v[10:11], v[8:9], 0, v[4:5]
	v_add_u32_e32 v4, 0xe00, v14
	ds_read_b128 v[0:3], v0
	v_ashrrev_i32_e32 v12, 5, v4
	v_mad_u64_u32 v[4:5], s[2:3], v12, s80, v[168:169]
	ds_read_b128 v[4:7], v4
	v_ashrrev_i32_e32 v13, 31, v12
	s_waitcnt lgkmcnt(1)
	global_store_dwordx4 v[10:11], v[0:3], off
	s_nop 1
	v_lshlrev_b64 v[0:1], 12, v[12:13]
	v_lshl_add_u64 v[0:1], v[8:9], 0, v[0:1]
	s_waitcnt lgkmcnt(0)
	global_store_dwordx4 v[0:1], v[4:7], off
	v_add_u32_e32 v0, 0x1000, v14
	s_nop 0
	v_ashrrev_i32_e32 v4, 5, v0
	v_ashrrev_i32_e32 v5, 31, v4
	v_mad_u64_u32 v[0:1], s[2:3], v4, s80, v[168:169]
	v_lshlrev_b64 v[4:5], 12, v[4:5]
	v_lshl_add_u64 v[10:11], v[8:9], 0, v[4:5]
	v_add_u32_e32 v4, 0x1200, v14
	ds_read_b128 v[0:3], v0
	v_ashrrev_i32_e32 v12, 5, v4
	v_mad_u64_u32 v[4:5], s[2:3], v12, s80, v[168:169]
	ds_read_b128 v[4:7], v4
	v_ashrrev_i32_e32 v13, 31, v12
	s_waitcnt lgkmcnt(1)
	global_store_dwordx4 v[10:11], v[0:3], off
	s_nop 1
	v_lshlrev_b64 v[0:1], 12, v[12:13]
	v_lshl_add_u64 v[0:1], v[8:9], 0, v[0:1]
	s_waitcnt lgkmcnt(0)
	global_store_dwordx4 v[0:1], v[4:7], off
	v_add_u32_e32 v0, 0x1400, v14
	s_nop 0
	v_ashrrev_i32_e32 v4, 5, v0
	v_ashrrev_i32_e32 v5, 31, v4
	v_mad_u64_u32 v[0:1], s[2:3], v4, s80, v[168:169]
	v_lshlrev_b64 v[4:5], 12, v[4:5]
	v_lshl_add_u64 v[10:11], v[8:9], 0, v[4:5]
	v_add_u32_e32 v4, 0x1600, v14
	ds_read_b128 v[0:3], v0
	v_ashrrev_i32_e32 v12, 5, v4
	v_mad_u64_u32 v[4:5], s[2:3], v12, s80, v[168:169]
	ds_read_b128 v[4:7], v4
	v_ashrrev_i32_e32 v13, 31, v12
	s_waitcnt lgkmcnt(1)
	global_store_dwordx4 v[10:11], v[0:3], off
	s_nop 1
	v_lshlrev_b64 v[0:1], 12, v[12:13]
	v_lshl_add_u64 v[0:1], v[8:9], 0, v[0:1]
	s_waitcnt lgkmcnt(0)
	global_store_dwordx4 v[0:1], v[4:7], off
	v_add_u32_e32 v0, 0x1800, v14
	s_nop 0
	v_ashrrev_i32_e32 v4, 5, v0
	v_ashrrev_i32_e32 v5, 31, v4
	v_mad_u64_u32 v[0:1], s[2:3], v4, s80, v[168:169]
	v_lshlrev_b64 v[4:5], 12, v[4:5]
	v_lshl_add_u64 v[10:11], v[8:9], 0, v[4:5]
	v_add_u32_e32 v4, 0x1a00, v14
	ds_read_b128 v[0:3], v0
	v_ashrrev_i32_e32 v12, 5, v4
	v_mad_u64_u32 v[4:5], s[2:3], v12, s80, v[168:169]
	ds_read_b128 v[4:7], v4
	v_ashrrev_i32_e32 v13, 31, v12
	s_waitcnt lgkmcnt(1)
	global_store_dwordx4 v[10:11], v[0:3], off
	s_nop 1
	v_lshlrev_b64 v[0:1], 12, v[12:13]
	v_lshl_add_u64 v[0:1], v[8:9], 0, v[0:1]
	s_waitcnt lgkmcnt(0)
	global_store_dwordx4 v[0:1], v[4:7], off
	v_add_u32_e32 v0, 0x1c00, v14
	s_nop 0
	v_ashrrev_i32_e32 v4, 5, v0
	v_ashrrev_i32_e32 v5, 31, v4
	v_mad_u64_u32 v[0:1], s[2:3], v4, s80, v[168:169]
	v_lshlrev_b64 v[4:5], 12, v[4:5]
	v_lshl_add_u64 v[10:11], v[8:9], 0, v[4:5]
	v_add_u32_e32 v4, 0x1e00, v14
	ds_read_b128 v[0:3], v0
	v_ashrrev_i32_e32 v12, 5, v4
	v_mad_u64_u32 v[4:5], s[2:3], v12, s80, v[168:169]
	ds_read_b128 v[4:7], v4
	v_ashrrev_i32_e32 v13, 31, v12
	s_waitcnt lgkmcnt(1)
	global_store_dwordx4 v[10:11], v[0:3], off
	s_mov_b64 s[2:3], 0
	s_nop 0
	v_lshlrev_b64 v[0:1], 12, v[12:13]
	v_lshl_add_u64 v[0:1], v[8:9], 0, v[0:1]
	s_waitcnt lgkmcnt(0)
	global_store_dwordx4 v[0:1], v[4:7], off
	s_barrier
.LBB0_632:
	s_and_b64 vcc, exec, s[2:3]
	s_cbranch_vccz .LBB0_627
	s_and_b32 s58, s83, 7
	s_ashr_i32 s2, s83, 3
	s_lshl_b32 s3, s58, 19
	s_add_u32 s6, s1, s3
	s_addc_u32 s7, s69, 0
	s_mov_b32 s54, s6
	s_mov_b32 s55, s7
	s_ashr_i32 s3, s2, 31
	s_lshl_b64 s[6:7], s[2:3], 19
	s_add_u32 s6, s63, s6
	s_addc_u32 s7, s68, s7
	s_mov_b32 s56, s6
	s_mov_b32 s57, s7
	s_movk_i32 s3, 0x100
	s_mov_b32 s6, -2
	v_lshrrev_b32_e32 v212, 6, v208
	v_and_b32_e32 v213, 63, v208
	v_readfirstlane_b32 s98, v212
	v_and_b32_e32 v214, 3, v213
	v_bfe_u32 v215, v213, 2, 1
	v_lshl_or_b32 v214, v215, 3, v214
	v_bfe_u32 v215, v213, 3, 1
	v_lshl_or_b32 v214, v215, 2, v214
	s_and_b32 s14, s98, 1
	s_lshr_b32 s100, s98, 2
	s_lshl_b32 s99, s98, 10
	v_lshrrev_b32_e32 v215, 4, v213
	v_bfe_u32 v216, v214, 1, 3
	v_xor_b32_e32 v216, v215, v216
	v_lshlrev_b32_e32 v216, 4, v216
	v_lshl_add_u32 v214, s14, 6, v214
	v_lshl_add_u32 v168, v214, 7, v216
	v_xor_b32_e32 v171, 64, v168
	v_add_u32_e32 v170, 0x10000, v168
	v_add_u32_e32 v196, 0x10000, v171
	v_bfe_u32 v216, v213, 1, 3
	v_xor_b32_e32 v216, v215, v216
	v_lshlrev_b32_e32 v216, 4, v216
	v_and_b32_e32 v214, 15, v213
	s_lshr_b32 s101, s98, 1
	v_lshl_add_u32 v214, s101, 5, v214
	v_lshl_add_u32 v197, v214, 7, v216
	v_add_u32_e32 v197, 0x8000, v197
	v_xor_b32_e32 v199, 64, v197
	v_add_u32_e32 v198, 0x10000, v197
	v_add_u32_e32 v200, 0x10000, v199
	v_lshl_add_u32 v216, s14, 2, v215
	v_and_b32_e32 v214, 7, v213
	v_xor_b32_e32 v216, v214, v216
	v_lshlrev_b32_e32 v216, 4, v216
	v_lshrrev_b32_e32 v214, 3, v213
	v_lshl_add_u32 v215, s98, 3, v214
	v_lshl_add_u32 v201, v215, 11, v216
	v_add_u32_e32 v202, 0x40000, v201
	v_add_u32_e32 v203, 0x20000, v201
	v_add_u32_e32 v204, 0x60000, v201
	s_and_b32 s101, s98, 3
	s_lshl_b32 s101, s101, 3
	s_lshl_b32 s14, s100, 6
	s_add_u32 s101, s101, s14
	v_add_u32_e32 v215, s101, v214
	v_lshl_add_u32 v205, v215, 11, v216
	v_add_u32_e32 v206, 0x40000, v205
	v_add_u32_e32 v210, 0x10000, v205
	v_add_u32_e32 v211, 0x50000, v205
	v_mov_b32_e32 v0, 0
	v_mov_b32_e32 v1, 0
	v_mov_b32_e32 v2, 0
	v_mov_b32_e32 v3, 0
	v_mov_b32_e32 v4, 0
	v_mov_b32_e32 v5, 0
	v_mov_b32_e32 v6, 0
	v_mov_b32_e32 v7, 0
	v_mov_b32_e32 v8, 0
	v_mov_b32_e32 v9, 0
	v_mov_b32_e32 v10, 0
	v_mov_b32_e32 v11, 0
	v_mov_b32_e32 v12, 0
	v_mov_b32_e32 v13, 0
	v_mov_b32_e32 v14, 0
	v_mov_b32_e32 v15, 0
	v_mov_b32_e32 v112, 0
	v_mov_b32_e32 v113, 0
	v_mov_b32_e32 v114, 0
	v_mov_b32_e32 v115, 0
	v_mov_b32_e32 v116, 0
	v_mov_b32_e32 v117, 0
	v_mov_b32_e32 v118, 0
	v_mov_b32_e32 v119, 0
	v_mov_b32_e32 v120, 0
	v_mov_b32_e32 v121, 0
	v_mov_b32_e32 v122, 0
	v_mov_b32_e32 v123, 0
	v_mov_b32_e32 v124, 0
	v_mov_b32_e32 v125, 0
	v_mov_b32_e32 v126, 0
	v_mov_b32_e32 v127, 0
	v_mov_b32_e32 v96, 0
	v_mov_b32_e32 v97, 0
	v_mov_b32_e32 v98, 0
	v_mov_b32_e32 v99, 0
	v_mov_b32_e32 v100, 0
	v_mov_b32_e32 v101, 0
	v_mov_b32_e32 v102, 0
	v_mov_b32_e32 v103, 0
	v_mov_b32_e32 v104, 0
	v_mov_b32_e32 v105, 0
	v_mov_b32_e32 v106, 0
	v_mov_b32_e32 v107, 0
	v_mov_b32_e32 v108, 0
	v_mov_b32_e32 v109, 0
	v_mov_b32_e32 v110, 0
	v_mov_b32_e32 v111, 0
	v_mov_b32_e32 v80, 0
	v_mov_b32_e32 v81, 0
	v_mov_b32_e32 v82, 0
	v_mov_b32_e32 v83, 0
	v_mov_b32_e32 v84, 0
	v_mov_b32_e32 v85, 0
	v_mov_b32_e32 v86, 0
	v_mov_b32_e32 v87, 0
	v_mov_b32_e32 v88, 0
	v_mov_b32_e32 v89, 0
	v_mov_b32_e32 v90, 0
	v_mov_b32_e32 v91, 0
	v_mov_b32_e32 v92, 0
	v_mov_b32_e32 v93, 0
	v_mov_b32_e32 v94, 0
	v_mov_b32_e32 v95, 0
	v_mov_b32_e32 v64, 0
	v_mov_b32_e32 v65, 0
	v_mov_b32_e32 v66, 0
	v_mov_b32_e32 v67, 0
	v_mov_b32_e32 v68, 0
	v_mov_b32_e32 v69, 0
	v_mov_b32_e32 v70, 0
	v_mov_b32_e32 v71, 0
	v_mov_b32_e32 v72, 0
	v_mov_b32_e32 v73, 0
	v_mov_b32_e32 v74, 0
	v_mov_b32_e32 v75, 0
	v_mov_b32_e32 v76, 0
	v_mov_b32_e32 v77, 0
	v_mov_b32_e32 v78, 0
	v_mov_b32_e32 v79, 0
	v_mov_b32_e32 v48, 0
	v_mov_b32_e32 v49, 0
	v_mov_b32_e32 v50, 0
	v_mov_b32_e32 v51, 0
	v_mov_b32_e32 v52, 0
	v_mov_b32_e32 v53, 0
	v_mov_b32_e32 v54, 0
	v_mov_b32_e32 v55, 0
	v_mov_b32_e32 v56, 0
	v_mov_b32_e32 v57, 0
	v_mov_b32_e32 v58, 0
	v_mov_b32_e32 v59, 0
	v_mov_b32_e32 v60, 0
	v_mov_b32_e32 v61, 0
	v_mov_b32_e32 v62, 0
	v_mov_b32_e32 v63, 0
	v_mov_b32_e32 v32, 0
	v_mov_b32_e32 v33, 0
	v_mov_b32_e32 v34, 0
	v_mov_b32_e32 v35, 0
	v_mov_b32_e32 v36, 0
	v_mov_b32_e32 v37, 0
	v_mov_b32_e32 v38, 0
	v_mov_b32_e32 v39, 0
	v_mov_b32_e32 v40, 0
	v_mov_b32_e32 v41, 0
	v_mov_b32_e32 v42, 0
	v_mov_b32_e32 v43, 0
	v_mov_b32_e32 v44, 0
	v_mov_b32_e32 v45, 0
	v_mov_b32_e32 v46, 0
	v_mov_b32_e32 v47, 0
	v_mov_b32_e32 v16, 0
	v_mov_b32_e32 v17, 0
	v_mov_b32_e32 v18, 0
	v_mov_b32_e32 v19, 0
	v_mov_b32_e32 v20, 0
	v_mov_b32_e32 v21, 0
	v_mov_b32_e32 v22, 0
	v_mov_b32_e32 v23, 0
	v_mov_b32_e32 v24, 0
	v_mov_b32_e32 v25, 0
	v_mov_b32_e32 v26, 0
	v_mov_b32_e32 v27, 0
	v_mov_b32_e32 v28, 0
	v_mov_b32_e32 v29, 0
	v_mov_b32_e32 v30, 0
	v_mov_b32_e32 v31, 0
	s_add_u32 m0, s99, 0x8000
	s_nop 0
	global_load_lds_dwordx4 v205, s[54:55]
	s_add_u32 m0, s99, 0xa000
	s_nop 0
	global_load_lds_dwordx4 v206, s[54:55]
	s_add_u32 m0, s99, 0x0
	s_nop 0
	global_load_lds_dwordx4 v201, s[56:57]
	s_add_u32 m0, s99, 0x2000
	s_nop 0
	global_load_lds_dwordx4 v202, s[56:57]
	s_add_u32 m0, s99, 0xc000
	s_nop 0
	global_load_lds_dwordx4 v210, s[54:55]
	s_add_u32 m0, s99, 0xe000
	s_nop 0
	global_load_lds_dwordx4 v211, s[54:55]
	s_add_u32 s54, s54, 0x80
	s_addc_u32 s55, s55, 0
	s_add_u32 m0, s99, 0x4000
	s_nop 0
	global_load_lds_dwordx4 v203, s[56:57]
	s_add_u32 m0, s99, 0x6000
	s_nop 0
	global_load_lds_dwordx4 v204, s[56:57]
	s_add_u32 s56, s56, 0x80
	s_addc_u32 s57, s57, 0
	s_cmp_eq_u32 s100, 0
	s_cbranch_scc1 .Lg8_p6h_pg0
	s_barrier
.Lg8_p6h_pg0:
	s_waitcnt vmcnt(4)
	s_barrier
	s_add_u32 m0, s99, 0x18000
	s_nop 0
	global_load_lds_dwordx4 v205, s[54:55]
	s_add_u32 m0, s99, 0x1a000
	s_nop 0
	global_load_lds_dwordx4 v206, s[54:55]
	s_add_u32 m0, s99, 0x10000
	s_nop 0
	global_load_lds_dwordx4 v201, s[56:57]
	s_add_u32 m0, s99, 0x12000
	s_nop 0
	global_load_lds_dwordx4 v202, s[56:57]
	s_add_u32 m0, s99, 0x1c000
	s_nop 0
	global_load_lds_dwordx4 v210, s[54:55]
	s_add_u32 m0, s99, 0x1e000
	s_nop 0
	global_load_lds_dwordx4 v211, s[54:55]
	s_add_u32 s54, s54, 0x80
	s_addc_u32 s55, s55, 0
	s_waitcnt vmcnt(6)
	s_barrier
	s_mov_b32 s101, 7
.Lg8_p6h_loop:
	ds_read_b128 v[160:163], v197 offset:0
	ds_read_b128 v[164:167], v199 offset:0
	ds_read_b128 v[172:175], v197 offset:2048
	ds_read_b128 v[176:179], v199 offset:2048
	ds_read_b128 v[128:131], v168 offset:0
	ds_read_b128 v[132:135], v171 offset:0
	ds_read_b128 v[136:139], v168 offset:2048
	ds_read_b128 v[140:143], v171 offset:2048
	ds_read_b128 v[144:147], v168 offset:4096
	ds_read_b128 v[148:151], v171 offset:4096
	ds_read_b128 v[152:155], v168 offset:6144
	ds_read_b128 v[156:159], v171 offset:6144
	s_add_u32 m0, s99, 0x14000
	s_nop 0
	global_load_lds_dwordx4 v203, s[56:57]
	s_add_u32 m0, s99, 0x16000
	s_nop 0
	global_load_lds_dwordx4 v204, s[56:57]
	s_add_u32 s56, s56, 0x80
	s_addc_u32 s57, s57, 0
	s_waitcnt lgkmcnt(8)
	s_barrier
	s_waitcnt lgkmcnt(0)
	s_setprio 1
	v_mfma_f32_16x16x32_bf16 v[0:3], v[128:131], v[160:163], v[0:3]
	v_mfma_f32_16x16x32_bf16 v[0:3], v[132:135], v[164:167], v[0:3]
	v_mfma_f32_16x16x32_bf16 v[4:7], v[128:131], v[172:175], v[4:7]
	v_mfma_f32_16x16x32_bf16 v[4:7], v[132:135], v[176:179], v[4:7]
	v_mfma_f32_16x16x32_bf16 v[8:11], v[136:139], v[160:163], v[8:11]
	v_mfma_f32_16x16x32_bf16 v[8:11], v[140:143], v[164:167], v[8:11]
	v_mfma_f32_16x16x32_bf16 v[12:15], v[136:139], v[172:175], v[12:15]
	v_mfma_f32_16x16x32_bf16 v[12:15], v[140:143], v[176:179], v[12:15]
	v_mfma_f32_16x16x32_bf16 v[112:115], v[144:147], v[160:163], v[112:115]
	v_mfma_f32_16x16x32_bf16 v[112:115], v[148:151], v[164:167], v[112:115]
	v_mfma_f32_16x16x32_bf16 v[116:119], v[144:147], v[172:175], v[116:119]
	v_mfma_f32_16x16x32_bf16 v[116:119], v[148:151], v[176:179], v[116:119]
	v_mfma_f32_16x16x32_bf16 v[120:123], v[152:155], v[160:163], v[120:123]
	v_mfma_f32_16x16x32_bf16 v[120:123], v[156:159], v[164:167], v[120:123]
	v_mfma_f32_16x16x32_bf16 v[124:127], v[152:155], v[172:175], v[124:127]
	v_mfma_f32_16x16x32_bf16 v[124:127], v[156:159], v[176:179], v[124:127]
	s_setprio 0
	s_barrier
	ds_read_b128 v[180:183], v197 offset:16384
	ds_read_b128 v[184:187], v199 offset:16384
	ds_read_b128 v[188:191], v197 offset:18432
	ds_read_b128 v[192:195], v199 offset:18432
	s_add_u32 m0, s99, 0x8000
	s_nop 0
	global_load_lds_dwordx4 v205, s[54:55]
	s_add_u32 m0, s99, 0xa000
	s_nop 0
	global_load_lds_dwordx4 v206, s[54:55]
	s_barrier
	s_waitcnt lgkmcnt(0)
	s_setprio 1
	v_mfma_f32_16x16x32_bf16 v[64:67], v[128:131], v[180:183], v[64:67]
	v_mfma_f32_16x16x32_bf16 v[64:67], v[132:135], v[184:187], v[64:67]
	v_mfma_f32_16x16x32_bf16 v[68:71], v[128:131], v[188:191], v[68:71]
	v_mfma_f32_16x16x32_bf16 v[68:71], v[132:135], v[192:195], v[68:71]
	v_mfma_f32_16x16x32_bf16 v[72:75], v[136:139], v[180:183], v[72:75]
	v_mfma_f32_16x16x32_bf16 v[72:75], v[140:143], v[184:187], v[72:75]
	v_mfma_f32_16x16x32_bf16 v[76:79], v[136:139], v[188:191], v[76:79]
	v_mfma_f32_16x16x32_bf16 v[76:79], v[140:143], v[192:195], v[76:79]
	v_mfma_f32_16x16x32_bf16 v[48:51], v[144:147], v[180:183], v[48:51]
	v_mfma_f32_16x16x32_bf16 v[48:51], v[148:151], v[184:187], v[48:51]
	v_mfma_f32_16x16x32_bf16 v[52:55], v[144:147], v[188:191], v[52:55]
	v_mfma_f32_16x16x32_bf16 v[52:55], v[148:151], v[192:195], v[52:55]
	v_mfma_f32_16x16x32_bf16 v[56:59], v[152:155], v[180:183], v[56:59]
	v_mfma_f32_16x16x32_bf16 v[56:59], v[156:159], v[184:187], v[56:59]
	v_mfma_f32_16x16x32_bf16 v[60:63], v[152:155], v[188:191], v[60:63]
	v_mfma_f32_16x16x32_bf16 v[60:63], v[156:159], v[192:195], v[60:63]
	s_setprio 0
	s_barrier
	ds_read_b128 v[128:131], v168 offset:16384
	ds_read_b128 v[132:135], v171 offset:16384
	ds_read_b128 v[136:139], v168 offset:18432
	ds_read_b128 v[140:143], v171 offset:18432
	ds_read_b128 v[144:147], v168 offset:20480
	ds_read_b128 v[148:151], v171 offset:20480
	ds_read_b128 v[152:155], v168 offset:22528
	ds_read_b128 v[156:159], v171 offset:22528
	s_add_u32 m0, s99, 0x0
	s_nop 0
	global_load_lds_dwordx4 v201, s[56:57]
	s_add_u32 m0, s99, 0x2000
	s_nop 0
	global_load_lds_dwordx4 v202, s[56:57]
	s_barrier
	s_waitcnt lgkmcnt(0)
	s_setprio 1
	v_mfma_f32_16x16x32_bf16 v[96:99], v[128:131], v[160:163], v[96:99]
	v_mfma_f32_16x16x32_bf16 v[96:99], v[132:135], v[164:167], v[96:99]
	v_mfma_f32_16x16x32_bf16 v[100:103], v[128:131], v[172:175], v[100:103]
	v_mfma_f32_16x16x32_bf16 v[100:103], v[132:135], v[176:179], v[100:103]
	v_mfma_f32_16x16x32_bf16 v[104:107], v[136:139], v[160:163], v[104:107]
	v_mfma_f32_16x16x32_bf16 v[104:107], v[140:143], v[164:167], v[104:107]
	v_mfma_f32_16x16x32_bf16 v[108:111], v[136:139], v[172:175], v[108:111]
	v_mfma_f32_16x16x32_bf16 v[108:111], v[140:143], v[176:179], v[108:111]
	v_mfma_f32_16x16x32_bf16 v[80:83], v[144:147], v[160:163], v[80:83]
	v_mfma_f32_16x16x32_bf16 v[80:83], v[148:151], v[164:167], v[80:83]
	v_mfma_f32_16x16x32_bf16 v[84:87], v[144:147], v[172:175], v[84:87]
	v_mfma_f32_16x16x32_bf16 v[84:87], v[148:151], v[176:179], v[84:87]
	v_mfma_f32_16x16x32_bf16 v[88:91], v[152:155], v[160:163], v[88:91]
	v_mfma_f32_16x16x32_bf16 v[88:91], v[156:159], v[164:167], v[88:91]
	v_mfma_f32_16x16x32_bf16 v[92:95], v[152:155], v[172:175], v[92:95]
	v_mfma_f32_16x16x32_bf16 v[92:95], v[156:159], v[176:179], v[92:95]
	s_setprio 0
	s_barrier
	s_add_u32 m0, s99, 0xc000
	s_nop 0
	global_load_lds_dwordx4 v210, s[54:55]
	s_add_u32 m0, s99, 0xe000
	s_nop 0
	global_load_lds_dwordx4 v211, s[54:55]
	s_add_u32 s54, s54, 0x80
	s_addc_u32 s55, s55, 0
	s_waitcnt vmcnt(6)
	s_barrier
	s_setprio 1
	v_mfma_f32_16x16x32_bf16 v[32:35], v[128:131], v[180:183], v[32:35]
	v_mfma_f32_16x16x32_bf16 v[32:35], v[132:135], v[184:187], v[32:35]
	v_mfma_f32_16x16x32_bf16 v[36:39], v[128:131], v[188:191], v[36:39]
	v_mfma_f32_16x16x32_bf16 v[36:39], v[132:135], v[192:195], v[36:39]
	v_mfma_f32_16x16x32_bf16 v[40:43], v[136:139], v[180:183], v[40:43]
	v_mfma_f32_16x16x32_bf16 v[40:43], v[140:143], v[184:187], v[40:43]
	v_mfma_f32_16x16x32_bf16 v[44:47], v[136:139], v[188:191], v[44:47]
	v_mfma_f32_16x16x32_bf16 v[44:47], v[140:143], v[192:195], v[44:47]
	v_mfma_f32_16x16x32_bf16 v[16:19], v[144:147], v[180:183], v[16:19]
	v_mfma_f32_16x16x32_bf16 v[16:19], v[148:151], v[184:187], v[16:19]
	v_mfma_f32_16x16x32_bf16 v[20:23], v[144:147], v[188:191], v[20:23]
	v_mfma_f32_16x16x32_bf16 v[20:23], v[148:151], v[192:195], v[20:23]
	v_mfma_f32_16x16x32_bf16 v[24:27], v[152:155], v[180:183], v[24:27]
	v_mfma_f32_16x16x32_bf16 v[24:27], v[156:159], v[184:187], v[24:27]
	v_mfma_f32_16x16x32_bf16 v[28:31], v[152:155], v[188:191], v[28:31]
	v_mfma_f32_16x16x32_bf16 v[28:31], v[156:159], v[192:195], v[28:31]
	s_setprio 0
	s_barrier
	ds_read_b128 v[160:163], v198 offset:0
	ds_read_b128 v[164:167], v200 offset:0
	ds_read_b128 v[172:175], v198 offset:2048
	ds_read_b128 v[176:179], v200 offset:2048
	ds_read_b128 v[128:131], v170 offset:0
	ds_read_b128 v[132:135], v196 offset:0
	ds_read_b128 v[136:139], v170 offset:2048
	ds_read_b128 v[140:143], v196 offset:2048
	ds_read_b128 v[144:147], v170 offset:4096
	ds_read_b128 v[148:151], v196 offset:4096
	ds_read_b128 v[152:155], v170 offset:6144
	ds_read_b128 v[156:159], v196 offset:6144
	s_add_u32 m0, s99, 0x4000
	s_nop 0
	global_load_lds_dwordx4 v203, s[56:57]
	s_add_u32 m0, s99, 0x6000
	s_nop 0
	global_load_lds_dwordx4 v204, s[56:57]
	s_add_u32 s56, s56, 0x80
	s_addc_u32 s57, s57, 0
	s_waitcnt lgkmcnt(8)
	s_barrier
	s_waitcnt lgkmcnt(0)
	s_setprio 1
	v_mfma_f32_16x16x32_bf16 v[0:3], v[128:131], v[160:163], v[0:3]
	v_mfma_f32_16x16x32_bf16 v[0:3], v[132:135], v[164:167], v[0:3]
	v_mfma_f32_16x16x32_bf16 v[4:7], v[128:131], v[172:175], v[4:7]
	v_mfma_f32_16x16x32_bf16 v[4:7], v[132:135], v[176:179], v[4:7]
	v_mfma_f32_16x16x32_bf16 v[8:11], v[136:139], v[160:163], v[8:11]
	v_mfma_f32_16x16x32_bf16 v[8:11], v[140:143], v[164:167], v[8:11]
	v_mfma_f32_16x16x32_bf16 v[12:15], v[136:139], v[172:175], v[12:15]
	v_mfma_f32_16x16x32_bf16 v[12:15], v[140:143], v[176:179], v[12:15]
	v_mfma_f32_16x16x32_bf16 v[112:115], v[144:147], v[160:163], v[112:115]
	v_mfma_f32_16x16x32_bf16 v[112:115], v[148:151], v[164:167], v[112:115]
	v_mfma_f32_16x16x32_bf16 v[116:119], v[144:147], v[172:175], v[116:119]
	v_mfma_f32_16x16x32_bf16 v[116:119], v[148:151], v[176:179], v[116:119]
	v_mfma_f32_16x16x32_bf16 v[120:123], v[152:155], v[160:163], v[120:123]
	v_mfma_f32_16x16x32_bf16 v[120:123], v[156:159], v[164:167], v[120:123]
	v_mfma_f32_16x16x32_bf16 v[124:127], v[152:155], v[172:175], v[124:127]
	v_mfma_f32_16x16x32_bf16 v[124:127], v[156:159], v[176:179], v[124:127]
	s_setprio 0
	s_barrier
	ds_read_b128 v[180:183], v198 offset:16384
	ds_read_b128 v[184:187], v200 offset:16384
	ds_read_b128 v[188:191], v198 offset:18432
	ds_read_b128 v[192:195], v200 offset:18432
	s_add_u32 m0, s99, 0x18000
	s_nop 0
	global_load_lds_dwordx4 v205, s[54:55]
	s_add_u32 m0, s99, 0x1a000
	s_nop 0
	global_load_lds_dwordx4 v206, s[54:55]
	s_barrier
	s_waitcnt lgkmcnt(0)
	s_setprio 1
	v_mfma_f32_16x16x32_bf16 v[64:67], v[128:131], v[180:183], v[64:67]
	v_mfma_f32_16x16x32_bf16 v[64:67], v[132:135], v[184:187], v[64:67]
	v_mfma_f32_16x16x32_bf16 v[68:71], v[128:131], v[188:191], v[68:71]
	v_mfma_f32_16x16x32_bf16 v[68:71], v[132:135], v[192:195], v[68:71]
	v_mfma_f32_16x16x32_bf16 v[72:75], v[136:139], v[180:183], v[72:75]
	v_mfma_f32_16x16x32_bf16 v[72:75], v[140:143], v[184:187], v[72:75]
	v_mfma_f32_16x16x32_bf16 v[76:79], v[136:139], v[188:191], v[76:79]
	v_mfma_f32_16x16x32_bf16 v[76:79], v[140:143], v[192:195], v[76:79]
	v_mfma_f32_16x16x32_bf16 v[48:51], v[144:147], v[180:183], v[48:51]
	v_mfma_f32_16x16x32_bf16 v[48:51], v[148:151], v[184:187], v[48:51]
	v_mfma_f32_16x16x32_bf16 v[52:55], v[144:147], v[188:191], v[52:55]
	v_mfma_f32_16x16x32_bf16 v[52:55], v[148:151], v[192:195], v[52:55]
	v_mfma_f32_16x16x32_bf16 v[56:59], v[152:155], v[180:183], v[56:59]
	v_mfma_f32_16x16x32_bf16 v[56:59], v[156:159], v[184:187], v[56:59]
	v_mfma_f32_16x16x32_bf16 v[60:63], v[152:155], v[188:191], v[60:63]
	v_mfma_f32_16x16x32_bf16 v[60:63], v[156:159], v[192:195], v[60:63]
	s_setprio 0
	s_barrier
	ds_read_b128 v[128:131], v170 offset:16384
	ds_read_b128 v[132:135], v196 offset:16384
	ds_read_b128 v[136:139], v170 offset:18432
	ds_read_b128 v[140:143], v196 offset:18432
	ds_read_b128 v[144:147], v170 offset:20480
	ds_read_b128 v[148:151], v196 offset:20480
	ds_read_b128 v[152:155], v170 offset:22528
	ds_read_b128 v[156:159], v196 offset:22528
	s_add_u32 m0, s99, 0x10000
	s_nop 0
	global_load_lds_dwordx4 v201, s[56:57]
	s_add_u32 m0, s99, 0x12000
	s_nop 0
	global_load_lds_dwordx4 v202, s[56:57]
	s_barrier
	s_waitcnt lgkmcnt(0)
	s_setprio 1
	v_mfma_f32_16x16x32_bf16 v[96:99], v[128:131], v[160:163], v[96:99]
	v_mfma_f32_16x16x32_bf16 v[96:99], v[132:135], v[164:167], v[96:99]
	v_mfma_f32_16x16x32_bf16 v[100:103], v[128:131], v[172:175], v[100:103]
	v_mfma_f32_16x16x32_bf16 v[100:103], v[132:135], v[176:179], v[100:103]
	v_mfma_f32_16x16x32_bf16 v[104:107], v[136:139], v[160:163], v[104:107]
	v_mfma_f32_16x16x32_bf16 v[104:107], v[140:143], v[164:167], v[104:107]
	v_mfma_f32_16x16x32_bf16 v[108:111], v[136:139], v[172:175], v[108:111]
	v_mfma_f32_16x16x32_bf16 v[108:111], v[140:143], v[176:179], v[108:111]
	v_mfma_f32_16x16x32_bf16 v[80:83], v[144:147], v[160:163], v[80:83]
	v_mfma_f32_16x16x32_bf16 v[80:83], v[148:151], v[164:167], v[80:83]
	v_mfma_f32_16x16x32_bf16 v[84:87], v[144:147], v[172:175], v[84:87]
	v_mfma_f32_16x16x32_bf16 v[84:87], v[148:151], v[176:179], v[84:87]
	v_mfma_f32_16x16x32_bf16 v[88:91], v[152:155], v[160:163], v[88:91]
	v_mfma_f32_16x16x32_bf16 v[88:91], v[156:159], v[164:167], v[88:91]
	v_mfma_f32_16x16x32_bf16 v[92:95], v[152:155], v[172:175], v[92:95]
	v_mfma_f32_16x16x32_bf16 v[92:95], v[156:159], v[176:179], v[92:95]
	s_setprio 0
	s_barrier
	s_add_u32 m0, s99, 0x1c000
	s_nop 0
	global_load_lds_dwordx4 v210, s[54:55]
	s_add_u32 m0, s99, 0x1e000
	s_nop 0
	global_load_lds_dwordx4 v211, s[54:55]
	s_add_u32 s54, s54, 0x80
	s_addc_u32 s55, s55, 0
	s_waitcnt vmcnt(6)
	s_barrier
	s_setprio 1
	v_mfma_f32_16x16x32_bf16 v[32:35], v[128:131], v[180:183], v[32:35]
	v_mfma_f32_16x16x32_bf16 v[32:35], v[132:135], v[184:187], v[32:35]
	v_mfma_f32_16x16x32_bf16 v[36:39], v[128:131], v[188:191], v[36:39]
	v_mfma_f32_16x16x32_bf16 v[36:39], v[132:135], v[192:195], v[36:39]
	v_mfma_f32_16x16x32_bf16 v[40:43], v[136:139], v[180:183], v[40:43]
	v_mfma_f32_16x16x32_bf16 v[40:43], v[140:143], v[184:187], v[40:43]
	v_mfma_f32_16x16x32_bf16 v[44:47], v[136:139], v[188:191], v[44:47]
	v_mfma_f32_16x16x32_bf16 v[44:47], v[140:143], v[192:195], v[44:47]
	v_mfma_f32_16x16x32_bf16 v[16:19], v[144:147], v[180:183], v[16:19]
	v_mfma_f32_16x16x32_bf16 v[16:19], v[148:151], v[184:187], v[16:19]
	v_mfma_f32_16x16x32_bf16 v[20:23], v[144:147], v[188:191], v[20:23]
	v_mfma_f32_16x16x32_bf16 v[20:23], v[148:151], v[192:195], v[20:23]
	v_mfma_f32_16x16x32_bf16 v[24:27], v[152:155], v[180:183], v[24:27]
	v_mfma_f32_16x16x32_bf16 v[24:27], v[156:159], v[184:187], v[24:27]
	v_mfma_f32_16x16x32_bf16 v[28:31], v[152:155], v[188:191], v[28:31]
	v_mfma_f32_16x16x32_bf16 v[28:31], v[156:159], v[192:195], v[28:31]
	s_setprio 0
	s_barrier
	s_sub_u32 s101, s101, 1
	s_cmp_lg_u32 s101, 0
	s_cbranch_scc1 .Lg8_p6h_loop
	ds_read_b128 v[160:163], v197 offset:0
	ds_read_b128 v[164:167], v199 offset:0
	ds_read_b128 v[172:175], v197 offset:2048
	ds_read_b128 v[176:179], v199 offset:2048
	ds_read_b128 v[128:131], v168 offset:0
	ds_read_b128 v[132:135], v171 offset:0
	ds_read_b128 v[136:139], v168 offset:2048
	ds_read_b128 v[140:143], v171 offset:2048
	ds_read_b128 v[144:147], v168 offset:4096
	ds_read_b128 v[148:151], v171 offset:4096
	ds_read_b128 v[152:155], v168 offset:6144
	ds_read_b128 v[156:159], v171 offset:6144
	s_add_u32 m0, s99, 0x14000
	s_nop 0
	global_load_lds_dwordx4 v203, s[56:57]
	s_add_u32 m0, s99, 0x16000
	s_nop 0
	global_load_lds_dwordx4 v204, s[56:57]
	s_add_u32 s56, s56, 0x80
	s_addc_u32 s57, s57, 0
	s_barrier
	s_waitcnt lgkmcnt(0)
	s_setprio 1
	v_mfma_f32_16x16x32_bf16 v[0:3], v[128:131], v[160:163], v[0:3]
	v_mfma_f32_16x16x32_bf16 v[0:3], v[132:135], v[164:167], v[0:3]
	v_mfma_f32_16x16x32_bf16 v[4:7], v[128:131], v[172:175], v[4:7]
	v_mfma_f32_16x16x32_bf16 v[4:7], v[132:135], v[176:179], v[4:7]
	v_mfma_f32_16x16x32_bf16 v[8:11], v[136:139], v[160:163], v[8:11]
	v_mfma_f32_16x16x32_bf16 v[8:11], v[140:143], v[164:167], v[8:11]
	v_mfma_f32_16x16x32_bf16 v[12:15], v[136:139], v[172:175], v[12:15]
	v_mfma_f32_16x16x32_bf16 v[12:15], v[140:143], v[176:179], v[12:15]
	v_mfma_f32_16x16x32_bf16 v[112:115], v[144:147], v[160:163], v[112:115]
	v_mfma_f32_16x16x32_bf16 v[112:115], v[148:151], v[164:167], v[112:115]
	v_mfma_f32_16x16x32_bf16 v[116:119], v[144:147], v[172:175], v[116:119]
	v_mfma_f32_16x16x32_bf16 v[116:119], v[148:151], v[176:179], v[116:119]
	v_mfma_f32_16x16x32_bf16 v[120:123], v[152:155], v[160:163], v[120:123]
	v_mfma_f32_16x16x32_bf16 v[120:123], v[156:159], v[164:167], v[120:123]
	v_mfma_f32_16x16x32_bf16 v[124:127], v[152:155], v[172:175], v[124:127]
	v_mfma_f32_16x16x32_bf16 v[124:127], v[156:159], v[176:179], v[124:127]
	s_setprio 0
	s_barrier
	ds_read_b128 v[180:183], v197 offset:16384
	ds_read_b128 v[184:187], v199 offset:16384
	ds_read_b128 v[188:191], v197 offset:18432
	ds_read_b128 v[192:195], v199 offset:18432
	s_barrier
	s_waitcnt lgkmcnt(0)
	s_setprio 1
	v_mfma_f32_16x16x32_bf16 v[64:67], v[128:131], v[180:183], v[64:67]
	v_mfma_f32_16x16x32_bf16 v[64:67], v[132:135], v[184:187], v[64:67]
	v_mfma_f32_16x16x32_bf16 v[68:71], v[128:131], v[188:191], v[68:71]
	v_mfma_f32_16x16x32_bf16 v[68:71], v[132:135], v[192:195], v[68:71]
	v_mfma_f32_16x16x32_bf16 v[72:75], v[136:139], v[180:183], v[72:75]
	v_mfma_f32_16x16x32_bf16 v[72:75], v[140:143], v[184:187], v[72:75]
	v_mfma_f32_16x16x32_bf16 v[76:79], v[136:139], v[188:191], v[76:79]
	v_mfma_f32_16x16x32_bf16 v[76:79], v[140:143], v[192:195], v[76:79]
	v_mfma_f32_16x16x32_bf16 v[48:51], v[144:147], v[180:183], v[48:51]
	v_mfma_f32_16x16x32_bf16 v[48:51], v[148:151], v[184:187], v[48:51]
	v_mfma_f32_16x16x32_bf16 v[52:55], v[144:147], v[188:191], v[52:55]
	v_mfma_f32_16x16x32_bf16 v[52:55], v[148:151], v[192:195], v[52:55]
	v_mfma_f32_16x16x32_bf16 v[56:59], v[152:155], v[180:183], v[56:59]
	v_mfma_f32_16x16x32_bf16 v[56:59], v[156:159], v[184:187], v[56:59]
	v_mfma_f32_16x16x32_bf16 v[60:63], v[152:155], v[188:191], v[60:63]
	v_mfma_f32_16x16x32_bf16 v[60:63], v[156:159], v[192:195], v[60:63]
	s_setprio 0
	s_barrier
	ds_read_b128 v[128:131], v168 offset:16384
	ds_read_b128 v[132:135], v171 offset:16384
	ds_read_b128 v[136:139], v168 offset:18432
	ds_read_b128 v[140:143], v171 offset:18432
	ds_read_b128 v[144:147], v168 offset:20480
	ds_read_b128 v[148:151], v171 offset:20480
	ds_read_b128 v[152:155], v168 offset:22528
	ds_read_b128 v[156:159], v171 offset:22528
	s_waitcnt vmcnt(4)
	s_barrier
	s_waitcnt lgkmcnt(0)
	s_setprio 1
	v_mfma_f32_16x16x32_bf16 v[96:99], v[128:131], v[160:163], v[96:99]
	v_mfma_f32_16x16x32_bf16 v[96:99], v[132:135], v[164:167], v[96:99]
	v_mfma_f32_16x16x32_bf16 v[100:103], v[128:131], v[172:175], v[100:103]
	v_mfma_f32_16x16x32_bf16 v[100:103], v[132:135], v[176:179], v[100:103]
	v_mfma_f32_16x16x32_bf16 v[104:107], v[136:139], v[160:163], v[104:107]
	v_mfma_f32_16x16x32_bf16 v[104:107], v[140:143], v[164:167], v[104:107]
	v_mfma_f32_16x16x32_bf16 v[108:111], v[136:139], v[172:175], v[108:111]
	v_mfma_f32_16x16x32_bf16 v[108:111], v[140:143], v[176:179], v[108:111]
	v_mfma_f32_16x16x32_bf16 v[80:83], v[144:147], v[160:163], v[80:83]
	v_mfma_f32_16x16x32_bf16 v[80:83], v[148:151], v[164:167], v[80:83]
	v_mfma_f32_16x16x32_bf16 v[84:87], v[144:147], v[172:175], v[84:87]
	v_mfma_f32_16x16x32_bf16 v[84:87], v[148:151], v[176:179], v[84:87]
	v_mfma_f32_16x16x32_bf16 v[88:91], v[152:155], v[160:163], v[88:91]
	v_mfma_f32_16x16x32_bf16 v[88:91], v[156:159], v[164:167], v[88:91]
	v_mfma_f32_16x16x32_bf16 v[92:95], v[152:155], v[172:175], v[92:95]
	v_mfma_f32_16x16x32_bf16 v[92:95], v[156:159], v[176:179], v[92:95]
	s_setprio 0
	s_setprio 1
	v_mfma_f32_16x16x32_bf16 v[32:35], v[128:131], v[180:183], v[32:35]
	v_mfma_f32_16x16x32_bf16 v[32:35], v[132:135], v[184:187], v[32:35]
	v_mfma_f32_16x16x32_bf16 v[36:39], v[128:131], v[188:191], v[36:39]
	v_mfma_f32_16x16x32_bf16 v[36:39], v[132:135], v[192:195], v[36:39]
	v_mfma_f32_16x16x32_bf16 v[40:43], v[136:139], v[180:183], v[40:43]
	v_mfma_f32_16x16x32_bf16 v[40:43], v[140:143], v[184:187], v[40:43]
	v_mfma_f32_16x16x32_bf16 v[44:47], v[136:139], v[188:191], v[44:47]
	v_mfma_f32_16x16x32_bf16 v[44:47], v[140:143], v[192:195], v[44:47]
	v_mfma_f32_16x16x32_bf16 v[16:19], v[144:147], v[180:183], v[16:19]
	v_mfma_f32_16x16x32_bf16 v[16:19], v[148:151], v[184:187], v[16:19]
	v_mfma_f32_16x16x32_bf16 v[20:23], v[144:147], v[188:191], v[20:23]
	v_mfma_f32_16x16x32_bf16 v[20:23], v[148:151], v[192:195], v[20:23]
	v_mfma_f32_16x16x32_bf16 v[24:27], v[152:155], v[180:183], v[24:27]
	v_mfma_f32_16x16x32_bf16 v[24:27], v[156:159], v[184:187], v[24:27]
	v_mfma_f32_16x16x32_bf16 v[28:31], v[152:155], v[188:191], v[28:31]
	v_mfma_f32_16x16x32_bf16 v[28:31], v[156:159], v[192:195], v[28:31]
	s_setprio 0
	s_barrier
	ds_read_b128 v[160:163], v198 offset:0
	ds_read_b128 v[164:167], v200 offset:0
	ds_read_b128 v[172:175], v198 offset:2048
	ds_read_b128 v[176:179], v200 offset:2048
	ds_read_b128 v[128:131], v170 offset:0
	ds_read_b128 v[132:135], v196 offset:0
	ds_read_b128 v[136:139], v170 offset:2048
	ds_read_b128 v[140:143], v196 offset:2048
	ds_read_b128 v[144:147], v170 offset:4096
	ds_read_b128 v[148:151], v196 offset:4096
	ds_read_b128 v[152:155], v170 offset:6144
	ds_read_b128 v[156:159], v196 offset:6144
	s_waitcnt vmcnt(2)
	s_barrier
	s_waitcnt lgkmcnt(0)
	s_setprio 1
	v_mfma_f32_16x16x32_bf16 v[0:3], v[128:131], v[160:163], v[0:3]
	v_mfma_f32_16x16x32_bf16 v[0:3], v[132:135], v[164:167], v[0:3]
	v_mfma_f32_16x16x32_bf16 v[4:7], v[128:131], v[172:175], v[4:7]
	v_mfma_f32_16x16x32_bf16 v[4:7], v[132:135], v[176:179], v[4:7]
	v_mfma_f32_16x16x32_bf16 v[8:11], v[136:139], v[160:163], v[8:11]
	v_mfma_f32_16x16x32_bf16 v[8:11], v[140:143], v[164:167], v[8:11]
	v_mfma_f32_16x16x32_bf16 v[12:15], v[136:139], v[172:175], v[12:15]
	v_mfma_f32_16x16x32_bf16 v[12:15], v[140:143], v[176:179], v[12:15]
	v_mfma_f32_16x16x32_bf16 v[112:115], v[144:147], v[160:163], v[112:115]
	v_mfma_f32_16x16x32_bf16 v[112:115], v[148:151], v[164:167], v[112:115]
	v_mfma_f32_16x16x32_bf16 v[116:119], v[144:147], v[172:175], v[116:119]
	v_mfma_f32_16x16x32_bf16 v[116:119], v[148:151], v[176:179], v[116:119]
	v_mfma_f32_16x16x32_bf16 v[120:123], v[152:155], v[160:163], v[120:123]
	v_mfma_f32_16x16x32_bf16 v[120:123], v[156:159], v[164:167], v[120:123]
	v_mfma_f32_16x16x32_bf16 v[124:127], v[152:155], v[172:175], v[124:127]
	v_mfma_f32_16x16x32_bf16 v[124:127], v[156:159], v[176:179], v[124:127]
	s_setprio 0
	s_barrier
	ds_read_b128 v[180:183], v198 offset:16384
	ds_read_b128 v[184:187], v200 offset:16384
	ds_read_b128 v[188:191], v198 offset:18432
	ds_read_b128 v[192:195], v200 offset:18432
	s_waitcnt vmcnt(0)
	s_barrier
	s_waitcnt lgkmcnt(0)
	s_setprio 1
	v_mfma_f32_16x16x32_bf16 v[64:67], v[128:131], v[180:183], v[64:67]
	v_mfma_f32_16x16x32_bf16 v[64:67], v[132:135], v[184:187], v[64:67]
	v_mfma_f32_16x16x32_bf16 v[68:71], v[128:131], v[188:191], v[68:71]
	v_mfma_f32_16x16x32_bf16 v[68:71], v[132:135], v[192:195], v[68:71]
	v_mfma_f32_16x16x32_bf16 v[72:75], v[136:139], v[180:183], v[72:75]
	v_mfma_f32_16x16x32_bf16 v[72:75], v[140:143], v[184:187], v[72:75]
	v_mfma_f32_16x16x32_bf16 v[76:79], v[136:139], v[188:191], v[76:79]
	v_mfma_f32_16x16x32_bf16 v[76:79], v[140:143], v[192:195], v[76:79]
	v_mfma_f32_16x16x32_bf16 v[48:51], v[144:147], v[180:183], v[48:51]
	v_mfma_f32_16x16x32_bf16 v[48:51], v[148:151], v[184:187], v[48:51]
	v_mfma_f32_16x16x32_bf16 v[52:55], v[144:147], v[188:191], v[52:55]
	v_mfma_f32_16x16x32_bf16 v[52:55], v[148:151], v[192:195], v[52:55]
	v_mfma_f32_16x16x32_bf16 v[56:59], v[152:155], v[180:183], v[56:59]
	v_mfma_f32_16x16x32_bf16 v[56:59], v[156:159], v[184:187], v[56:59]
	v_mfma_f32_16x16x32_bf16 v[60:63], v[152:155], v[188:191], v[60:63]
	v_mfma_f32_16x16x32_bf16 v[60:63], v[156:159], v[192:195], v[60:63]
	s_setprio 0
	s_barrier
	ds_read_b128 v[128:131], v170 offset:16384
	ds_read_b128 v[132:135], v196 offset:16384
	ds_read_b128 v[136:139], v170 offset:18432
	ds_read_b128 v[140:143], v196 offset:18432
	ds_read_b128 v[144:147], v170 offset:20480
	ds_read_b128 v[148:151], v196 offset:20480
	ds_read_b128 v[152:155], v170 offset:22528
	ds_read_b128 v[156:159], v196 offset:22528
	s_barrier
	s_waitcnt lgkmcnt(0)
	s_setprio 1
	v_mfma_f32_16x16x32_bf16 v[96:99], v[128:131], v[160:163], v[96:99]
	v_mfma_f32_16x16x32_bf16 v[96:99], v[132:135], v[164:167], v[96:99]
	v_mfma_f32_16x16x32_bf16 v[100:103], v[128:131], v[172:175], v[100:103]
	v_mfma_f32_16x16x32_bf16 v[100:103], v[132:135], v[176:179], v[100:103]
	v_mfma_f32_16x16x32_bf16 v[104:107], v[136:139], v[160:163], v[104:107]
	v_mfma_f32_16x16x32_bf16 v[104:107], v[140:143], v[164:167], v[104:107]
	v_mfma_f32_16x16x32_bf16 v[108:111], v[136:139], v[172:175], v[108:111]
	v_mfma_f32_16x16x32_bf16 v[108:111], v[140:143], v[176:179], v[108:111]
	v_mfma_f32_16x16x32_bf16 v[80:83], v[144:147], v[160:163], v[80:83]
	v_mfma_f32_16x16x32_bf16 v[80:83], v[148:151], v[164:167], v[80:83]
	v_mfma_f32_16x16x32_bf16 v[84:87], v[144:147], v[172:175], v[84:87]
	v_mfma_f32_16x16x32_bf16 v[84:87], v[148:151], v[176:179], v[84:87]
	v_mfma_f32_16x16x32_bf16 v[88:91], v[152:155], v[160:163], v[88:91]
	v_mfma_f32_16x16x32_bf16 v[88:91], v[156:159], v[164:167], v[88:91]
	v_mfma_f32_16x16x32_bf16 v[92:95], v[152:155], v[172:175], v[92:95]
	v_mfma_f32_16x16x32_bf16 v[92:95], v[156:159], v[176:179], v[92:95]
	s_setprio 0
	s_setprio 1
	v_mfma_f32_16x16x32_bf16 v[32:35], v[128:131], v[180:183], v[32:35]
	v_mfma_f32_16x16x32_bf16 v[32:35], v[132:135], v[184:187], v[32:35]
	v_mfma_f32_16x16x32_bf16 v[36:39], v[128:131], v[188:191], v[36:39]
	v_mfma_f32_16x16x32_bf16 v[36:39], v[132:135], v[192:195], v[36:39]
	v_mfma_f32_16x16x32_bf16 v[40:43], v[136:139], v[180:183], v[40:43]
	v_mfma_f32_16x16x32_bf16 v[40:43], v[140:143], v[184:187], v[40:43]
	v_mfma_f32_16x16x32_bf16 v[44:47], v[136:139], v[188:191], v[44:47]
	v_mfma_f32_16x16x32_bf16 v[44:47], v[140:143], v[192:195], v[44:47]
	v_mfma_f32_16x16x32_bf16 v[16:19], v[144:147], v[180:183], v[16:19]
	v_mfma_f32_16x16x32_bf16 v[16:19], v[148:151], v[184:187], v[16:19]
	v_mfma_f32_16x16x32_bf16 v[20:23], v[144:147], v[188:191], v[20:23]
	v_mfma_f32_16x16x32_bf16 v[20:23], v[148:151], v[192:195], v[20:23]
	v_mfma_f32_16x16x32_bf16 v[24:27], v[152:155], v[180:183], v[24:27]
	v_mfma_f32_16x16x32_bf16 v[24:27], v[156:159], v[184:187], v[24:27]
	v_mfma_f32_16x16x32_bf16 v[28:31], v[152:155], v[188:191], v[28:31]
	v_mfma_f32_16x16x32_bf16 v[28:31], v[156:159], v[192:195], v[28:31]
	s_setprio 0
	s_barrier
	s_cmp_lg_u32 s100, 0
	s_cbranch_scc1 .Lg8_p6h_eg1
	s_barrier
.Lg8_p6h_eg1:
	s_nop 7
	s_nop 7
	v_permlane16_swap_b32_e32 v0, v4
	v_permlane16_swap_b32_e32 v1, v5
	v_permlane16_swap_b32_e32 v2, v6
	v_permlane16_swap_b32_e32 v3, v7
	v_permlane16_swap_b32_e32 v8, v12
	v_permlane16_swap_b32_e32 v9, v13
	v_permlane16_swap_b32_e32 v10, v14
	v_permlane16_swap_b32_e32 v11, v15
	v_permlane16_swap_b32_e32 v112, v116
	v_permlane16_swap_b32_e32 v113, v117
	v_permlane16_swap_b32_e32 v114, v118
	v_permlane16_swap_b32_e32 v115, v119
	v_permlane16_swap_b32_e32 v120, v124
	v_permlane16_swap_b32_e32 v121, v125
	v_permlane16_swap_b32_e32 v122, v126
	v_permlane16_swap_b32_e32 v123, v127
	v_permlane16_swap_b32_e32 v96, v100
	v_permlane16_swap_b32_e32 v97, v101
	v_permlane16_swap_b32_e32 v98, v102
	v_permlane16_swap_b32_e32 v99, v103
	v_permlane16_swap_b32_e32 v104, v108
	v_permlane16_swap_b32_e32 v105, v109
	v_permlane16_swap_b32_e32 v106, v110
	v_permlane16_swap_b32_e32 v107, v111
	v_permlane16_swap_b32_e32 v80, v84
	v_permlane16_swap_b32_e32 v81, v85
	v_permlane16_swap_b32_e32 v82, v86
	v_permlane16_swap_b32_e32 v83, v87
	v_permlane16_swap_b32_e32 v88, v92
	v_permlane16_swap_b32_e32 v89, v93
	v_permlane16_swap_b32_e32 v90, v94
	v_permlane16_swap_b32_e32 v91, v95
	v_permlane16_swap_b32_e32 v64, v68
	v_permlane16_swap_b32_e32 v65, v69
	v_permlane16_swap_b32_e32 v66, v70
	v_permlane16_swap_b32_e32 v67, v71
	v_permlane16_swap_b32_e32 v72, v76
	v_permlane16_swap_b32_e32 v73, v77
	v_permlane16_swap_b32_e32 v74, v78
	v_permlane16_swap_b32_e32 v75, v79
	v_permlane16_swap_b32_e32 v48, v52
	v_permlane16_swap_b32_e32 v49, v53
	v_permlane16_swap_b32_e32 v50, v54
	v_permlane16_swap_b32_e32 v51, v55
	v_permlane16_swap_b32_e32 v56, v60
	v_permlane16_swap_b32_e32 v57, v61
	v_permlane16_swap_b32_e32 v58, v62
	v_permlane16_swap_b32_e32 v59, v63
	v_permlane16_swap_b32_e32 v32, v36
	v_permlane16_swap_b32_e32 v33, v37
	v_permlane16_swap_b32_e32 v34, v38
	v_permlane16_swap_b32_e32 v35, v39
	v_permlane16_swap_b32_e32 v40, v44
	v_permlane16_swap_b32_e32 v41, v45
	v_permlane16_swap_b32_e32 v42, v46
	v_permlane16_swap_b32_e32 v43, v47
	v_permlane16_swap_b32_e32 v16, v20
	v_permlane16_swap_b32_e32 v17, v21
	v_permlane16_swap_b32_e32 v18, v22
	v_permlane16_swap_b32_e32 v19, v23
	v_permlane16_swap_b32_e32 v24, v28
	v_permlane16_swap_b32_e32 v25, v29
	v_permlane16_swap_b32_e32 v26, v30
	v_permlane16_swap_b32_e32 v27, v31
	s_nop 1
	s_ashr_i32 s54, s83, 6
	s_lshl_b32 s2, s2, 8
	s_ashr_i32 s55, s54, 31
	s_and_b32 s84, s2, 0x700
	s_lshl_b64 s[2:3], s[54:55], 21
	s_lshl_b32 s6, s58, 18
	s_or_b32 s2, s2, s6
	s_cmpk_gt_u32 s84, 0x3ff
	s_mov_b64 s[6:7], -1
	s_cbranch_scc0 .LBB0_715
	s_waitcnt vmcnt(1)
	v_mov_b32_e32 v129, v208
	s_waitcnt vmcnt(0)
	v_cvt_pk_bf16_f32 v133, v0, s0
	v_and_b32_e32 v128, 31, v129
	v_ashrrev_i32_e32 v130, 1, v129
	v_and_or_b32 v128, v130, s81, v128
	v_lshlrev_b32_e32 v130, 1, v129
	v_lshrrev_b32_e32 v129, 3, v129
	v_and_b32_e32 v129, 4, v129
	v_and_or_b32 v129, v130, s72, v129
	v_mul_lo_u32 v130, v128, s80
	v_lshlrev_b32_e32 v131, 1, v129
	v_cmp_ne_u32_e64 s[6:7], 0, v129
	v_sub_u32_e32 v132, v130, v131
	s_and_saveexec_b64 s[56:57], s[6:7]
	s_xor_b64 s[56:57], exec, s[56:57]
	ds_write_b16 v132, v133 offset:512
	s_or_saveexec_b64 s[56:57], s[56:57]
	s_lshl_b32 s86, s58, 8
	s_sub_i32 s85, 0x700, s84
	v_ashrrev_i32_e32 v129, 31, v128
	s_xor_b64 exec, exec, s[56:57]
	s_cbranch_execz .LBB0_643
	s_cmpk_lg_i32 s84, 0x400
	s_mov_b64 s[58:59], -1
	s_cbranch_scc0 .LBB0_641
	s_lshl_b64 s[58:59], s[2:3], 1
	s_add_u32 s58, s8, s58
	v_lshlrev_b64 v[134:135], 11, v[128:129]
	s_addc_u32 s59, s9, s59
	v_lshl_add_u64 v[134:135], s[58:59], 0, v[134:135]
	s_lshl_b32 s14, s85, 1
	v_lshl_add_u64 v[134:135], v[134:135], 0, s[14:15]
	global_store_short v[134:135], v133, off offset:512
	s_mov_b64 s[58:59], 0

.LBB0_840:
	s_ashr_i32 s45, s44, 31
	s_bfe_u32 s27, s56, 0x40004
	s_bfe_u32 s26, s56, 0x10003
	s_lshl_b64 s[58:59], s[44:45], 19
	s_add_u32 s18, s47, s58
	s_addc_u32 s45, s48, s59
	s_lshl_b32 s57, s26, 18
	s_add_u32 s58, s18, s57
	s_addc_u32 s59, s45, 0
	s_mov_b32 s70, s58
	s_mov_b32 s71, s59
	s_lshl_b32 s18, s56, 8
	s_and_b32 s45, s18, 0x700
	s_lshl_b32 s18, s27, 21
	s_add_u32 s2, s2, s18
	s_addc_u32 s3, s3, 0
	s_lshl_b32 s18, s45, 10
	s_add_u32 s2, s2, s18
	s_addc_u32 s3, s3, 0
	s_mov_b32 s72, s2
	s_mov_b32 s73, s3
	s_movk_i32 s2, 0x100
	s_mov_b32 s3, -2
	v_lshrrev_b32_e32 v212, 6, v208
	v_and_b32_e32 v213, 63, v208
	v_readfirstlane_b32 s98, v212
	v_and_b32_e32 v214, 3, v213
	v_bfe_u32 v215, v213, 2, 1
	v_lshl_or_b32 v214, v215, 3, v214
	v_bfe_u32 v215, v213, 3, 1
	v_lshl_or_b32 v214, v215, 2, v214
	s_and_b32 s74, s98, 1
	s_lshr_b32 s100, s98, 2
	s_lshl_b32 s99, s98, 10
	v_lshrrev_b32_e32 v215, 4, v213
	v_bfe_u32 v216, v214, 1, 3
	v_xor_b32_e32 v216, v215, v216
	v_lshlrev_b32_e32 v216, 4, v216
	v_lshl_add_u32 v214, s74, 6, v214
	v_lshl_add_u32 v168, v214, 7, v216
	v_xor_b32_e32 v171, 64, v168
	v_add_u32_e32 v170, 0x10000, v168
	v_add_u32_e32 v196, 0x10000, v171
	v_bfe_u32 v216, v213, 1, 3
	v_xor_b32_e32 v216, v215, v216
	v_lshlrev_b32_e32 v216, 4, v216
	v_and_b32_e32 v214, 15, v213
	s_lshr_b32 s101, s98, 1
	v_lshl_add_u32 v214, s101, 5, v214
	v_lshl_add_u32 v197, v214, 7, v216
	v_add_u32_e32 v197, 0x8000, v197
	v_xor_b32_e32 v199, 64, v197
	v_add_u32_e32 v198, 0x10000, v197
	v_add_u32_e32 v200, 0x10000, v199
	v_lshl_add_u32 v216, s74, 2, v215
	v_and_b32_e32 v214, 7, v213
	v_xor_b32_e32 v216, v214, v216
	v_lshlrev_b32_e32 v216, 4, v216
	v_lshrrev_b32_e32 v214, 3, v213
	v_lshl_add_u32 v215, s98, 3, v214
	v_lshl_add_u32 v201, v215, 10, v216
	v_add_u32_e32 v202, 0x20000, v201
	v_add_u32_e32 v203, 0x10000, v201
	v_add_u32_e32 v204, 0x30000, v201
	s_and_b32 s101, s98, 3
	s_lshl_b32 s101, s101, 3
	s_lshl_b32 s74, s100, 6
	s_add_u32 s101, s101, s74
	v_add_u32_e32 v215, s101, v214
	v_lshl_add_u32 v205, v215, 10, v216
	v_add_u32_e32 v206, 0x20000, v205
	v_add_u32_e32 v210, 0x8000, v205
	v_add_u32_e32 v211, 0x28000, v205
	v_mov_b32_e32 v112, 0
	v_mov_b32_e32 v113, 0
	v_mov_b32_e32 v114, 0
	v_mov_b32_e32 v115, 0
	v_mov_b32_e32 v116, 0
	v_mov_b32_e32 v117, 0
	v_mov_b32_e32 v118, 0
	v_mov_b32_e32 v119, 0
	v_mov_b32_e32 v120, 0
	v_mov_b32_e32 v121, 0
	v_mov_b32_e32 v122, 0
	v_mov_b32_e32 v123, 0
	v_mov_b32_e32 v124, 0
	v_mov_b32_e32 v125, 0
	v_mov_b32_e32 v126, 0
	v_mov_b32_e32 v127, 0
	v_mov_b32_e32 v96, 0
	v_mov_b32_e32 v97, 0
	v_mov_b32_e32 v98, 0
	v_mov_b32_e32 v99, 0
	v_mov_b32_e32 v100, 0
	v_mov_b32_e32 v101, 0
	v_mov_b32_e32 v102, 0
	v_mov_b32_e32 v103, 0
	v_mov_b32_e32 v104, 0
	v_mov_b32_e32 v105, 0
	v_mov_b32_e32 v106, 0
	v_mov_b32_e32 v107, 0
	v_mov_b32_e32 v108, 0
	v_mov_b32_e32 v109, 0
	v_mov_b32_e32 v110, 0
	v_mov_b32_e32 v111, 0
	v_mov_b32_e32 v80, 0
	v_mov_b32_e32 v81, 0
	v_mov_b32_e32 v82, 0
	v_mov_b32_e32 v83, 0
	v_mov_b32_e32 v84, 0
	v_mov_b32_e32 v85, 0
	v_mov_b32_e32 v86, 0
	v_mov_b32_e32 v87, 0
	v_mov_b32_e32 v88, 0
	v_mov_b32_e32 v89, 0
	v_mov_b32_e32 v90, 0
	v_mov_b32_e32 v91, 0
	v_mov_b32_e32 v92, 0
	v_mov_b32_e32 v93, 0
	v_mov_b32_e32 v94, 0
	v_mov_b32_e32 v95, 0
	v_mov_b32_e32 v64, 0
	v_mov_b32_e32 v65, 0
	v_mov_b32_e32 v66, 0
	v_mov_b32_e32 v67, 0
	v_mov_b32_e32 v68, 0
	v_mov_b32_e32 v69, 0
	v_mov_b32_e32 v70, 0
	v_mov_b32_e32 v71, 0
	v_mov_b32_e32 v72, 0
	v_mov_b32_e32 v73, 0
	v_mov_b32_e32 v74, 0
	v_mov_b32_e32 v75, 0
	v_mov_b32_e32 v76, 0
	v_mov_b32_e32 v77, 0
	v_mov_b32_e32 v78, 0
	v_mov_b32_e32 v79, 0
	v_mov_b32_e32 v48, 0
	v_mov_b32_e32 v49, 0
	v_mov_b32_e32 v50, 0
	v_mov_b32_e32 v51, 0
	v_mov_b32_e32 v52, 0
	v_mov_b32_e32 v53, 0
	v_mov_b32_e32 v54, 0
	v_mov_b32_e32 v55, 0
	v_mov_b32_e32 v56, 0
	v_mov_b32_e32 v57, 0
	v_mov_b32_e32 v58, 0
	v_mov_b32_e32 v59, 0
	v_mov_b32_e32 v60, 0
	v_mov_b32_e32 v61, 0
	v_mov_b32_e32 v62, 0
	v_mov_b32_e32 v63, 0
	v_mov_b32_e32 v32, 0
	v_mov_b32_e32 v33, 0
	v_mov_b32_e32 v34, 0
	v_mov_b32_e32 v35, 0
	v_mov_b32_e32 v36, 0
	v_mov_b32_e32 v37, 0
	v_mov_b32_e32 v38, 0
	v_mov_b32_e32 v39, 0
	v_mov_b32_e32 v40, 0
	v_mov_b32_e32 v41, 0
	v_mov_b32_e32 v42, 0
	v_mov_b32_e32 v43, 0
	v_mov_b32_e32 v44, 0
	v_mov_b32_e32 v45, 0
	v_mov_b32_e32 v46, 0
	v_mov_b32_e32 v47, 0
	v_mov_b32_e32 v16, 0
	v_mov_b32_e32 v17, 0
	v_mov_b32_e32 v18, 0
	v_mov_b32_e32 v19, 0
	v_mov_b32_e32 v20, 0
	v_mov_b32_e32 v21, 0
	v_mov_b32_e32 v22, 0
	v_mov_b32_e32 v23, 0
	v_mov_b32_e32 v24, 0
	v_mov_b32_e32 v25, 0
	v_mov_b32_e32 v26, 0
	v_mov_b32_e32 v27, 0
	v_mov_b32_e32 v28, 0
	v_mov_b32_e32 v29, 0
	v_mov_b32_e32 v30, 0
	v_mov_b32_e32 v31, 0
	v_mov_b32_e32 v0, 0
	v_mov_b32_e32 v1, 0
	v_mov_b32_e32 v2, 0
	v_mov_b32_e32 v3, 0
	v_mov_b32_e32 v4, 0
	v_mov_b32_e32 v5, 0
	v_mov_b32_e32 v6, 0
	v_mov_b32_e32 v7, 0
	v_mov_b32_e32 v8, 0
	v_mov_b32_e32 v9, 0
	v_mov_b32_e32 v10, 0
	v_mov_b32_e32 v11, 0
	v_mov_b32_e32 v12, 0
	v_mov_b32_e32 v13, 0
	v_mov_b32_e32 v14, 0
	v_mov_b32_e32 v15, 0
	s_add_u32 m0, s99, 0x8000
	s_nop 0
	global_load_lds_dwordx4 v205, s[70:71]
	s_add_u32 m0, s99, 0xa000
	s_nop 0
	global_load_lds_dwordx4 v206, s[70:71]
	s_add_u32 m0, s99, 0x0
	s_nop 0
	global_load_lds_dwordx4 v201, s[72:73]
	s_add_u32 m0, s99, 0x2000
	s_nop 0
	global_load_lds_dwordx4 v202, s[72:73]
	s_add_u32 m0, s99, 0xc000
	s_nop 0
	global_load_lds_dwordx4 v210, s[70:71]
	s_add_u32 m0, s99, 0xe000
	s_nop 0
	global_load_lds_dwordx4 v211, s[70:71]
	s_add_u32 s70, s70, 0x80
	s_addc_u32 s71, s71, 0
	s_add_u32 m0, s99, 0x4000
	s_nop 0
	global_load_lds_dwordx4 v203, s[72:73]
	s_add_u32 m0, s99, 0x6000
	s_nop 0
	global_load_lds_dwordx4 v204, s[72:73]
	s_add_u32 s72, s72, 0x80
	s_addc_u32 s73, s73, 0
	s_cmp_eq_u32 s100, 0
	s_cbranch_scc1 .Lg8_p7_pg0
	s_barrier
.Lg8_p7_pg0:
	s_waitcnt vmcnt(4)
	s_barrier
	s_add_u32 m0, s99, 0x18000
	s_nop 0
	global_load_lds_dwordx4 v205, s[70:71]
	s_add_u32 m0, s99, 0x1a000
	s_nop 0
	global_load_lds_dwordx4 v206, s[70:71]
	s_add_u32 m0, s99, 0x10000
	s_nop 0
	global_load_lds_dwordx4 v201, s[72:73]
	s_add_u32 m0, s99, 0x12000
	s_nop 0
	global_load_lds_dwordx4 v202, s[72:73]
	s_add_u32 m0, s99, 0x1c000
	s_nop 0
	global_load_lds_dwordx4 v210, s[70:71]
	s_add_u32 m0, s99, 0x1e000
	s_nop 0
	global_load_lds_dwordx4 v211, s[70:71]
	s_add_u32 s70, s70, 0x80
	s_addc_u32 s71, s71, 0
	s_waitcnt vmcnt(6)
	s_barrier
	s_mov_b32 s101, 3
.Lg8_p7_loop:
	ds_read_b128 v[160:163], v197 offset:0
	ds_read_b128 v[164:167], v199 offset:0
	ds_read_b128 v[172:175], v197 offset:2048
	ds_read_b128 v[176:179], v199 offset:2048
	ds_read_b128 v[128:131], v168 offset:0
	ds_read_b128 v[132:135], v171 offset:0
	ds_read_b128 v[136:139], v168 offset:2048
	ds_read_b128 v[140:143], v171 offset:2048
	ds_read_b128 v[144:147], v168 offset:4096
	ds_read_b128 v[148:151], v171 offset:4096
	ds_read_b128 v[152:155], v168 offset:6144
	ds_read_b128 v[156:159], v171 offset:6144
	s_add_u32 m0, s99, 0x14000
	s_nop 0
	global_load_lds_dwordx4 v203, s[72:73]
	s_add_u32 m0, s99, 0x16000
	s_nop 0
	global_load_lds_dwordx4 v204, s[72:73]
	s_add_u32 s72, s72, 0x80
	s_addc_u32 s73, s73, 0
	s_waitcnt lgkmcnt(8)
	s_barrier
	s_waitcnt lgkmcnt(0)
	s_setprio 1
	v_mfma_f32_16x16x32_bf16 v[112:115], v[128:131], v[160:163], v[112:115]
	v_mfma_f32_16x16x32_bf16 v[112:115], v[132:135], v[164:167], v[112:115]
	v_mfma_f32_16x16x32_bf16 v[116:119], v[128:131], v[172:175], v[116:119]
	v_mfma_f32_16x16x32_bf16 v[116:119], v[132:135], v[176:179], v[116:119]
	v_mfma_f32_16x16x32_bf16 v[120:123], v[136:139], v[160:163], v[120:123]
	v_mfma_f32_16x16x32_bf16 v[120:123], v[140:143], v[164:167], v[120:123]
	v_mfma_f32_16x16x32_bf16 v[124:127], v[136:139], v[172:175], v[124:127]
	v_mfma_f32_16x16x32_bf16 v[124:127], v[140:143], v[176:179], v[124:127]
	v_mfma_f32_16x16x32_bf16 v[96:99], v[144:147], v[160:163], v[96:99]
	v_mfma_f32_16x16x32_bf16 v[96:99], v[148:151], v[164:167], v[96:99]
	v_mfma_f32_16x16x32_bf16 v[100:103], v[144:147], v[172:175], v[100:103]
	v_mfma_f32_16x16x32_bf16 v[100:103], v[148:151], v[176:179], v[100:103]
	v_mfma_f32_16x16x32_bf16 v[104:107], v[152:155], v[160:163], v[104:107]
	v_mfma_f32_16x16x32_bf16 v[104:107], v[156:159], v[164:167], v[104:107]
	v_mfma_f32_16x16x32_bf16 v[108:111], v[152:155], v[172:175], v[108:111]
	v_mfma_f32_16x16x32_bf16 v[108:111], v[156:159], v[176:179], v[108:111]
	s_setprio 0
	s_barrier
	ds_read_b128 v[180:183], v197 offset:16384
	ds_read_b128 v[184:187], v199 offset:16384
	ds_read_b128 v[188:191], v197 offset:18432
	ds_read_b128 v[192:195], v199 offset:18432
	s_add_u32 m0, s99, 0x8000
	s_nop 0
	global_load_lds_dwordx4 v205, s[70:71]
	s_add_u32 m0, s99, 0xa000
	s_nop 0
	global_load_lds_dwordx4 v206, s[70:71]
	s_barrier
	s_waitcnt lgkmcnt(0)
	s_setprio 1
	v_mfma_f32_16x16x32_bf16 v[48:51], v[128:131], v[180:183], v[48:51]
	v_mfma_f32_16x16x32_bf16 v[48:51], v[132:135], v[184:187], v[48:51]
	v_mfma_f32_16x16x32_bf16 v[52:55], v[128:131], v[188:191], v[52:55]
	v_mfma_f32_16x16x32_bf16 v[52:55], v[132:135], v[192:195], v[52:55]
	v_mfma_f32_16x16x32_bf16 v[56:59], v[136:139], v[180:183], v[56:59]
	v_mfma_f32_16x16x32_bf16 v[56:59], v[140:143], v[184:187], v[56:59]
	v_mfma_f32_16x16x32_bf16 v[60:63], v[136:139], v[188:191], v[60:63]
	v_mfma_f32_16x16x32_bf16 v[60:63], v[140:143], v[192:195], v[60:63]
	v_mfma_f32_16x16x32_bf16 v[32:35], v[144:147], v[180:183], v[32:35]
	v_mfma_f32_16x16x32_bf16 v[32:35], v[148:151], v[184:187], v[32:35]
	v_mfma_f32_16x16x32_bf16 v[36:39], v[144:147], v[188:191], v[36:39]
	v_mfma_f32_16x16x32_bf16 v[36:39], v[148:151], v[192:195], v[36:39]
	v_mfma_f32_16x16x32_bf16 v[40:43], v[152:155], v[180:183], v[40:43]
	v_mfma_f32_16x16x32_bf16 v[40:43], v[156:159], v[184:187], v[40:43]
	v_mfma_f32_16x16x32_bf16 v[44:47], v[152:155], v[188:191], v[44:47]
	v_mfma_f32_16x16x32_bf16 v[44:47], v[156:159], v[192:195], v[44:47]
	s_setprio 0
	s_barrier
	ds_read_b128 v[128:131], v168 offset:16384
	ds_read_b128 v[132:135], v171 offset:16384
	ds_read_b128 v[136:139], v168 offset:18432
	ds_read_b128 v[140:143], v171 offset:18432
	ds_read_b128 v[144:147], v168 offset:20480
	ds_read_b128 v[148:151], v171 offset:20480
	ds_read_b128 v[152:155], v168 offset:22528
	ds_read_b128 v[156:159], v171 offset:22528
	s_add_u32 m0, s99, 0x0
	s_nop 0
	global_load_lds_dwordx4 v201, s[72:73]
	s_add_u32 m0, s99, 0x2000
	s_nop 0
	global_load_lds_dwordx4 v202, s[72:73]
	s_barrier
	s_waitcnt lgkmcnt(0)
	s_setprio 1
	v_mfma_f32_16x16x32_bf16 v[80:83], v[128:131], v[160:163], v[80:83]
	v_mfma_f32_16x16x32_bf16 v[80:83], v[132:135], v[164:167], v[80:83]
	v_mfma_f32_16x16x32_bf16 v[84:87], v[128:131], v[172:175], v[84:87]
	v_mfma_f32_16x16x32_bf16 v[84:87], v[132:135], v[176:179], v[84:87]
	v_mfma_f32_16x16x32_bf16 v[88:91], v[136:139], v[160:163], v[88:91]
	v_mfma_f32_16x16x32_bf16 v[88:91], v[140:143], v[164:167], v[88:91]
	v_mfma_f32_16x16x32_bf16 v[92:95], v[136:139], v[172:175], v[92:95]
	v_mfma_f32_16x16x32_bf16 v[92:95], v[140:143], v[176:179], v[92:95]
	v_mfma_f32_16x16x32_bf16 v[64:67], v[144:147], v[160:163], v[64:67]
	v_mfma_f32_16x16x32_bf16 v[64:67], v[148:151], v[164:167], v[64:67]
	v_mfma_f32_16x16x32_bf16 v[68:71], v[144:147], v[172:175], v[68:71]
	v_mfma_f32_16x16x32_bf16 v[68:71], v[148:151], v[176:179], v[68:71]
	v_mfma_f32_16x16x32_bf16 v[72:75], v[152:155], v[160:163], v[72:75]
	v_mfma_f32_16x16x32_bf16 v[72:75], v[156:159], v[164:167], v[72:75]
	v_mfma_f32_16x16x32_bf16 v[76:79], v[152:155], v[172:175], v[76:79]
	v_mfma_f32_16x16x32_bf16 v[76:79], v[156:159], v[176:179], v[76:79]
	s_setprio 0
	s_barrier
	s_add_u32 m0, s99, 0xc000
	s_nop 0
	global_load_lds_dwordx4 v210, s[70:71]
	s_add_u32 m0, s99, 0xe000
	s_nop 0
	global_load_lds_dwordx4 v211, s[70:71]
	s_add_u32 s70, s70, 0x80
	s_addc_u32 s71, s71, 0
	s_waitcnt vmcnt(6)
	s_barrier
	s_setprio 1
	v_mfma_f32_16x16x32_bf16 v[16:19], v[128:131], v[180:183], v[16:19]
	v_mfma_f32_16x16x32_bf16 v[16:19], v[132:135], v[184:187], v[16:19]
	v_mfma_f32_16x16x32_bf16 v[20:23], v[128:131], v[188:191], v[20:23]
	v_mfma_f32_16x16x32_bf16 v[20:23], v[132:135], v[192:195], v[20:23]
	v_mfma_f32_16x16x32_bf16 v[24:27], v[136:139], v[180:183], v[24:27]
	v_mfma_f32_16x16x32_bf16 v[24:27], v[140:143], v[184:187], v[24:27]
	v_mfma_f32_16x16x32_bf16 v[28:31], v[136:139], v[188:191], v[28:31]
	v_mfma_f32_16x16x32_bf16 v[28:31], v[140:143], v[192:195], v[28:31]
	v_mfma_f32_16x16x32_bf16 v[0:3], v[144:147], v[180:183], v[0:3]
	v_mfma_f32_16x16x32_bf16 v[0:3], v[148:151], v[184:187], v[0:3]
	v_mfma_f32_16x16x32_bf16 v[4:7], v[144:147], v[188:191], v[4:7]
	v_mfma_f32_16x16x32_bf16 v[4:7], v[148:151], v[192:195], v[4:7]
	v_mfma_f32_16x16x32_bf16 v[8:11], v[152:155], v[180:183], v[8:11]
	v_mfma_f32_16x16x32_bf16 v[8:11], v[156:159], v[184:187], v[8:11]
	v_mfma_f32_16x16x32_bf16 v[12:15], v[152:155], v[188:191], v[12:15]
	v_mfma_f32_16x16x32_bf16 v[12:15], v[156:159], v[192:195], v[12:15]
	s_setprio 0
	s_barrier
	ds_read_b128 v[160:163], v198 offset:0
	ds_read_b128 v[164:167], v200 offset:0
	ds_read_b128 v[172:175], v198 offset:2048
	ds_read_b128 v[176:179], v200 offset:2048
	ds_read_b128 v[128:131], v170 offset:0
	ds_read_b128 v[132:135], v196 offset:0
	ds_read_b128 v[136:139], v170 offset:2048
	ds_read_b128 v[140:143], v196 offset:2048
	ds_read_b128 v[144:147], v170 offset:4096
	ds_read_b128 v[148:151], v196 offset:4096
	ds_read_b128 v[152:155], v170 offset:6144
	ds_read_b128 v[156:159], v196 offset:6144
	s_add_u32 m0, s99, 0x4000
	s_nop 0
	global_load_lds_dwordx4 v203, s[72:73]
	s_add_u32 m0, s99, 0x6000
	s_nop 0
	global_load_lds_dwordx4 v204, s[72:73]
	s_add_u32 s72, s72, 0x80
	s_addc_u32 s73, s73, 0
	s_waitcnt lgkmcnt(8)
	s_barrier
	s_waitcnt lgkmcnt(0)
	s_setprio 1
	v_mfma_f32_16x16x32_bf16 v[112:115], v[128:131], v[160:163], v[112:115]
	v_mfma_f32_16x16x32_bf16 v[112:115], v[132:135], v[164:167], v[112:115]
	v_mfma_f32_16x16x32_bf16 v[116:119], v[128:131], v[172:175], v[116:119]
	v_mfma_f32_16x16x32_bf16 v[116:119], v[132:135], v[176:179], v[116:119]
	v_mfma_f32_16x16x32_bf16 v[120:123], v[136:139], v[160:163], v[120:123]
	v_mfma_f32_16x16x32_bf16 v[120:123], v[140:143], v[164:167], v[120:123]
	v_mfma_f32_16x16x32_bf16 v[124:127], v[136:139], v[172:175], v[124:127]
	v_mfma_f32_16x16x32_bf16 v[124:127], v[140:143], v[176:179], v[124:127]
	v_mfma_f32_16x16x32_bf16 v[96:99], v[144:147], v[160:163], v[96:99]
	v_mfma_f32_16x16x32_bf16 v[96:99], v[148:151], v[164:167], v[96:99]
	v_mfma_f32_16x16x32_bf16 v[100:103], v[144:147], v[172:175], v[100:103]
	v_mfma_f32_16x16x32_bf16 v[100:103], v[148:151], v[176:179], v[100:103]
	v_mfma_f32_16x16x32_bf16 v[104:107], v[152:155], v[160:163], v[104:107]
	v_mfma_f32_16x16x32_bf16 v[104:107], v[156:159], v[164:167], v[104:107]
	v_mfma_f32_16x16x32_bf16 v[108:111], v[152:155], v[172:175], v[108:111]
	v_mfma_f32_16x16x32_bf16 v[108:111], v[156:159], v[176:179], v[108:111]
	s_setprio 0
	s_barrier
	ds_read_b128 v[180:183], v198 offset:16384
	ds_read_b128 v[184:187], v200 offset:16384
	ds_read_b128 v[188:191], v198 offset:18432
	ds_read_b128 v[192:195], v200 offset:18432
	s_add_u32 m0, s99, 0x18000
	s_nop 0
	global_load_lds_dwordx4 v205, s[70:71]
	s_add_u32 m0, s99, 0x1a000
	s_nop 0
	global_load_lds_dwordx4 v206, s[70:71]
	s_barrier
	s_waitcnt lgkmcnt(0)
	s_setprio 1
	v_mfma_f32_16x16x32_bf16 v[48:51], v[128:131], v[180:183], v[48:51]
	v_mfma_f32_16x16x32_bf16 v[48:51], v[132:135], v[184:187], v[48:51]
	v_mfma_f32_16x16x32_bf16 v[52:55], v[128:131], v[188:191], v[52:55]
	v_mfma_f32_16x16x32_bf16 v[52:55], v[132:135], v[192:195], v[52:55]
	v_mfma_f32_16x16x32_bf16 v[56:59], v[136:139], v[180:183], v[56:59]
	v_mfma_f32_16x16x32_bf16 v[56:59], v[140:143], v[184:187], v[56:59]
	v_mfma_f32_16x16x32_bf16 v[60:63], v[136:139], v[188:191], v[60:63]
	v_mfma_f32_16x16x32_bf16 v[60:63], v[140:143], v[192:195], v[60:63]
	v_mfma_f32_16x16x32_bf16 v[32:35], v[144:147], v[180:183], v[32:35]
	v_mfma_f32_16x16x32_bf16 v[32:35], v[148:151], v[184:187], v[32:35]
	v_mfma_f32_16x16x32_bf16 v[36:39], v[144:147], v[188:191], v[36:39]
	v_mfma_f32_16x16x32_bf16 v[36:39], v[148:151], v[192:195], v[36:39]
	v_mfma_f32_16x16x32_bf16 v[40:43], v[152:155], v[180:183], v[40:43]
	v_mfma_f32_16x16x32_bf16 v[40:43], v[156:159], v[184:187], v[40:43]
	v_mfma_f32_16x16x32_bf16 v[44:47], v[152:155], v[188:191], v[44:47]
	v_mfma_f32_16x16x32_bf16 v[44:47], v[156:159], v[192:195], v[44:47]
	s_setprio 0
	s_barrier
	ds_read_b128 v[128:131], v170 offset:16384
	ds_read_b128 v[132:135], v196 offset:16384
	ds_read_b128 v[136:139], v170 offset:18432
	ds_read_b128 v[140:143], v196 offset:18432
	ds_read_b128 v[144:147], v170 offset:20480
	ds_read_b128 v[148:151], v196 offset:20480
	ds_read_b128 v[152:155], v170 offset:22528
	ds_read_b128 v[156:159], v196 offset:22528
	s_add_u32 m0, s99, 0x10000
	s_nop 0
	global_load_lds_dwordx4 v201, s[72:73]
	s_add_u32 m0, s99, 0x12000
	s_nop 0
	global_load_lds_dwordx4 v202, s[72:73]
	s_barrier
	s_waitcnt lgkmcnt(0)
	s_setprio 1
	v_mfma_f32_16x16x32_bf16 v[80:83], v[128:131], v[160:163], v[80:83]
	v_mfma_f32_16x16x32_bf16 v[80:83], v[132:135], v[164:167], v[80:83]
	v_mfma_f32_16x16x32_bf16 v[84:87], v[128:131], v[172:175], v[84:87]
	v_mfma_f32_16x16x32_bf16 v[84:87], v[132:135], v[176:179], v[84:87]
	v_mfma_f32_16x16x32_bf16 v[88:91], v[136:139], v[160:163], v[88:91]
	v_mfma_f32_16x16x32_bf16 v[88:91], v[140:143], v[164:167], v[88:91]
	v_mfma_f32_16x16x32_bf16 v[92:95], v[136:139], v[172:175], v[92:95]
	v_mfma_f32_16x16x32_bf16 v[92:95], v[140:143], v[176:179], v[92:95]
	v_mfma_f32_16x16x32_bf16 v[64:67], v[144:147], v[160:163], v[64:67]
	v_mfma_f32_16x16x32_bf16 v[64:67], v[148:151], v[164:167], v[64:67]
	v_mfma_f32_16x16x32_bf16 v[68:71], v[144:147], v[172:175], v[68:71]
	v_mfma_f32_16x16x32_bf16 v[68:71], v[148:151], v[176:179], v[68:71]
	v_mfma_f32_16x16x32_bf16 v[72:75], v[152:155], v[160:163], v[72:75]
	v_mfma_f32_16x16x32_bf16 v[72:75], v[156:159], v[164:167], v[72:75]
	v_mfma_f32_16x16x32_bf16 v[76:79], v[152:155], v[172:175], v[76:79]
	v_mfma_f32_16x16x32_bf16 v[76:79], v[156:159], v[176:179], v[76:79]
	s_setprio 0
	s_barrier
	s_add_u32 m0, s99, 0x1c000
	s_nop 0
	global_load_lds_dwordx4 v210, s[70:71]
	s_add_u32 m0, s99, 0x1e000
	s_nop 0
	global_load_lds_dwordx4 v211, s[70:71]
	s_add_u32 s70, s70, 0x80
	s_addc_u32 s71, s71, 0
	s_waitcnt vmcnt(6)
	s_barrier
	s_setprio 1
	v_mfma_f32_16x16x32_bf16 v[16:19], v[128:131], v[180:183], v[16:19]
	v_mfma_f32_16x16x32_bf16 v[16:19], v[132:135], v[184:187], v[16:19]
	v_mfma_f32_16x16x32_bf16 v[20:23], v[128:131], v[188:191], v[20:23]
	v_mfma_f32_16x16x32_bf16 v[20:23], v[132:135], v[192:195], v[20:23]
	v_mfma_f32_16x16x32_bf16 v[24:27], v[136:139], v[180:183], v[24:27]
	v_mfma_f32_16x16x32_bf16 v[24:27], v[140:143], v[184:187], v[24:27]
	v_mfma_f32_16x16x32_bf16 v[28:31], v[136:139], v[188:191], v[28:31]
	v_mfma_f32_16x16x32_bf16 v[28:31], v[140:143], v[192:195], v[28:31]
	v_mfma_f32_16x16x32_bf16 v[0:3], v[144:147], v[180:183], v[0:3]
	v_mfma_f32_16x16x32_bf16 v[0:3], v[148:151], v[184:187], v[0:3]
	v_mfma_f32_16x16x32_bf16 v[4:7], v[144:147], v[188:191], v[4:7]
	v_mfma_f32_16x16x32_bf16 v[4:7], v[148:151], v[192:195], v[4:7]
	v_mfma_f32_16x16x32_bf16 v[8:11], v[152:155], v[180:183], v[8:11]
	v_mfma_f32_16x16x32_bf16 v[8:11], v[156:159], v[184:187], v[8:11]
	v_mfma_f32_16x16x32_bf16 v[12:15], v[152:155], v[188:191], v[12:15]
	v_mfma_f32_16x16x32_bf16 v[12:15], v[156:159], v[192:195], v[12:15]
	s_setprio 0
	s_barrier
	s_sub_u32 s101, s101, 1
	s_cmp_lg_u32 s101, 0
	s_cbranch_scc1 .Lg8_p7_loop
	ds_read_b128 v[160:163], v197 offset:0
	ds_read_b128 v[164:167], v199 offset:0
	ds_read_b128 v[172:175], v197 offset:2048
	ds_read_b128 v[176:179], v199 offset:2048
	ds_read_b128 v[128:131], v168 offset:0
	ds_read_b128 v[132:135], v171 offset:0
	ds_read_b128 v[136:139], v168 offset:2048
	ds_read_b128 v[140:143], v171 offset:2048
	ds_read_b128 v[144:147], v168 offset:4096
	ds_read_b128 v[148:151], v171 offset:4096
	ds_read_b128 v[152:155], v168 offset:6144
	ds_read_b128 v[156:159], v171 offset:6144
	s_add_u32 m0, s99, 0x14000
	s_nop 0
	global_load_lds_dwordx4 v203, s[72:73]
	s_add_u32 m0, s99, 0x16000
	s_nop 0
	global_load_lds_dwordx4 v204, s[72:73]
	s_add_u32 s72, s72, 0x80
	s_addc_u32 s73, s73, 0
	s_barrier
	s_waitcnt lgkmcnt(0)
	s_setprio 1
	v_mfma_f32_16x16x32_bf16 v[112:115], v[128:131], v[160:163], v[112:115]
	v_mfma_f32_16x16x32_bf16 v[112:115], v[132:135], v[164:167], v[112:115]
	v_mfma_f32_16x16x32_bf16 v[116:119], v[128:131], v[172:175], v[116:119]
	v_mfma_f32_16x16x32_bf16 v[116:119], v[132:135], v[176:179], v[116:119]
	v_mfma_f32_16x16x32_bf16 v[120:123], v[136:139], v[160:163], v[120:123]
	v_mfma_f32_16x16x32_bf16 v[120:123], v[140:143], v[164:167], v[120:123]
	v_mfma_f32_16x16x32_bf16 v[124:127], v[136:139], v[172:175], v[124:127]
	v_mfma_f32_16x16x32_bf16 v[124:127], v[140:143], v[176:179], v[124:127]
	v_mfma_f32_16x16x32_bf16 v[96:99], v[144:147], v[160:163], v[96:99]
	v_mfma_f32_16x16x32_bf16 v[96:99], v[148:151], v[164:167], v[96:99]
	v_mfma_f32_16x16x32_bf16 v[100:103], v[144:147], v[172:175], v[100:103]
	v_mfma_f32_16x16x32_bf16 v[100:103], v[148:151], v[176:179], v[100:103]
	v_mfma_f32_16x16x32_bf16 v[104:107], v[152:155], v[160:163], v[104:107]
	v_mfma_f32_16x16x32_bf16 v[104:107], v[156:159], v[164:167], v[104:107]
	v_mfma_f32_16x16x32_bf16 v[108:111], v[152:155], v[172:175], v[108:111]
	v_mfma_f32_16x16x32_bf16 v[108:111], v[156:159], v[176:179], v[108:111]
	s_setprio 0
	s_barrier
	ds_read_b128 v[180:183], v197 offset:16384
	ds_read_b128 v[184:187], v199 offset:16384
	ds_read_b128 v[188:191], v197 offset:18432
	ds_read_b128 v[192:195], v199 offset:18432
	s_barrier
	s_waitcnt lgkmcnt(0)
	s_setprio 1
	v_mfma_f32_16x16x32_bf16 v[48:51], v[128:131], v[180:183], v[48:51]
	v_mfma_f32_16x16x32_bf16 v[48:51], v[132:135], v[184:187], v[48:51]
	v_mfma_f32_16x16x32_bf16 v[52:55], v[128:131], v[188:191], v[52:55]
	v_mfma_f32_16x16x32_bf16 v[52:55], v[132:135], v[192:195], v[52:55]
	v_mfma_f32_16x16x32_bf16 v[56:59], v[136:139], v[180:183], v[56:59]
	v_mfma_f32_16x16x32_bf16 v[56:59], v[140:143], v[184:187], v[56:59]
	v_mfma_f32_16x16x32_bf16 v[60:63], v[136:139], v[188:191], v[60:63]
	v_mfma_f32_16x16x32_bf16 v[60:63], v[140:143], v[192:195], v[60:63]
	v_mfma_f32_16x16x32_bf16 v[32:35], v[144:147], v[180:183], v[32:35]
	v_mfma_f32_16x16x32_bf16 v[32:35], v[148:151], v[184:187], v[32:35]
	v_mfma_f32_16x16x32_bf16 v[36:39], v[144:147], v[188:191], v[36:39]
	v_mfma_f32_16x16x32_bf16 v[36:39], v[148:151], v[192:195], v[36:39]
	v_mfma_f32_16x16x32_bf16 v[40:43], v[152:155], v[180:183], v[40:43]
	v_mfma_f32_16x16x32_bf16 v[40:43], v[156:159], v[184:187], v[40:43]
	v_mfma_f32_16x16x32_bf16 v[44:47], v[152:155], v[188:191], v[44:47]
	v_mfma_f32_16x16x32_bf16 v[44:47], v[156:159], v[192:195], v[44:47]
	s_setprio 0
	s_barrier
	ds_read_b128 v[128:131], v168 offset:16384
	ds_read_b128 v[132:135], v171 offset:16384
	ds_read_b128 v[136:139], v168 offset:18432
	ds_read_b128 v[140:143], v171 offset:18432
	ds_read_b128 v[144:147], v168 offset:20480
	ds_read_b128 v[148:151], v171 offset:20480
	ds_read_b128 v[152:155], v168 offset:22528
	ds_read_b128 v[156:159], v171 offset:22528
	s_waitcnt vmcnt(4)
	s_barrier
	s_waitcnt lgkmcnt(0)
	s_setprio 1
	v_mfma_f32_16x16x32_bf16 v[80:83], v[128:131], v[160:163], v[80:83]
	v_mfma_f32_16x16x32_bf16 v[80:83], v[132:135], v[164:167], v[80:83]
	v_mfma_f32_16x16x32_bf16 v[84:87], v[128:131], v[172:175], v[84:87]
	v_mfma_f32_16x16x32_bf16 v[84:87], v[132:135], v[176:179], v[84:87]
	v_mfma_f32_16x16x32_bf16 v[88:91], v[136:139], v[160:163], v[88:91]
	v_mfma_f32_16x16x32_bf16 v[88:91], v[140:143], v[164:167], v[88:91]
	v_mfma_f32_16x16x32_bf16 v[92:95], v[136:139], v[172:175], v[92:95]
	v_mfma_f32_16x16x32_bf16 v[92:95], v[140:143], v[176:179], v[92:95]
	v_mfma_f32_16x16x32_bf16 v[64:67], v[144:147], v[160:163], v[64:67]
	v_mfma_f32_16x16x32_bf16 v[64:67], v[148:151], v[164:167], v[64:67]
	v_mfma_f32_16x16x32_bf16 v[68:71], v[144:147], v[172:175], v[68:71]
	v_mfma_f32_16x16x32_bf16 v[68:71], v[148:151], v[176:179], v[68:71]
	v_mfma_f32_16x16x32_bf16 v[72:75], v[152:155], v[160:163], v[72:75]
	v_mfma_f32_16x16x32_bf16 v[72:75], v[156:159], v[164:167], v[72:75]
	v_mfma_f32_16x16x32_bf16 v[76:79], v[152:155], v[172:175], v[76:79]
	v_mfma_f32_16x16x32_bf16 v[76:79], v[156:159], v[176:179], v[76:79]
	s_setprio 0
	s_setprio 1
	v_mfma_f32_16x16x32_bf16 v[16:19], v[128:131], v[180:183], v[16:19]
	v_mfma_f32_16x16x32_bf16 v[16:19], v[132:135], v[184:187], v[16:19]
	v_mfma_f32_16x16x32_bf16 v[20:23], v[128:131], v[188:191], v[20:23]
	v_mfma_f32_16x16x32_bf16 v[20:23], v[132:135], v[192:195], v[20:23]
	v_mfma_f32_16x16x32_bf16 v[24:27], v[136:139], v[180:183], v[24:27]
	v_mfma_f32_16x16x32_bf16 v[24:27], v[140:143], v[184:187], v[24:27]
	v_mfma_f32_16x16x32_bf16 v[28:31], v[136:139], v[188:191], v[28:31]
	v_mfma_f32_16x16x32_bf16 v[28:31], v[140:143], v[192:195], v[28:31]
	v_mfma_f32_16x16x32_bf16 v[0:3], v[144:147], v[180:183], v[0:3]
	v_mfma_f32_16x16x32_bf16 v[0:3], v[148:151], v[184:187], v[0:3]
	v_mfma_f32_16x16x32_bf16 v[4:7], v[144:147], v[188:191], v[4:7]
	v_mfma_f32_16x16x32_bf16 v[4:7], v[148:151], v[192:195], v[4:7]
	v_mfma_f32_16x16x32_bf16 v[8:11], v[152:155], v[180:183], v[8:11]
	v_mfma_f32_16x16x32_bf16 v[8:11], v[156:159], v[184:187], v[8:11]
	v_mfma_f32_16x16x32_bf16 v[12:15], v[152:155], v[188:191], v[12:15]
	v_mfma_f32_16x16x32_bf16 v[12:15], v[156:159], v[192:195], v[12:15]
	s_setprio 0
	s_barrier
	ds_read_b128 v[160:163], v198 offset:0
	ds_read_b128 v[164:167], v200 offset:0
	ds_read_b128 v[172:175], v198 offset:2048
	ds_read_b128 v[176:179], v200 offset:2048
	ds_read_b128 v[128:131], v170 offset:0
	ds_read_b128 v[132:135], v196 offset:0
	ds_read_b128 v[136:139], v170 offset:2048
	ds_read_b128 v[140:143], v196 offset:2048
	ds_read_b128 v[144:147], v170 offset:4096
	ds_read_b128 v[148:151], v196 offset:4096
	ds_read_b128 v[152:155], v170 offset:6144
	ds_read_b128 v[156:159], v196 offset:6144
	s_waitcnt vmcnt(2)
	s_barrier
	s_waitcnt lgkmcnt(0)
	s_setprio 1
	v_mfma_f32_16x16x32_bf16 v[112:115], v[128:131], v[160:163], v[112:115]
	v_mfma_f32_16x16x32_bf16 v[112:115], v[132:135], v[164:167], v[112:115]
	v_mfma_f32_16x16x32_bf16 v[116:119], v[128:131], v[172:175], v[116:119]
	v_mfma_f32_16x16x32_bf16 v[116:119], v[132:135], v[176:179], v[116:119]
	v_mfma_f32_16x16x32_bf16 v[120:123], v[136:139], v[160:163], v[120:123]
	v_mfma_f32_16x16x32_bf16 v[120:123], v[140:143], v[164:167], v[120:123]
	v_mfma_f32_16x16x32_bf16 v[124:127], v[136:139], v[172:175], v[124:127]
	v_mfma_f32_16x16x32_bf16 v[124:127], v[140:143], v[176:179], v[124:127]
	v_mfma_f32_16x16x32_bf16 v[96:99], v[144:147], v[160:163], v[96:99]
	v_mfma_f32_16x16x32_bf16 v[96:99], v[148:151], v[164:167], v[96:99]
	v_mfma_f32_16x16x32_bf16 v[100:103], v[144:147], v[172:175], v[100:103]
	v_mfma_f32_16x16x32_bf16 v[100:103], v[148:151], v[176:179], v[100:103]
	v_mfma_f32_16x16x32_bf16 v[104:107], v[152:155], v[160:163], v[104:107]
	v_mfma_f32_16x16x32_bf16 v[104:107], v[156:159], v[164:167], v[104:107]
	v_mfma_f32_16x16x32_bf16 v[108:111], v[152:155], v[172:175], v[108:111]
	v_mfma_f32_16x16x32_bf16 v[108:111], v[156:159], v[176:179], v[108:111]
	s_setprio 0
	s_barrier
	ds_read_b128 v[180:183], v198 offset:16384
	ds_read_b128 v[184:187], v200 offset:16384
	ds_read_b128 v[188:191], v198 offset:18432
	ds_read_b128 v[192:195], v200 offset:18432
	s_waitcnt vmcnt(0)
	s_barrier
	s_waitcnt lgkmcnt(0)
	s_setprio 1
	v_mfma_f32_16x16x32_bf16 v[48:51], v[128:131], v[180:183], v[48:51]
	v_mfma_f32_16x16x32_bf16 v[48:51], v[132:135], v[184:187], v[48:51]
	v_mfma_f32_16x16x32_bf16 v[52:55], v[128:131], v[188:191], v[52:55]
	v_mfma_f32_16x16x32_bf16 v[52:55], v[132:135], v[192:195], v[52:55]
	v_mfma_f32_16x16x32_bf16 v[56:59], v[136:139], v[180:183], v[56:59]
	v_mfma_f32_16x16x32_bf16 v[56:59], v[140:143], v[184:187], v[56:59]
	v_mfma_f32_16x16x32_bf16 v[60:63], v[136:139], v[188:191], v[60:63]
	v_mfma_f32_16x16x32_bf16 v[60:63], v[140:143], v[192:195], v[60:63]
	v_mfma_f32_16x16x32_bf16 v[32:35], v[144:147], v[180:183], v[32:35]
	v_mfma_f32_16x16x32_bf16 v[32:35], v[148:151], v[184:187], v[32:35]
	v_mfma_f32_16x16x32_bf16 v[36:39], v[144:147], v[188:191], v[36:39]
	v_mfma_f32_16x16x32_bf16 v[36:39], v[148:151], v[192:195], v[36:39]
	v_mfma_f32_16x16x32_bf16 v[40:43], v[152:155], v[180:183], v[40:43]
	v_mfma_f32_16x16x32_bf16 v[40:43], v[156:159], v[184:187], v[40:43]
	v_mfma_f32_16x16x32_bf16 v[44:47], v[152:155], v[188:191], v[44:47]
	v_mfma_f32_16x16x32_bf16 v[44:47], v[156:159], v[192:195], v[44:47]
	s_setprio 0
	s_barrier
	ds_read_b128 v[128:131], v170 offset:16384
	ds_read_b128 v[132:135], v196 offset:16384
	ds_read_b128 v[136:139], v170 offset:18432
	ds_read_b128 v[140:143], v196 offset:18432
	ds_read_b128 v[144:147], v170 offset:20480
	ds_read_b128 v[148:151], v196 offset:20480
	ds_read_b128 v[152:155], v170 offset:22528
	ds_read_b128 v[156:159], v196 offset:22528
	s_barrier
	s_waitcnt lgkmcnt(0)
	s_setprio 1
	v_mfma_f32_16x16x32_bf16 v[80:83], v[128:131], v[160:163], v[80:83]
	v_mfma_f32_16x16x32_bf16 v[80:83], v[132:135], v[164:167], v[80:83]
	v_mfma_f32_16x16x32_bf16 v[84:87], v[128:131], v[172:175], v[84:87]
	v_mfma_f32_16x16x32_bf16 v[84:87], v[132:135], v[176:179], v[84:87]
	v_mfma_f32_16x16x32_bf16 v[88:91], v[136:139], v[160:163], v[88:91]
	v_mfma_f32_16x16x32_bf16 v[88:91], v[140:143], v[164:167], v[88:91]
	v_mfma_f32_16x16x32_bf16 v[92:95], v[136:139], v[172:175], v[92:95]
	v_mfma_f32_16x16x32_bf16 v[92:95], v[140:143], v[176:179], v[92:95]
	v_mfma_f32_16x16x32_bf16 v[64:67], v[144:147], v[160:163], v[64:67]
	v_mfma_f32_16x16x32_bf16 v[64:67], v[148:151], v[164:167], v[64:67]
	v_mfma_f32_16x16x32_bf16 v[68:71], v[144:147], v[172:175], v[68:71]
	v_mfma_f32_16x16x32_bf16 v[68:71], v[148:151], v[176:179], v[68:71]
	v_mfma_f32_16x16x32_bf16 v[72:75], v[152:155], v[160:163], v[72:75]
	v_mfma_f32_16x16x32_bf16 v[72:75], v[156:159], v[164:167], v[72:75]
	v_mfma_f32_16x16x32_bf16 v[76:79], v[152:155], v[172:175], v[76:79]
	v_mfma_f32_16x16x32_bf16 v[76:79], v[156:159], v[176:179], v[76:79]
	s_setprio 0
	s_setprio 1
	v_mfma_f32_16x16x32_bf16 v[16:19], v[128:131], v[180:183], v[16:19]
	v_mfma_f32_16x16x32_bf16 v[16:19], v[132:135], v[184:187], v[16:19]
	v_mfma_f32_16x16x32_bf16 v[20:23], v[128:131], v[188:191], v[20:23]
	v_mfma_f32_16x16x32_bf16 v[20:23], v[132:135], v[192:195], v[20:23]
	v_mfma_f32_16x16x32_bf16 v[24:27], v[136:139], v[180:183], v[24:27]
	v_mfma_f32_16x16x32_bf16 v[24:27], v[140:143], v[184:187], v[24:27]
	v_mfma_f32_16x16x32_bf16 v[28:31], v[136:139], v[188:191], v[28:31]
	v_mfma_f32_16x16x32_bf16 v[28:31], v[140:143], v[192:195], v[28:31]
	v_mfma_f32_16x16x32_bf16 v[0:3], v[144:147], v[180:183], v[0:3]
	v_mfma_f32_16x16x32_bf16 v[0:3], v[148:151], v[184:187], v[0:3]
	v_mfma_f32_16x16x32_bf16 v[4:7], v[144:147], v[188:191], v[4:7]
	v_mfma_f32_16x16x32_bf16 v[4:7], v[148:151], v[192:195], v[4:7]
	v_mfma_f32_16x16x32_bf16 v[8:11], v[152:155], v[180:183], v[8:11]
	v_mfma_f32_16x16x32_bf16 v[8:11], v[156:159], v[184:187], v[8:11]
	v_mfma_f32_16x16x32_bf16 v[12:15], v[152:155], v[188:191], v[12:15]
	v_mfma_f32_16x16x32_bf16 v[12:15], v[156:159], v[192:195], v[12:15]
	s_setprio 0
	s_barrier
	s_cmp_lg_u32 s100, 0
	s_cbranch_scc1 .Lg8_p7_eg1
	s_barrier
.Lg8_p7_eg1:
	s_nop 7
	s_nop 7
	v_permlane16_swap_b32_e32 v112, v116
	v_permlane16_swap_b32_e32 v113, v117
	v_permlane16_swap_b32_e32 v114, v118
	v_permlane16_swap_b32_e32 v115, v119
	v_permlane16_swap_b32_e32 v120, v124
	v_permlane16_swap_b32_e32 v121, v125
	v_permlane16_swap_b32_e32 v122, v126
	v_permlane16_swap_b32_e32 v123, v127
	v_permlane16_swap_b32_e32 v96, v100
	v_permlane16_swap_b32_e32 v97, v101
	v_permlane16_swap_b32_e32 v98, v102
	v_permlane16_swap_b32_e32 v99, v103
	v_permlane16_swap_b32_e32 v104, v108
	v_permlane16_swap_b32_e32 v105, v109
	v_permlane16_swap_b32_e32 v106, v110
	v_permlane16_swap_b32_e32 v107, v111
	v_permlane16_swap_b32_e32 v80, v84
	v_permlane16_swap_b32_e32 v81, v85
	v_permlane16_swap_b32_e32 v82, v86
	v_permlane16_swap_b32_e32 v83, v87
	v_permlane16_swap_b32_e32 v88, v92
	v_permlane16_swap_b32_e32 v89, v93
	v_permlane16_swap_b32_e32 v90, v94
	v_permlane16_swap_b32_e32 v91, v95
	v_permlane16_swap_b32_e32 v64, v68
	v_permlane16_swap_b32_e32 v65, v69
	v_permlane16_swap_b32_e32 v66, v70
	v_permlane16_swap_b32_e32 v67, v71
	v_permlane16_swap_b32_e32 v72, v76
	v_permlane16_swap_b32_e32 v73, v77
	v_permlane16_swap_b32_e32 v74, v78
	v_permlane16_swap_b32_e32 v75, v79
	v_permlane16_swap_b32_e32 v48, v52
	v_permlane16_swap_b32_e32 v49, v53
	v_permlane16_swap_b32_e32 v50, v54
	v_permlane16_swap_b32_e32 v51, v55
	v_permlane16_swap_b32_e32 v56, v60
	v_permlane16_swap_b32_e32 v57, v61
	v_permlane16_swap_b32_e32 v58, v62
	v_permlane16_swap_b32_e32 v59, v63
	v_permlane16_swap_b32_e32 v32, v36
	v_permlane16_swap_b32_e32 v33, v37
	v_permlane16_swap_b32_e32 v34, v38
	v_permlane16_swap_b32_e32 v35, v39
	v_permlane16_swap_b32_e32 v40, v44
	v_permlane16_swap_b32_e32 v41, v45
	v_permlane16_swap_b32_e32 v42, v46
	v_permlane16_swap_b32_e32 v43, v47
	v_permlane16_swap_b32_e32 v16, v20
	v_permlane16_swap_b32_e32 v17, v21
	v_permlane16_swap_b32_e32 v18, v22
	v_permlane16_swap_b32_e32 v19, v23
	v_permlane16_swap_b32_e32 v24, v28
	v_permlane16_swap_b32_e32 v25, v29
	v_permlane16_swap_b32_e32 v26, v30
	v_permlane16_swap_b32_e32 v27, v31
	v_permlane16_swap_b32_e32 v0, v4
	v_permlane16_swap_b32_e32 v1, v5
	v_permlane16_swap_b32_e32 v2, v6
	v_permlane16_swap_b32_e32 v3, v7
	v_permlane16_swap_b32_e32 v8, v12
	v_permlane16_swap_b32_e32 v9, v13
	v_permlane16_swap_b32_e32 v10, v14
	v_permlane16_swap_b32_e32 v11, v15
	s_nop 1
	s_waitcnt vmcnt(0)
	v_mov_b32_e32 v135, v208
	s_lshl_b32 s18, s27, 11
	v_lshrrev_b32_e32 v129, 3, v135
	v_lshlrev_b32_e32 v128, 1, v135
	v_and_b32_e32 v129, 4, v129
	v_and_or_b32 v134, v128, s51, v129
	v_and_b32_e32 v128, 1, v135
	v_cmp_eq_u32_e32 vcc, 0, v128
	v_or_b32_e32 v129, s45, v134
	v_or_b32_e32 v129, s18, v129
	v_cndmask_b32_e64 v128, -1.0, 1.0, vcc
	s_cmp_lt_i32 s44, 1
	s_mov_b64 s[2:3], -1
	s_cbranch_scc1 .LBB0_851
	s_cmp_lt_i32 s44, 3
	s_cbranch_scc1 .LBB0_847
	s_cmp_eq_u32 s44, 3
	v_mov_b32_e32 v131, v115
	v_mov_b32_e32 v130, v114
	v_mov_b32_e32 v133, v113
	v_mov_b32_e32 v132, v112
	s_cbranch_scc0 .LBB0_846
	v_lshlrev_b32_e32 v130, 2, v129
	global_load_dwordx4 v[136:139], v130, s[16:17]
	s_waitcnt vmcnt(0)
	v_pk_fma_f32 v[132:133], v[128:129], v[136:137], v[112:113] op_sel_hi:[0,1,1]
	v_pk_fma_f32 v[130:131], v[128:129], v[138:139], v[114:115] op_sel_hi:[0,1,1]

.LBB0_1393:
	s_ashr_i32 s20, s56, 2
	s_ashr_i32 s21, s20, 31
	s_and_b32 s39, s56, 3
	v_lshrrev_b32_e32 v212, 6, v208
	v_and_b32_e32 v213, 63, v208
	v_readfirstlane_b32 s98, v212
	v_and_b32_e32 v214, 3, v213
	v_bfe_u32 v215, v213, 2, 1
	v_lshl_or_b32 v214, v215, 3, v214
	v_bfe_u32 v215, v213, 3, 1
	v_lshl_or_b32 v214, v215, 2, v214
	s_and_b32 s2, s98, 1
	s_lshr_b32 s100, s98, 2
	s_lshl_b32 s99, s98, 10
	v_lshrrev_b32_e32 v215, 4, v213
	v_bfe_u32 v216, v214, 1, 3
	v_xor_b32_e32 v216, v215, v216
	v_lshlrev_b32_e32 v216, 4, v216
	v_lshl_add_u32 v214, s2, 6, v214
	v_lshl_add_u32 v184, v214, 7, v216
	v_xor_b32_e32 v187, 64, v184
	v_add_u32_e32 v186, 0x10000, v184
	v_add_u32_e32 v196, 0x10000, v187
	v_bfe_u32 v216, v213, 1, 3
	v_xor_b32_e32 v216, v215, v216
	v_lshlrev_b32_e32 v216, 4, v216
	v_and_b32_e32 v214, 15, v213
	s_lshr_b32 s101, s98, 1
	v_lshl_add_u32 v214, s101, 5, v214
	v_lshl_add_u32 v197, v214, 7, v216
	v_add_u32_e32 v197, 0x8000, v197
	v_xor_b32_e32 v199, 64, v197
	v_add_u32_e32 v198, 0x10000, v197
	v_add_u32_e32 v200, 0x10000, v199
	v_lshl_add_u32 v216, s2, 2, v215
	v_and_b32_e32 v214, 7, v213
	v_xor_b32_e32 v216, v214, v216
	v_lshlrev_b32_e32 v216, 4, v216
	v_lshrrev_b32_e32 v214, 3, v213
	v_lshl_add_u32 v215, s98, 3, v214
	v_lshl_add_u32 v201, v215, 12, v216
	v_add_u32_e32 v202, 0x80000, v201
	v_add_u32_e32 v203, 0x40000, v201
	v_add_u32_e32 v204, 0xc0000, v201
	s_and_b32 s101, s98, 3
	s_lshl_b32 s101, s101, 3
	s_lshl_b32 s2, s100, 6
	s_add_u32 s101, s101, s2
	v_add_u32_e32 v215, s101, v214
	v_lshl_add_u32 v205, v215, 12, v216
	v_add_u32_e32 v206, 0x80000, v205
	v_add_u32_e32 v210, 0x20000, v205
	v_add_u32_e32 v211, 0xa0000, v205
	s_lshl_b64 s[40:41], s[20:21], 20
	s_add_u32 s40, s61, s40
	s_addc_u32 s41, s62, s41
	s_lshl_b32 s2, s39, 20
	s_add_u32 s42, s1, s2
	s_addc_u32 s43, s26, 0
	v_mov_b32_e32 v112, 0
	v_mov_b32_e32 v113, 0
	v_mov_b32_e32 v114, 0
	v_mov_b32_e32 v115, 0
	v_mov_b32_e32 v116, 0
	v_mov_b32_e32 v117, 0
	v_mov_b32_e32 v118, 0
	v_mov_b32_e32 v119, 0
	v_mov_b32_e32 v120, 0
	v_mov_b32_e32 v121, 0
	v_mov_b32_e32 v122, 0
	v_mov_b32_e32 v123, 0
	v_mov_b32_e32 v124, 0
	v_mov_b32_e32 v125, 0
	v_mov_b32_e32 v126, 0
	v_mov_b32_e32 v127, 0
	v_mov_b32_e32 v96, 0
	v_mov_b32_e32 v97, 0
	v_mov_b32_e32 v98, 0
	v_mov_b32_e32 v99, 0
	v_mov_b32_e32 v100, 0
	v_mov_b32_e32 v101, 0
	v_mov_b32_e32 v102, 0
	v_mov_b32_e32 v103, 0
	v_mov_b32_e32 v104, 0
	v_mov_b32_e32 v105, 0
	v_mov_b32_e32 v106, 0
	v_mov_b32_e32 v107, 0
	v_mov_b32_e32 v108, 0
	v_mov_b32_e32 v109, 0
	v_mov_b32_e32 v110, 0
	v_mov_b32_e32 v111, 0
	v_mov_b32_e32 v64, 0
	v_mov_b32_e32 v65, 0
	v_mov_b32_e32 v66, 0
	v_mov_b32_e32 v67, 0
	v_mov_b32_e32 v68, 0
	v_mov_b32_e32 v69, 0
	v_mov_b32_e32 v70, 0
	v_mov_b32_e32 v71, 0
	v_mov_b32_e32 v72, 0
	v_mov_b32_e32 v73, 0
	v_mov_b32_e32 v74, 0
	v_mov_b32_e32 v75, 0
	v_mov_b32_e32 v76, 0
	v_mov_b32_e32 v77, 0
	v_mov_b32_e32 v78, 0
	v_mov_b32_e32 v79, 0
	v_mov_b32_e32 v80, 0
	v_mov_b32_e32 v81, 0
	v_mov_b32_e32 v82, 0
	v_mov_b32_e32 v83, 0
	v_mov_b32_e32 v84, 0
	v_mov_b32_e32 v85, 0
	v_mov_b32_e32 v86, 0
	v_mov_b32_e32 v87, 0
	v_mov_b32_e32 v88, 0
	v_mov_b32_e32 v89, 0
	v_mov_b32_e32 v90, 0
	v_mov_b32_e32 v91, 0
	v_mov_b32_e32 v92, 0
	v_mov_b32_e32 v93, 0
	v_mov_b32_e32 v94, 0
	v_mov_b32_e32 v95, 0
	v_mov_b32_e32 v48, 0
	v_mov_b32_e32 v49, 0
	v_mov_b32_e32 v50, 0
	v_mov_b32_e32 v51, 0
	v_mov_b32_e32 v52, 0
	v_mov_b32_e32 v53, 0
	v_mov_b32_e32 v54, 0
	v_mov_b32_e32 v55, 0
	v_mov_b32_e32 v56, 0
	v_mov_b32_e32 v57, 0
	v_mov_b32_e32 v58, 0
	v_mov_b32_e32 v59, 0
	v_mov_b32_e32 v60, 0
	v_mov_b32_e32 v61, 0
	v_mov_b32_e32 v62, 0
	v_mov_b32_e32 v63, 0
	v_mov_b32_e32 v32, 0
	v_mov_b32_e32 v33, 0
	v_mov_b32_e32 v34, 0
	v_mov_b32_e32 v35, 0
	v_mov_b32_e32 v36, 0
	v_mov_b32_e32 v37, 0
	v_mov_b32_e32 v38, 0
	v_mov_b32_e32 v39, 0
	v_mov_b32_e32 v40, 0
	v_mov_b32_e32 v41, 0
	v_mov_b32_e32 v42, 0
	v_mov_b32_e32 v43, 0
	v_mov_b32_e32 v44, 0
	v_mov_b32_e32 v45, 0
	v_mov_b32_e32 v46, 0
	v_mov_b32_e32 v47, 0
	v_mov_b32_e32 v16, 0
	v_mov_b32_e32 v17, 0
	v_mov_b32_e32 v18, 0
	v_mov_b32_e32 v19, 0
	v_mov_b32_e32 v20, 0
	v_mov_b32_e32 v21, 0
	v_mov_b32_e32 v22, 0
	v_mov_b32_e32 v23, 0
	v_mov_b32_e32 v24, 0
	v_mov_b32_e32 v25, 0
	v_mov_b32_e32 v26, 0
	v_mov_b32_e32 v27, 0
	v_mov_b32_e32 v28, 0
	v_mov_b32_e32 v29, 0
	v_mov_b32_e32 v30, 0
	v_mov_b32_e32 v31, 0
	v_mov_b32_e32 v0, 0
	v_mov_b32_e32 v1, 0
	v_mov_b32_e32 v2, 0
	v_mov_b32_e32 v3, 0
	v_mov_b32_e32 v4, 0
	v_mov_b32_e32 v5, 0
	v_mov_b32_e32 v6, 0
	v_mov_b32_e32 v7, 0
	v_mov_b32_e32 v8, 0
	v_mov_b32_e32 v9, 0
	v_mov_b32_e32 v10, 0
	v_mov_b32_e32 v11, 0
	v_mov_b32_e32 v12, 0
	v_mov_b32_e32 v13, 0
	v_mov_b32_e32 v14, 0
	v_mov_b32_e32 v15, 0
	s_add_u32 m0, s99, 0x8000
	s_nop 0
	global_load_lds_dwordx4 v205, s[40:41]
	s_add_u32 m0, s99, 0xa000
	s_nop 0
	global_load_lds_dwordx4 v206, s[40:41]
	s_add_u32 m0, s99, 0x0
	s_nop 0
	global_load_lds_dwordx4 v201, s[42:43]
	s_add_u32 m0, s99, 0x2000
	s_nop 0
	global_load_lds_dwordx4 v202, s[42:43]
	s_add_u32 m0, s99, 0xc000
	s_nop 0
	global_load_lds_dwordx4 v210, s[40:41]
	s_add_u32 m0, s99, 0xe000
	s_nop 0
	global_load_lds_dwordx4 v211, s[40:41]
	s_add_u32 s40, s40, 0x80
	s_addc_u32 s41, s41, 0
	s_add_u32 m0, s99, 0x4000
	s_nop 0
	global_load_lds_dwordx4 v203, s[42:43]
	s_add_u32 m0, s99, 0x6000
	s_nop 0
	global_load_lds_dwordx4 v204, s[42:43]
	s_add_u32 s42, s42, 0x80
	s_addc_u32 s43, s43, 0
	s_cmp_eq_u32 s100, 0
	s_cbranch_scc1 .Lg8_p9_pg0
	s_barrier
.Lg8_p9_pg0:
	s_waitcnt vmcnt(4)
	s_barrier
	s_add_u32 m0, s99, 0x18000
	s_nop 0
	global_load_lds_dwordx4 v205, s[40:41]
	s_add_u32 m0, s99, 0x1a000
	s_nop 0
	global_load_lds_dwordx4 v206, s[40:41]
	s_add_u32 m0, s99, 0x10000
	s_nop 0
	global_load_lds_dwordx4 v201, s[42:43]
	s_add_u32 m0, s99, 0x12000
	s_nop 0
	global_load_lds_dwordx4 v202, s[42:43]
	s_add_u32 m0, s99, 0x1c000
	s_nop 0
	global_load_lds_dwordx4 v210, s[40:41]
	s_add_u32 m0, s99, 0x1e000
	s_nop 0
	global_load_lds_dwordx4 v211, s[40:41]
	s_add_u32 s40, s40, 0x80
	s_addc_u32 s41, s41, 0
	s_waitcnt vmcnt(6)
	s_barrier
	s_mov_b32 s101, 15
.Lg8_p9_loop:
	ds_read_b128 v[160:163], v197 offset:0
	ds_read_b128 v[164:167], v199 offset:0
	ds_read_b128 v[168:171], v197 offset:2048
	ds_read_b128 v[172:175], v199 offset:2048
	ds_read_b128 v[128:131], v184 offset:0
	ds_read_b128 v[132:135], v187 offset:0
	ds_read_b128 v[136:139], v184 offset:2048
	ds_read_b128 v[140:143], v187 offset:2048
	ds_read_b128 v[144:147], v184 offset:4096
	ds_read_b128 v[148:151], v187 offset:4096
	ds_read_b128 v[152:155], v184 offset:6144
	ds_read_b128 v[156:159], v187 offset:6144
	s_add_u32 m0, s99, 0x14000
	s_nop 0
	global_load_lds_dwordx4 v203, s[42:43]
	s_add_u32 m0, s99, 0x16000
	s_nop 0
	global_load_lds_dwordx4 v204, s[42:43]
	s_add_u32 s42, s42, 0x80
	s_addc_u32 s43, s43, 0
	s_waitcnt lgkmcnt(8)
	s_barrier
	s_waitcnt lgkmcnt(0)
	s_setprio 1
	v_mfma_f32_16x16x32_bf16 v[112:115], v[128:131], v[160:163], v[112:115]
	v_mfma_f32_16x16x32_bf16 v[112:115], v[132:135], v[164:167], v[112:115]
	v_mfma_f32_16x16x32_bf16 v[116:119], v[128:131], v[168:171], v[116:119]
	v_mfma_f32_16x16x32_bf16 v[116:119], v[132:135], v[172:175], v[116:119]
	v_mfma_f32_16x16x32_bf16 v[120:123], v[136:139], v[160:163], v[120:123]
	v_mfma_f32_16x16x32_bf16 v[120:123], v[140:143], v[164:167], v[120:123]
	v_mfma_f32_16x16x32_bf16 v[124:127], v[136:139], v[168:171], v[124:127]
	v_mfma_f32_16x16x32_bf16 v[124:127], v[140:143], v[172:175], v[124:127]
	v_mfma_f32_16x16x32_bf16 v[96:99], v[144:147], v[160:163], v[96:99]
	v_mfma_f32_16x16x32_bf16 v[96:99], v[148:151], v[164:167], v[96:99]
	v_mfma_f32_16x16x32_bf16 v[100:103], v[144:147], v[168:171], v[100:103]
	v_mfma_f32_16x16x32_bf16 v[100:103], v[148:151], v[172:175], v[100:103]
	v_mfma_f32_16x16x32_bf16 v[104:107], v[152:155], v[160:163], v[104:107]
	v_mfma_f32_16x16x32_bf16 v[104:107], v[156:159], v[164:167], v[104:107]
	v_mfma_f32_16x16x32_bf16 v[108:111], v[152:155], v[168:171], v[108:111]
	v_mfma_f32_16x16x32_bf16 v[108:111], v[156:159], v[172:175], v[108:111]
	s_setprio 0
	s_barrier
	ds_read_b128 v[176:179], v197 offset:16384
	ds_read_b128 v[180:183], v199 offset:16384
	ds_read_b128 v[188:191], v197 offset:18432
	ds_read_b128 v[192:195], v199 offset:18432
	s_add_u32 m0, s99, 0x8000
	s_nop 0
	global_load_lds_dwordx4 v205, s[40:41]
	s_add_u32 m0, s99, 0xa000
	s_nop 0
	global_load_lds_dwordx4 v206, s[40:41]
	s_barrier
	s_waitcnt lgkmcnt(0)
	s_setprio 1
	v_mfma_f32_16x16x32_bf16 v[48:51], v[128:131], v[176:179], v[48:51]
	v_mfma_f32_16x16x32_bf16 v[48:51], v[132:135], v[180:183], v[48:51]
	v_mfma_f32_16x16x32_bf16 v[52:55], v[128:131], v[188:191], v[52:55]
	v_mfma_f32_16x16x32_bf16 v[52:55], v[132:135], v[192:195], v[52:55]
	v_mfma_f32_16x16x32_bf16 v[56:59], v[136:139], v[176:179], v[56:59]
	v_mfma_f32_16x16x32_bf16 v[56:59], v[140:143], v[180:183], v[56:59]
	v_mfma_f32_16x16x32_bf16 v[60:63], v[136:139], v[188:191], v[60:63]
	v_mfma_f32_16x16x32_bf16 v[60:63], v[140:143], v[192:195], v[60:63]
	v_mfma_f32_16x16x32_bf16 v[32:35], v[144:147], v[176:179], v[32:35]
	v_mfma_f32_16x16x32_bf16 v[32:35], v[148:151], v[180:183], v[32:35]
	v_mfma_f32_16x16x32_bf16 v[36:39], v[144:147], v[188:191], v[36:39]
	v_mfma_f32_16x16x32_bf16 v[36:39], v[148:151], v[192:195], v[36:39]
	v_mfma_f32_16x16x32_bf16 v[40:43], v[152:155], v[176:179], v[40:43]
	v_mfma_f32_16x16x32_bf16 v[40:43], v[156:159], v[180:183], v[40:43]
	v_mfma_f32_16x16x32_bf16 v[44:47], v[152:155], v[188:191], v[44:47]
	v_mfma_f32_16x16x32_bf16 v[44:47], v[156:159], v[192:195], v[44:47]
	s_setprio 0
	s_barrier
	ds_read_b128 v[128:131], v184 offset:16384
	ds_read_b128 v[132:135], v187 offset:16384
	ds_read_b128 v[136:139], v184 offset:18432
	ds_read_b128 v[140:143], v187 offset:18432
	ds_read_b128 v[144:147], v184 offset:20480
	ds_read_b128 v[148:151], v187 offset:20480
	ds_read_b128 v[152:155], v184 offset:22528
	ds_read_b128 v[156:159], v187 offset:22528
	s_add_u32 m0, s99, 0x0
	s_nop 0
	global_load_lds_dwordx4 v201, s[42:43]
	s_add_u32 m0, s99, 0x2000
	s_nop 0
	global_load_lds_dwordx4 v202, s[42:43]
	s_barrier
	s_waitcnt lgkmcnt(0)
	s_setprio 1
	v_mfma_f32_16x16x32_bf16 v[64:67], v[128:131], v[160:163], v[64:67]
	v_mfma_f32_16x16x32_bf16 v[64:67], v[132:135], v[164:167], v[64:67]
	v_mfma_f32_16x16x32_bf16 v[68:71], v[128:131], v[168:171], v[68:71]
	v_mfma_f32_16x16x32_bf16 v[68:71], v[132:135], v[172:175], v[68:71]
	v_mfma_f32_16x16x32_bf16 v[72:75], v[136:139], v[160:163], v[72:75]
	v_mfma_f32_16x16x32_bf16 v[72:75], v[140:143], v[164:167], v[72:75]
	v_mfma_f32_16x16x32_bf16 v[76:79], v[136:139], v[168:171], v[76:79]
	v_mfma_f32_16x16x32_bf16 v[76:79], v[140:143], v[172:175], v[76:79]
	v_mfma_f32_16x16x32_bf16 v[80:83], v[144:147], v[160:163], v[80:83]
	v_mfma_f32_16x16x32_bf16 v[80:83], v[148:151], v[164:167], v[80:83]
	v_mfma_f32_16x16x32_bf16 v[84:87], v[144:147], v[168:171], v[84:87]
	v_mfma_f32_16x16x32_bf16 v[84:87], v[148:151], v[172:175], v[84:87]
	v_mfma_f32_16x16x32_bf16 v[88:91], v[152:155], v[160:163], v[88:91]
	v_mfma_f32_16x16x32_bf16 v[88:91], v[156:159], v[164:167], v[88:91]
	v_mfma_f32_16x16x32_bf16 v[92:95], v[152:155], v[168:171], v[92:95]
	v_mfma_f32_16x16x32_bf16 v[92:95], v[156:159], v[172:175], v[92:95]
	s_setprio 0
	s_barrier
	s_add_u32 m0, s99, 0xc000
	s_nop 0
	global_load_lds_dwordx4 v210, s[40:41]
	s_add_u32 m0, s99, 0xe000
	s_nop 0
	global_load_lds_dwordx4 v211, s[40:41]
	s_add_u32 s40, s40, 0x80
	s_addc_u32 s41, s41, 0
	s_waitcnt vmcnt(6)
	s_barrier
	s_setprio 1
	v_mfma_f32_16x16x32_bf16 v[16:19], v[128:131], v[176:179], v[16:19]
	v_mfma_f32_16x16x32_bf16 v[16:19], v[132:135], v[180:183], v[16:19]
	v_mfma_f32_16x16x32_bf16 v[20:23], v[128:131], v[188:191], v[20:23]
	v_mfma_f32_16x16x32_bf16 v[20:23], v[132:135], v[192:195], v[20:23]
	v_mfma_f32_16x16x32_bf16 v[24:27], v[136:139], v[176:179], v[24:27]
	v_mfma_f32_16x16x32_bf16 v[24:27], v[140:143], v[180:183], v[24:27]
	v_mfma_f32_16x16x32_bf16 v[28:31], v[136:139], v[188:191], v[28:31]
	v_mfma_f32_16x16x32_bf16 v[28:31], v[140:143], v[192:195], v[28:31]
	v_mfma_f32_16x16x32_bf16 v[0:3], v[144:147], v[176:179], v[0:3]
	v_mfma_f32_16x16x32_bf16 v[0:3], v[148:151], v[180:183], v[0:3]
	v_mfma_f32_16x16x32_bf16 v[4:7], v[144:147], v[188:191], v[4:7]
	v_mfma_f32_16x16x32_bf16 v[4:7], v[148:151], v[192:195], v[4:7]
	v_mfma_f32_16x16x32_bf16 v[8:11], v[152:155], v[176:179], v[8:11]
	v_mfma_f32_16x16x32_bf16 v[8:11], v[156:159], v[180:183], v[8:11]
	v_mfma_f32_16x16x32_bf16 v[12:15], v[152:155], v[188:191], v[12:15]
	v_mfma_f32_16x16x32_bf16 v[12:15], v[156:159], v[192:195], v[12:15]
	s_setprio 0
	s_barrier
	ds_read_b128 v[160:163], v198 offset:0
	ds_read_b128 v[164:167], v200 offset:0
	ds_read_b128 v[168:171], v198 offset:2048
	ds_read_b128 v[172:175], v200 offset:2048
	ds_read_b128 v[128:131], v186 offset:0
	ds_read_b128 v[132:135], v196 offset:0
	ds_read_b128 v[136:139], v186 offset:2048
	ds_read_b128 v[140:143], v196 offset:2048
	ds_read_b128 v[144:147], v186 offset:4096
	ds_read_b128 v[148:151], v196 offset:4096
	ds_read_b128 v[152:155], v186 offset:6144
	ds_read_b128 v[156:159], v196 offset:6144
	s_add_u32 m0, s99, 0x4000
	s_nop 0
	global_load_lds_dwordx4 v203, s[42:43]
	s_add_u32 m0, s99, 0x6000
	s_nop 0
	global_load_lds_dwordx4 v204, s[42:43]
	s_add_u32 s42, s42, 0x80
	s_addc_u32 s43, s43, 0
	s_waitcnt lgkmcnt(8)
	s_barrier
	s_waitcnt lgkmcnt(0)
	s_setprio 1
	v_mfma_f32_16x16x32_bf16 v[112:115], v[128:131], v[160:163], v[112:115]
	v_mfma_f32_16x16x32_bf16 v[112:115], v[132:135], v[164:167], v[112:115]
	v_mfma_f32_16x16x32_bf16 v[116:119], v[128:131], v[168:171], v[116:119]
	v_mfma_f32_16x16x32_bf16 v[116:119], v[132:135], v[172:175], v[116:119]
	v_mfma_f32_16x16x32_bf16 v[120:123], v[136:139], v[160:163], v[120:123]
	v_mfma_f32_16x16x32_bf16 v[120:123], v[140:143], v[164:167], v[120:123]
	v_mfma_f32_16x16x32_bf16 v[124:127], v[136:139], v[168:171], v[124:127]
	v_mfma_f32_16x16x32_bf16 v[124:127], v[140:143], v[172:175], v[124:127]
	v_mfma_f32_16x16x32_bf16 v[96:99], v[144:147], v[160:163], v[96:99]
	v_mfma_f32_16x16x32_bf16 v[96:99], v[148:151], v[164:167], v[96:99]
	v_mfma_f32_16x16x32_bf16 v[100:103], v[144:147], v[168:171], v[100:103]
	v_mfma_f32_16x16x32_bf16 v[100:103], v[148:151], v[172:175], v[100:103]
	v_mfma_f32_16x16x32_bf16 v[104:107], v[152:155], v[160:163], v[104:107]
	v_mfma_f32_16x16x32_bf16 v[104:107], v[156:159], v[164:167], v[104:107]
	v_mfma_f32_16x16x32_bf16 v[108:111], v[152:155], v[168:171], v[108:111]
	v_mfma_f32_16x16x32_bf16 v[108:111], v[156:159], v[172:175], v[108:111]
	s_setprio 0
	s_barrier
	ds_read_b128 v[176:179], v198 offset:16384
	ds_read_b128 v[180:183], v200 offset:16384
	ds_read_b128 v[188:191], v198 offset:18432
	ds_read_b128 v[192:195], v200 offset:18432
	s_add_u32 m0, s99, 0x18000
	s_nop 0
	global_load_lds_dwordx4 v205, s[40:41]
	s_add_u32 m0, s99, 0x1a000
	s_nop 0
	global_load_lds_dwordx4 v206, s[40:41]
	s_barrier
	s_waitcnt lgkmcnt(0)
	s_setprio 1
	v_mfma_f32_16x16x32_bf16 v[48:51], v[128:131], v[176:179], v[48:51]
	v_mfma_f32_16x16x32_bf16 v[48:51], v[132:135], v[180:183], v[48:51]
	v_mfma_f32_16x16x32_bf16 v[52:55], v[128:131], v[188:191], v[52:55]
	v_mfma_f32_16x16x32_bf16 v[52:55], v[132:135], v[192:195], v[52:55]
	v_mfma_f32_16x16x32_bf16 v[56:59], v[136:139], v[176:179], v[56:59]
	v_mfma_f32_16x16x32_bf16 v[56:59], v[140:143], v[180:183], v[56:59]
	v_mfma_f32_16x16x32_bf16 v[60:63], v[136:139], v[188:191], v[60:63]
	v_mfma_f32_16x16x32_bf16 v[60:63], v[140:143], v[192:195], v[60:63]
	v_mfma_f32_16x16x32_bf16 v[32:35], v[144:147], v[176:179], v[32:35]
	v_mfma_f32_16x16x32_bf16 v[32:35], v[148:151], v[180:183], v[32:35]
	v_mfma_f32_16x16x32_bf16 v[36:39], v[144:147], v[188:191], v[36:39]
	v_mfma_f32_16x16x32_bf16 v[36:39], v[148:151], v[192:195], v[36:39]
	v_mfma_f32_16x16x32_bf16 v[40:43], v[152:155], v[176:179], v[40:43]
	v_mfma_f32_16x16x32_bf16 v[40:43], v[156:159], v[180:183], v[40:43]
	v_mfma_f32_16x16x32_bf16 v[44:47], v[152:155], v[188:191], v[44:47]
	v_mfma_f32_16x16x32_bf16 v[44:47], v[156:159], v[192:195], v[44:47]
	s_setprio 0
	s_barrier
	ds_read_b128 v[128:131], v186 offset:16384
	ds_read_b128 v[132:135], v196 offset:16384
	ds_read_b128 v[136:139], v186 offset:18432
	ds_read_b128 v[140:143], v196 offset:18432
	ds_read_b128 v[144:147], v186 offset:20480
	ds_read_b128 v[148:151], v196 offset:20480
	ds_read_b128 v[152:155], v186 offset:22528
	ds_read_b128 v[156:159], v196 offset:22528
	s_add_u32 m0, s99, 0x10000
	s_nop 0
	global_load_lds_dwordx4 v201, s[42:43]
	s_add_u32 m0, s99, 0x12000
	s_nop 0
	global_load_lds_dwordx4 v202, s[42:43]
	s_barrier
	s_waitcnt lgkmcnt(0)
	s_setprio 1
	v_mfma_f32_16x16x32_bf16 v[64:67], v[128:131], v[160:163], v[64:67]
	v_mfma_f32_16x16x32_bf16 v[64:67], v[132:135], v[164:167], v[64:67]
	v_mfma_f32_16x16x32_bf16 v[68:71], v[128:131], v[168:171], v[68:71]
	v_mfma_f32_16x16x32_bf16 v[68:71], v[132:135], v[172:175], v[68:71]
	v_mfma_f32_16x16x32_bf16 v[72:75], v[136:139], v[160:163], v[72:75]
	v_mfma_f32_16x16x32_bf16 v[72:75], v[140:143], v[164:167], v[72:75]
	v_mfma_f32_16x16x32_bf16 v[76:79], v[136:139], v[168:171], v[76:79]
	v_mfma_f32_16x16x32_bf16 v[76:79], v[140:143], v[172:175], v[76:79]
	v_mfma_f32_16x16x32_bf16 v[80:83], v[144:147], v[160:163], v[80:83]
	v_mfma_f32_16x16x32_bf16 v[80:83], v[148:151], v[164:167], v[80:83]
	v_mfma_f32_16x16x32_bf16 v[84:87], v[144:147], v[168:171], v[84:87]
	v_mfma_f32_16x16x32_bf16 v[84:87], v[148:151], v[172:175], v[84:87]
	v_mfma_f32_16x16x32_bf16 v[88:91], v[152:155], v[160:163], v[88:91]
	v_mfma_f32_16x16x32_bf16 v[88:91], v[156:159], v[164:167], v[88:91]
	v_mfma_f32_16x16x32_bf16 v[92:95], v[152:155], v[168:171], v[92:95]
	v_mfma_f32_16x16x32_bf16 v[92:95], v[156:159], v[172:175], v[92:95]
	s_setprio 0
	s_barrier
	s_add_u32 m0, s99, 0x1c000
	s_nop 0
	global_load_lds_dwordx4 v210, s[40:41]
	s_add_u32 m0, s99, 0x1e000
	s_nop 0
	global_load_lds_dwordx4 v211, s[40:41]
	s_add_u32 s40, s40, 0x80
	s_addc_u32 s41, s41, 0
	s_waitcnt vmcnt(6)
	s_barrier
	s_setprio 1
	v_mfma_f32_16x16x32_bf16 v[16:19], v[128:131], v[176:179], v[16:19]
	v_mfma_f32_16x16x32_bf16 v[16:19], v[132:135], v[180:183], v[16:19]
	v_mfma_f32_16x16x32_bf16 v[20:23], v[128:131], v[188:191], v[20:23]
	v_mfma_f32_16x16x32_bf16 v[20:23], v[132:135], v[192:195], v[20:23]
	v_mfma_f32_16x16x32_bf16 v[24:27], v[136:139], v[176:179], v[24:27]
	v_mfma_f32_16x16x32_bf16 v[24:27], v[140:143], v[180:183], v[24:27]
	v_mfma_f32_16x16x32_bf16 v[28:31], v[136:139], v[188:191], v[28:31]
	v_mfma_f32_16x16x32_bf16 v[28:31], v[140:143], v[192:195], v[28:31]
	v_mfma_f32_16x16x32_bf16 v[0:3], v[144:147], v[176:179], v[0:3]
	v_mfma_f32_16x16x32_bf16 v[0:3], v[148:151], v[180:183], v[0:3]
	v_mfma_f32_16x16x32_bf16 v[4:7], v[144:147], v[188:191], v[4:7]
	v_mfma_f32_16x16x32_bf16 v[4:7], v[148:151], v[192:195], v[4:7]
	v_mfma_f32_16x16x32_bf16 v[8:11], v[152:155], v[176:179], v[8:11]
	v_mfma_f32_16x16x32_bf16 v[8:11], v[156:159], v[180:183], v[8:11]
	v_mfma_f32_16x16x32_bf16 v[12:15], v[152:155], v[188:191], v[12:15]
	v_mfma_f32_16x16x32_bf16 v[12:15], v[156:159], v[192:195], v[12:15]
	s_setprio 0
	s_barrier
	s_sub_u32 s101, s101, 1
	s_cmp_lg_u32 s101, 0
	s_cbranch_scc1 .Lg8_p9_loop
	ds_read_b128 v[160:163], v197 offset:0
	ds_read_b128 v[164:167], v199 offset:0
	ds_read_b128 v[168:171], v197 offset:2048
	ds_read_b128 v[172:175], v199 offset:2048
	ds_read_b128 v[128:131], v184 offset:0
	ds_read_b128 v[132:135], v187 offset:0
	ds_read_b128 v[136:139], v184 offset:2048
	ds_read_b128 v[140:143], v187 offset:2048
	ds_read_b128 v[144:147], v184 offset:4096
	ds_read_b128 v[148:151], v187 offset:4096
	ds_read_b128 v[152:155], v184 offset:6144
	ds_read_b128 v[156:159], v187 offset:6144
	s_add_u32 m0, s99, 0x14000
	s_nop 0
	global_load_lds_dwordx4 v203, s[42:43]
	s_add_u32 m0, s99, 0x16000
	s_nop 0
	global_load_lds_dwordx4 v204, s[42:43]
	s_add_u32 s42, s42, 0x80
	s_addc_u32 s43, s43, 0
	s_barrier
	s_waitcnt lgkmcnt(0)
	s_setprio 1
	v_mfma_f32_16x16x32_bf16 v[112:115], v[128:131], v[160:163], v[112:115]
	v_mfma_f32_16x16x32_bf16 v[112:115], v[132:135], v[164:167], v[112:115]
	v_mfma_f32_16x16x32_bf16 v[116:119], v[128:131], v[168:171], v[116:119]
	v_mfma_f32_16x16x32_bf16 v[116:119], v[132:135], v[172:175], v[116:119]
	v_mfma_f32_16x16x32_bf16 v[120:123], v[136:139], v[160:163], v[120:123]
	v_mfma_f32_16x16x32_bf16 v[120:123], v[140:143], v[164:167], v[120:123]
	v_mfma_f32_16x16x32_bf16 v[124:127], v[136:139], v[168:171], v[124:127]
	v_mfma_f32_16x16x32_bf16 v[124:127], v[140:143], v[172:175], v[124:127]
	v_mfma_f32_16x16x32_bf16 v[96:99], v[144:147], v[160:163], v[96:99]
	v_mfma_f32_16x16x32_bf16 v[96:99], v[148:151], v[164:167], v[96:99]
	v_mfma_f32_16x16x32_bf16 v[100:103], v[144:147], v[168:171], v[100:103]
	v_mfma_f32_16x16x32_bf16 v[100:103], v[148:151], v[172:175], v[100:103]
	v_mfma_f32_16x16x32_bf16 v[104:107], v[152:155], v[160:163], v[104:107]
	v_mfma_f32_16x16x32_bf16 v[104:107], v[156:159], v[164:167], v[104:107]
	v_mfma_f32_16x16x32_bf16 v[108:111], v[152:155], v[168:171], v[108:111]
	v_mfma_f32_16x16x32_bf16 v[108:111], v[156:159], v[172:175], v[108:111]
	s_setprio 0
	s_barrier
	ds_read_b128 v[176:179], v197 offset:16384
	ds_read_b128 v[180:183], v199 offset:16384
	ds_read_b128 v[188:191], v197 offset:18432
	ds_read_b128 v[192:195], v199 offset:18432
	s_barrier
	s_waitcnt lgkmcnt(0)
	s_setprio 1
	v_mfma_f32_16x16x32_bf16 v[48:51], v[128:131], v[176:179], v[48:51]
	v_mfma_f32_16x16x32_bf16 v[48:51], v[132:135], v[180:183], v[48:51]
	v_mfma_f32_16x16x32_bf16 v[52:55], v[128:131], v[188:191], v[52:55]
	v_mfma_f32_16x16x32_bf16 v[52:55], v[132:135], v[192:195], v[52:55]
	v_mfma_f32_16x16x32_bf16 v[56:59], v[136:139], v[176:179], v[56:59]
	v_mfma_f32_16x16x32_bf16 v[56:59], v[140:143], v[180:183], v[56:59]
	v_mfma_f32_16x16x32_bf16 v[60:63], v[136:139], v[188:191], v[60:63]
	v_mfma_f32_16x16x32_bf16 v[60:63], v[140:143], v[192:195], v[60:63]
	v_mfma_f32_16x16x32_bf16 v[32:35], v[144:147], v[176:179], v[32:35]
	v_mfma_f32_16x16x32_bf16 v[32:35], v[148:151], v[180:183], v[32:35]
	v_mfma_f32_16x16x32_bf16 v[36:39], v[144:147], v[188:191], v[36:39]
	v_mfma_f32_16x16x32_bf16 v[36:39], v[148:151], v[192:195], v[36:39]
	v_mfma_f32_16x16x32_bf16 v[40:43], v[152:155], v[176:179], v[40:43]
	v_mfma_f32_16x16x32_bf16 v[40:43], v[156:159], v[180:183], v[40:43]
	v_mfma_f32_16x16x32_bf16 v[44:47], v[152:155], v[188:191], v[44:47]
	v_mfma_f32_16x16x32_bf16 v[44:47], v[156:159], v[192:195], v[44:47]
	s_setprio 0
	s_barrier
	ds_read_b128 v[128:131], v184 offset:16384
	ds_read_b128 v[132:135], v187 offset:16384
	ds_read_b128 v[136:139], v184 offset:18432
	ds_read_b128 v[140:143], v187 offset:18432
	ds_read_b128 v[144:147], v184 offset:20480
	ds_read_b128 v[148:151], v187 offset:20480
	ds_read_b128 v[152:155], v184 offset:22528
	ds_read_b128 v[156:159], v187 offset:22528
	s_waitcnt vmcnt(4)
	s_barrier
	s_waitcnt lgkmcnt(0)
	s_setprio 1
	v_mfma_f32_16x16x32_bf16 v[64:67], v[128:131], v[160:163], v[64:67]
	v_mfma_f32_16x16x32_bf16 v[64:67], v[132:135], v[164:167], v[64:67]
	v_mfma_f32_16x16x32_bf16 v[68:71], v[128:131], v[168:171], v[68:71]
	v_mfma_f32_16x16x32_bf16 v[68:71], v[132:135], v[172:175], v[68:71]
	v_mfma_f32_16x16x32_bf16 v[72:75], v[136:139], v[160:163], v[72:75]
	v_mfma_f32_16x16x32_bf16 v[72:75], v[140:143], v[164:167], v[72:75]
	v_mfma_f32_16x16x32_bf16 v[76:79], v[136:139], v[168:171], v[76:79]
	v_mfma_f32_16x16x32_bf16 v[76:79], v[140:143], v[172:175], v[76:79]
	v_mfma_f32_16x16x32_bf16 v[80:83], v[144:147], v[160:163], v[80:83]
	v_mfma_f32_16x16x32_bf16 v[80:83], v[148:151], v[164:167], v[80:83]
	v_mfma_f32_16x16x32_bf16 v[84:87], v[144:147], v[168:171], v[84:87]
	v_mfma_f32_16x16x32_bf16 v[84:87], v[148:151], v[172:175], v[84:87]
	v_mfma_f32_16x16x32_bf16 v[88:91], v[152:155], v[160:163], v[88:91]
	v_mfma_f32_16x16x32_bf16 v[88:91], v[156:159], v[164:167], v[88:91]
	v_mfma_f32_16x16x32_bf16 v[92:95], v[152:155], v[168:171], v[92:95]
	v_mfma_f32_16x16x32_bf16 v[92:95], v[156:159], v[172:175], v[92:95]
	s_setprio 0
	s_setprio 1
	v_mfma_f32_16x16x32_bf16 v[16:19], v[128:131], v[176:179], v[16:19]
	v_mfma_f32_16x16x32_bf16 v[16:19], v[132:135], v[180:183], v[16:19]
	v_mfma_f32_16x16x32_bf16 v[20:23], v[128:131], v[188:191], v[20:23]
	v_mfma_f32_16x16x32_bf16 v[20:23], v[132:135], v[192:195], v[20:23]
	v_mfma_f32_16x16x32_bf16 v[24:27], v[136:139], v[176:179], v[24:27]
	v_mfma_f32_16x16x32_bf16 v[24:27], v[140:143], v[180:183], v[24:27]
	v_mfma_f32_16x16x32_bf16 v[28:31], v[136:139], v[188:191], v[28:31]
	v_mfma_f32_16x16x32_bf16 v[28:31], v[140:143], v[192:195], v[28:31]
	v_mfma_f32_16x16x32_bf16 v[0:3], v[144:147], v[176:179], v[0:3]
	v_mfma_f32_16x16x32_bf16 v[0:3], v[148:151], v[180:183], v[0:3]
	v_mfma_f32_16x16x32_bf16 v[4:7], v[144:147], v[188:191], v[4:7]
	v_mfma_f32_16x16x32_bf16 v[4:7], v[148:151], v[192:195], v[4:7]
	v_mfma_f32_16x16x32_bf16 v[8:11], v[152:155], v[176:179], v[8:11]
	v_mfma_f32_16x16x32_bf16 v[8:11], v[156:159], v[180:183], v[8:11]
	v_mfma_f32_16x16x32_bf16 v[12:15], v[152:155], v[188:191], v[12:15]
	v_mfma_f32_16x16x32_bf16 v[12:15], v[156:159], v[192:195], v[12:15]
	s_setprio 0
	s_barrier
	ds_read_b128 v[160:163], v198 offset:0
	ds_read_b128 v[164:167], v200 offset:0
	ds_read_b128 v[168:171], v198 offset:2048
	ds_read_b128 v[172:175], v200 offset:2048
	ds_read_b128 v[128:131], v186 offset:0
	ds_read_b128 v[132:135], v196 offset:0
	ds_read_b128 v[136:139], v186 offset:2048
	ds_read_b128 v[140:143], v196 offset:2048
	ds_read_b128 v[144:147], v186 offset:4096
	ds_read_b128 v[148:151], v196 offset:4096
	ds_read_b128 v[152:155], v186 offset:6144
	ds_read_b128 v[156:159], v196 offset:6144
	s_waitcnt vmcnt(2)
	s_barrier
	s_waitcnt lgkmcnt(0)
	s_setprio 1
	v_mfma_f32_16x16x32_bf16 v[112:115], v[128:131], v[160:163], v[112:115]
	v_mfma_f32_16x16x32_bf16 v[112:115], v[132:135], v[164:167], v[112:115]
	v_mfma_f32_16x16x32_bf16 v[116:119], v[128:131], v[168:171], v[116:119]
	v_mfma_f32_16x16x32_bf16 v[116:119], v[132:135], v[172:175], v[116:119]
	v_mfma_f32_16x16x32_bf16 v[120:123], v[136:139], v[160:163], v[120:123]
	v_mfma_f32_16x16x32_bf16 v[120:123], v[140:143], v[164:167], v[120:123]
	v_mfma_f32_16x16x32_bf16 v[124:127], v[136:139], v[168:171], v[124:127]
	v_mfma_f32_16x16x32_bf16 v[124:127], v[140:143], v[172:175], v[124:127]
	v_mfma_f32_16x16x32_bf16 v[96:99], v[144:147], v[160:163], v[96:99]
	v_mfma_f32_16x16x32_bf16 v[96:99], v[148:151], v[164:167], v[96:99]
	v_mfma_f32_16x16x32_bf16 v[100:103], v[144:147], v[168:171], v[100:103]
	v_mfma_f32_16x16x32_bf16 v[100:103], v[148:151], v[172:175], v[100:103]
	v_mfma_f32_16x16x32_bf16 v[104:107], v[152:155], v[160:163], v[104:107]
	v_mfma_f32_16x16x32_bf16 v[104:107], v[156:159], v[164:167], v[104:107]
	v_mfma_f32_16x16x32_bf16 v[108:111], v[152:155], v[168:171], v[108:111]
	v_mfma_f32_16x16x32_bf16 v[108:111], v[156:159], v[172:175], v[108:111]
	s_setprio 0
	s_barrier
	ds_read_b128 v[176:179], v198 offset:16384
	ds_read_b128 v[180:183], v200 offset:16384
	ds_read_b128 v[188:191], v198 offset:18432
	ds_read_b128 v[192:195], v200 offset:18432
	s_waitcnt vmcnt(0)
	s_barrier
	s_waitcnt lgkmcnt(0)
	s_setprio 1
	v_mfma_f32_16x16x32_bf16 v[48:51], v[128:131], v[176:179], v[48:51]
	v_mfma_f32_16x16x32_bf16 v[48:51], v[132:135], v[180:183], v[48:51]
	v_mfma_f32_16x16x32_bf16 v[52:55], v[128:131], v[188:191], v[52:55]
	v_mfma_f32_16x16x32_bf16 v[52:55], v[132:135], v[192:195], v[52:55]
	v_mfma_f32_16x16x32_bf16 v[56:59], v[136:139], v[176:179], v[56:59]
	v_mfma_f32_16x16x32_bf16 v[56:59], v[140:143], v[180:183], v[56:59]
	v_mfma_f32_16x16x32_bf16 v[60:63], v[136:139], v[188:191], v[60:63]
	v_mfma_f32_16x16x32_bf16 v[60:63], v[140:143], v[192:195], v[60:63]
	v_mfma_f32_16x16x32_bf16 v[32:35], v[144:147], v[176:179], v[32:35]
	v_mfma_f32_16x16x32_bf16 v[32:35], v[148:151], v[180:183], v[32:35]
	v_mfma_f32_16x16x32_bf16 v[36:39], v[144:147], v[188:191], v[36:39]
	v_mfma_f32_16x16x32_bf16 v[36:39], v[148:151], v[192:195], v[36:39]
	v_mfma_f32_16x16x32_bf16 v[40:43], v[152:155], v[176:179], v[40:43]
	v_mfma_f32_16x16x32_bf16 v[40:43], v[156:159], v[180:183], v[40:43]
	v_mfma_f32_16x16x32_bf16 v[44:47], v[152:155], v[188:191], v[44:47]
	v_mfma_f32_16x16x32_bf16 v[44:47], v[156:159], v[192:195], v[44:47]
	s_setprio 0
	s_barrier
	ds_read_b128 v[128:131], v186 offset:16384
	ds_read_b128 v[132:135], v196 offset:16384
	ds_read_b128 v[136:139], v186 offset:18432
	ds_read_b128 v[140:143], v196 offset:18432
	ds_read_b128 v[144:147], v186 offset:20480
	ds_read_b128 v[148:151], v196 offset:20480
	ds_read_b128 v[152:155], v186 offset:22528
	ds_read_b128 v[156:159], v196 offset:22528
	s_barrier
	s_waitcnt lgkmcnt(0)
	s_setprio 1
	v_mfma_f32_16x16x32_bf16 v[64:67], v[128:131], v[160:163], v[64:67]
	v_mfma_f32_16x16x32_bf16 v[64:67], v[132:135], v[164:167], v[64:67]
	v_mfma_f32_16x16x32_bf16 v[68:71], v[128:131], v[168:171], v[68:71]
	v_mfma_f32_16x16x32_bf16 v[68:71], v[132:135], v[172:175], v[68:71]
	v_mfma_f32_16x16x32_bf16 v[72:75], v[136:139], v[160:163], v[72:75]
	v_mfma_f32_16x16x32_bf16 v[72:75], v[140:143], v[164:167], v[72:75]
	v_mfma_f32_16x16x32_bf16 v[76:79], v[136:139], v[168:171], v[76:79]
	v_mfma_f32_16x16x32_bf16 v[76:79], v[140:143], v[172:175], v[76:79]
	v_mfma_f32_16x16x32_bf16 v[80:83], v[144:147], v[160:163], v[80:83]
	v_mfma_f32_16x16x32_bf16 v[80:83], v[148:151], v[164:167], v[80:83]
	v_mfma_f32_16x16x32_bf16 v[84:87], v[144:147], v[168:171], v[84:87]
	v_mfma_f32_16x16x32_bf16 v[84:87], v[148:151], v[172:175], v[84:87]
	v_mfma_f32_16x16x32_bf16 v[88:91], v[152:155], v[160:163], v[88:91]
	v_mfma_f32_16x16x32_bf16 v[88:91], v[156:159], v[164:167], v[88:91]
	v_mfma_f32_16x16x32_bf16 v[92:95], v[152:155], v[168:171], v[92:95]
	v_mfma_f32_16x16x32_bf16 v[92:95], v[156:159], v[172:175], v[92:95]
	s_setprio 0
	s_setprio 1
	v_mfma_f32_16x16x32_bf16 v[16:19], v[128:131], v[176:179], v[16:19]
	v_mfma_f32_16x16x32_bf16 v[16:19], v[132:135], v[180:183], v[16:19]
	v_mfma_f32_16x16x32_bf16 v[20:23], v[128:131], v[188:191], v[20:23]
	v_mfma_f32_16x16x32_bf16 v[20:23], v[132:135], v[192:195], v[20:23]
	v_mfma_f32_16x16x32_bf16 v[24:27], v[136:139], v[176:179], v[24:27]
	v_mfma_f32_16x16x32_bf16 v[24:27], v[140:143], v[180:183], v[24:27]
	v_mfma_f32_16x16x32_bf16 v[28:31], v[136:139], v[188:191], v[28:31]
	v_mfma_f32_16x16x32_bf16 v[28:31], v[140:143], v[192:195], v[28:31]
	v_mfma_f32_16x16x32_bf16 v[0:3], v[144:147], v[176:179], v[0:3]
	v_mfma_f32_16x16x32_bf16 v[0:3], v[148:151], v[180:183], v[0:3]
	v_mfma_f32_16x16x32_bf16 v[4:7], v[144:147], v[188:191], v[4:7]
	v_mfma_f32_16x16x32_bf16 v[4:7], v[148:151], v[192:195], v[4:7]
	v_mfma_f32_16x16x32_bf16 v[8:11], v[152:155], v[176:179], v[8:11]
	v_mfma_f32_16x16x32_bf16 v[8:11], v[156:159], v[180:183], v[8:11]
	v_mfma_f32_16x16x32_bf16 v[12:15], v[152:155], v[188:191], v[12:15]
	v_mfma_f32_16x16x32_bf16 v[12:15], v[156:159], v[192:195], v[12:15]
	s_setprio 0
	s_barrier
	s_cmp_lg_u32 s100, 0
	s_cbranch_scc1 .Lg8_p9_eg1
	s_barrier
.Lg8_p9_eg1:
	s_nop 7
	s_nop 7
	v_permlane16_swap_b32_e32 v112, v116
	v_permlane16_swap_b32_e32 v113, v117
	v_permlane16_swap_b32_e32 v114, v118
	v_permlane16_swap_b32_e32 v115, v119
	v_permlane16_swap_b32_e32 v120, v124
	v_permlane16_swap_b32_e32 v121, v125
	v_permlane16_swap_b32_e32 v122, v126
	v_permlane16_swap_b32_e32 v123, v127
	v_permlane16_swap_b32_e32 v96, v100
	v_permlane16_swap_b32_e32 v97, v101
	v_permlane16_swap_b32_e32 v98, v102
	v_permlane16_swap_b32_e32 v99, v103
	v_permlane16_swap_b32_e32 v104, v108
	v_permlane16_swap_b32_e32 v105, v109
	v_permlane16_swap_b32_e32 v106, v110
	v_permlane16_swap_b32_e32 v107, v111
	v_permlane16_swap_b32_e32 v64, v68
	v_permlane16_swap_b32_e32 v65, v69
	v_permlane16_swap_b32_e32 v66, v70
	v_permlane16_swap_b32_e32 v67, v71
	v_permlane16_swap_b32_e32 v72, v76
	v_permlane16_swap_b32_e32 v73, v77
	v_permlane16_swap_b32_e32 v74, v78
	v_permlane16_swap_b32_e32 v75, v79
	v_permlane16_swap_b32_e32 v80, v84
	v_permlane16_swap_b32_e32 v81, v85
	v_permlane16_swap_b32_e32 v82, v86
	v_permlane16_swap_b32_e32 v83, v87
	v_permlane16_swap_b32_e32 v88, v92
	v_permlane16_swap_b32_e32 v89, v93
	v_permlane16_swap_b32_e32 v90, v94
	v_permlane16_swap_b32_e32 v91, v95
	v_permlane16_swap_b32_e32 v48, v52
	v_permlane16_swap_b32_e32 v49, v53
	v_permlane16_swap_b32_e32 v50, v54
	v_permlane16_swap_b32_e32 v51, v55
	v_permlane16_swap_b32_e32 v56, v60
	v_permlane16_swap_b32_e32 v57, v61
	v_permlane16_swap_b32_e32 v58, v62
	v_permlane16_swap_b32_e32 v59, v63
	v_permlane16_swap_b32_e32 v32, v36
	v_permlane16_swap_b32_e32 v33, v37
	v_permlane16_swap_b32_e32 v34, v38
	v_permlane16_swap_b32_e32 v35, v39
	v_permlane16_swap_b32_e32 v40, v44
	v_permlane16_swap_b32_e32 v41, v45
	v_permlane16_swap_b32_e32 v42, v46
	v_permlane16_swap_b32_e32 v43, v47
	v_permlane16_swap_b32_e32 v16, v20
	v_permlane16_swap_b32_e32 v17, v21
	v_permlane16_swap_b32_e32 v18, v22
	v_permlane16_swap_b32_e32 v19, v23
	v_permlane16_swap_b32_e32 v24, v28
	v_permlane16_swap_b32_e32 v25, v29
	v_permlane16_swap_b32_e32 v26, v30
	v_permlane16_swap_b32_e32 v27, v31
	v_permlane16_swap_b32_e32 v0, v4
	v_permlane16_swap_b32_e32 v1, v5
	v_permlane16_swap_b32_e32 v2, v6
	v_permlane16_swap_b32_e32 v3, v7
	v_permlane16_swap_b32_e32 v8, v12
	v_permlane16_swap_b32_e32 v9, v13
	v_permlane16_swap_b32_e32 v10, v14
	v_permlane16_swap_b32_e32 v11, v15
	s_nop 1
	s_ashr_i32 s2, s56, 5
	s_mul_hi_i32 s40, s2, 0x3000
	s_mulk_i32 s2, 0x3000
	v_mov_b32_e32 v194, v208
	s_add_u32 s2, s28, s2
	s_addc_u32 s41, s29, s40
	s_waitcnt vmcnt(1)
	v_lshrrev_b32_e32 v129, 3, v194
	s_lshl_b32 s40, s39, 10
	v_lshlrev_b32_e32 v128, 1, v194
	v_and_b32_e32 v129, 4, v129
	s_add_u32 s40, s2, s40
	v_and_or_b32 v195, v128, s31, v129
	s_addc_u32 s41, s41, 0
	v_lshlrev_b32_e32 v184, 2, v195
	s_waitcnt vmcnt(0)
	v_lshl_add_u64 v[132:133], s[40:41], 0, v[184:185]
	v_add_co_u32_e32 v128, vcc, s38, v132
	v_lshl_add_u64 v[190:191], v[132:133], 0, s[18:19]
	s_nop 0
	v_addc_co_u32_e32 v129, vcc, 0, v133, vcc
	global_load_dwordx4 v[128:131], v[128:129], off
	s_nop 0
	global_load_dwordx4 v[132:135], v[190:191], off offset:32
	global_load_dwordx4 v[136:139], v[190:191], off offset:64
	global_load_dwordx4 v[140:143], v[190:191], off offset:96
	global_load_dwordx4 v[144:147], v[190:191], off offset:128
	global_load_dwordx4 v[148:151], v[190:191], off offset:160
	global_load_dwordx4 v[152:155], v[190:191], off offset:192
	global_load_dwordx4 v[156:159], v[190:191], off offset:224
	global_load_dwordx4 v[160:163], v[190:191], off offset:256
	global_load_dwordx4 v[164:167], v[190:191], off offset:288
	global_load_dwordx4 v[168:171], v[190:191], off offset:320
	global_load_dwordx4 v[172:175], v[190:191], off offset:352
	global_load_dwordx4 v[176:179], v[190:191], off offset:384
	global_load_dwordx4 v[180:183], v[190:191], off offset:416
	global_load_dwordx4 v[186:189], v[190:191], off offset:448
	s_nop 0
	global_load_dwordx4 v[190:193], v[190:191], off offset:480
	v_and_b32_e32 v184, 31, v194
	v_lshrrev_b32_e32 v194, 1, v194
	v_and_or_b32 v184, v194, s30, v184
	v_mul_lo_u32 v184, v184, s37
	v_lshl_add_u32 v184, v195, 1, v184
	s_lshl_b64 s[20:21], s[20:21], 19
	s_add_u32 s2, s24, s20
	s_addc_u32 s21, s25, s21
	s_lshl_b32 s20, s39, 9
	s_add_u32 s20, s2, s20
	s_addc_u32 s21, s21, 0
	s_add_i32 s56, s56, s44
	s_cmpk_lt_i32 s56, 0x200
	s_waitcnt vmcnt(14)
	v_pk_mul_f32 v[116:117], v[116:117], v[132:133]
	v_pk_mul_f32 v[118:119], v[118:119], v[134:135]
	s_waitcnt vmcnt(13)
	v_pk_mul_f32 v[120:121], v[120:121], v[136:137]
	v_pk_mul_f32 v[122:123], v[122:123], v[138:139]
	s_waitcnt vmcnt(12)
	v_pk_mul_f32 v[124:125], v[124:125], v[140:141]
	v_pk_mul_f32 v[126:127], v[126:127], v[142:143]
	s_waitcnt vmcnt(11)
	v_pk_mul_f32 v[96:97], v[96:97], v[144:145]
	s_waitcnt vmcnt(7)
	v_pk_mul_f32 v[64:65], v[64:65], v[160:161]
	v_pk_mul_f32 v[66:67], v[66:67], v[162:163]
	s_waitcnt vmcnt(6)
	v_pk_mul_f32 v[68:69], v[68:69], v[164:165]
	v_pk_mul_f32 v[70:71], v[70:71], v[166:167]
	v_pk_mul_f32 v[98:99], v[98:99], v[146:147]
	v_pk_mul_f32 v[100:101], v[100:101], v[148:149]
	v_pk_mul_f32 v[112:113], v[112:113], v[128:129]
	v_pk_mul_f32 v[114:115], v[114:115], v[130:131]
	v_pk_mul_f32 v[102:103], v[102:103], v[150:151]
	v_pk_mul_f32 v[104:105], v[104:105], v[152:153]
	v_pk_mul_f32 v[106:107], v[106:107], v[154:155]
	v_pk_mul_f32 v[108:109], v[108:109], v[156:157]
	v_pk_mul_f32 v[110:111], v[110:111], v[158:159]
	v_cvt_pk_bf16_f32 v112, v112, v113
	v_cvt_pk_bf16_f32 v113, v114, v115
	v_cvt_pk_bf16_f32 v114, v116, v117
	v_cvt_pk_bf16_f32 v115, v118, v119
	v_cvt_pk_bf16_f32 v64, v64, v65
	v_cvt_pk_bf16_f32 v65, v66, v67
	v_cvt_pk_bf16_f32 v66, v68, v69
	v_cvt_pk_bf16_f32 v67, v70, v71
	v_cvt_pk_bf16_f32 v116, v120, v121
	v_cvt_pk_bf16_f32 v117, v122, v123
	v_cvt_pk_bf16_f32 v118, v124, v125
	v_cvt_pk_bf16_f32 v119, v126, v127
	v_cvt_pk_bf16_f32 v96, v96, v97
	v_cvt_pk_bf16_f32 v97, v98, v99
	v_cvt_pk_bf16_f32 v98, v100, v101
	v_cvt_pk_bf16_f32 v99, v102, v103
	v_cvt_pk_bf16_f32 v100, v104, v105
	v_cvt_pk_bf16_f32 v101, v106, v107
	v_cvt_pk_bf16_f32 v102, v108, v109
	v_cvt_pk_bf16_f32 v103, v110, v111
	ds_write2_b64 v184, v[112:113], v[114:115] offset1:2
	ds_write2_b64 v184, v[116:117], v[118:119] offset0:4 offset1:6
	ds_write2_b64 v184, v[96:97], v[98:99] offset0:8 offset1:10
	ds_write2_b64 v184, v[100:101], v[102:103] offset0:12 offset1:14
	ds_write2_b64 v184, v[64:65], v[66:67] offset0:16 offset1:18
	s_waitcnt vmcnt(5)
	v_pk_mul_f32 v[64:65], v[72:73], v[168:169]
	v_pk_mul_f32 v[66:67], v[74:75], v[170:171]
	v_cvt_pk_bf16_f32 v64, v64, v65
	v_cvt_pk_bf16_f32 v65, v66, v67
	s_waitcnt vmcnt(4)
	v_pk_mul_f32 v[66:67], v[76:77], v[172:173]
	v_pk_mul_f32 v[68:69], v[78:79], v[174:175]
	v_cvt_pk_bf16_f32 v66, v66, v67
	v_cvt_pk_bf16_f32 v67, v68, v69
	ds_write2_b64 v184, v[64:65], v[66:67] offset0:20 offset1:22
	s_waitcnt vmcnt(3)
	v_pk_mul_f32 v[64:65], v[80:81], v[176:177]
	v_pk_mul_f32 v[66:67], v[82:83], v[178:179]
	v_pk_mul_f32 v[48:49], v[48:49], v[128:129]
	v_pk_mul_f32 v[50:51], v[50:51], v[130:131]
	v_pk_mul_f32 v[32:33], v[32:33], v[144:145]
	v_pk_mul_f32 v[34:35], v[34:35], v[146:147]
	v_pk_mul_f32 v[16:17], v[16:17], v[160:161]
	v_pk_mul_f32 v[18:19], v[18:19], v[162:163]
	v_pk_mul_f32 v[0:1], v[0:1], v[176:177]
	v_pk_mul_f32 v[2:3], v[2:3], v[178:179]
	v_cvt_pk_bf16_f32 v64, v64, v65
	v_cvt_pk_bf16_f32 v65, v66, v67
	s_waitcnt vmcnt(2)
	v_pk_mul_f32 v[66:67], v[84:85], v[180:181]
	v_pk_mul_f32 v[68:69], v[86:87], v[182:183]
	v_cvt_pk_bf16_f32 v48, v48, v49
	v_cvt_pk_bf16_f32 v49, v50, v51
	v_pk_mul_f32 v[50:51], v[52:53], v[132:133]
	v_pk_mul_f32 v[52:53], v[54:55], v[134:135]
	v_cvt_pk_bf16_f32 v32, v32, v33
	v_cvt_pk_bf16_f32 v33, v34, v35
	v_pk_mul_f32 v[34:35], v[36:37], v[148:149]
	v_pk_mul_f32 v[36:37], v[38:39], v[150:151]
	v_cvt_pk_bf16_f32 v16, v16, v17
	v_cvt_pk_bf16_f32 v17, v18, v19
	v_pk_mul_f32 v[18:19], v[20:21], v[164:165]
	v_pk_mul_f32 v[20:21], v[22:23], v[166:167]
	v_cvt_pk_bf16_f32 v0, v0, v1
	v_cvt_pk_bf16_f32 v1, v2, v3
	v_pk_mul_f32 v[2:3], v[4:5], v[180:181]
	v_pk_mul_f32 v[4:5], v[6:7], v[182:183]
	v_cvt_pk_bf16_f32 v66, v66, v67
	v_cvt_pk_bf16_f32 v67, v68, v69
	v_cvt_pk_bf16_f32 v50, v50, v51
	v_cvt_pk_bf16_f32 v51, v52, v53
	v_add_u32_e32 v54, 0x4000, v184
	v_cvt_pk_bf16_f32 v34, v34, v35
	v_cvt_pk_bf16_f32 v35, v36, v37
	v_cvt_pk_bf16_f32 v18, v18, v19
	v_cvt_pk_bf16_f32 v19, v20, v21
	v_cvt_pk_bf16_f32 v2, v2, v3
	v_cvt_pk_bf16_f32 v3, v4, v5
	ds_write2_b64 v184, v[64:65], v[66:67] offset0:24 offset1:26
	s_waitcnt vmcnt(1)
	v_pk_mul_f32 v[64:65], v[88:89], v[186:187]
	v_pk_mul_f32 v[66:67], v[90:91], v[188:189]
	ds_write2_b64 v54, v[48:49], v[50:51] offset0:64 offset1:66
	v_pk_mul_f32 v[48:49], v[56:57], v[136:137]
	v_pk_mul_f32 v[50:51], v[58:59], v[138:139]
	ds_write2_b64 v54, v[32:33], v[34:35] offset0:72 offset1:74
	v_pk_mul_f32 v[32:33], v[40:41], v[152:153]
	v_pk_mul_f32 v[34:35], v[42:43], v[154:155]
	ds_write2_b64 v54, v[16:17], v[18:19] offset0:80 offset1:82
	v_pk_mul_f32 v[16:17], v[24:25], v[168:169]
	v_pk_mul_f32 v[18:19], v[26:27], v[170:171]
	ds_write2_b64 v54, v[0:1], v[2:3] offset0:88 offset1:90
	v_pk_mul_f32 v[0:1], v[8:9], v[186:187]
	v_pk_mul_f32 v[2:3], v[10:11], v[188:189]
	v_cvt_pk_bf16_f32 v64, v64, v65
	v_cvt_pk_bf16_f32 v65, v66, v67
	s_waitcnt vmcnt(0)
	v_pk_mul_f32 v[66:67], v[92:93], v[190:191]
	v_pk_mul_f32 v[68:69], v[94:95], v[192:193]
	v_cvt_pk_bf16_f32 v48, v48, v49
	v_cvt_pk_bf16_f32 v49, v50, v51
	v_pk_mul_f32 v[50:51], v[60:61], v[140:141]
	v_pk_mul_f32 v[52:53], v[62:63], v[142:143]
	v_cvt_pk_bf16_f32 v32, v32, v33
	v_cvt_pk_bf16_f32 v33, v34, v35
	v_pk_mul_f32 v[34:35], v[44:45], v[156:157]
	v_pk_mul_f32 v[36:37], v[46:47], v[158:159]
	v_cvt_pk_bf16_f32 v16, v16, v17
	v_cvt_pk_bf16_f32 v17, v18, v19
	v_pk_mul_f32 v[18:19], v[28:29], v[172:173]
	v_pk_mul_f32 v[20:21], v[30:31], v[174:175]
	v_cvt_pk_bf16_f32 v0, v0, v1
	v_cvt_pk_bf16_f32 v1, v2, v3
	v_pk_mul_f32 v[2:3], v[12:13], v[190:191]
	v_pk_mul_f32 v[4:5], v[14:15], v[192:193]
	v_cvt_pk_bf16_f32 v66, v66, v67
	v_cvt_pk_bf16_f32 v67, v68, v69
	v_cvt_pk_bf16_f32 v50, v50, v51
	v_cvt_pk_bf16_f32 v51, v52, v53
	v_cvt_pk_bf16_f32 v34, v34, v35
	v_cvt_pk_bf16_f32 v35, v36, v37
	v_cvt_pk_bf16_f32 v18, v18, v19
	v_cvt_pk_bf16_f32 v19, v20, v21
	v_cvt_pk_bf16_f32 v2, v2, v3
	v_cvt_pk_bf16_f32 v3, v4, v5
	v_mov_b32_e32 v14, v208
	ds_write2_b64 v184, v[64:65], v[66:67] offset0:28 offset1:30
	ds_write2_b64 v54, v[48:49], v[50:51] offset0:68 offset1:70
	ds_write2_b64 v54, v[32:33], v[34:35] offset0:76 offset1:78
	ds_write2_b64 v54, v[16:17], v[18:19] offset0:84 offset1:86
	ds_write2_b64 v54, v[0:1], v[2:3] offset0:92 offset1:94
	s_waitcnt lgkmcnt(0)
	v_lshlrev_b32_e32 v0, 4, v14
	v_ashrrev_i32_e32 v4, 5, v14
	v_and_b32_e32 v184, 0x1f0, v0
	v_ashrrev_i32_e32 v5, 31, v4
	v_lshl_add_u64 v[8:9], s[20:21], 0, v[184:185]
	v_mad_u64_u32 v[0:1], s[20:21], v4, s37, v[184:185]
	v_lshlrev_b64 v[4:5], 11, v[4:5]
	v_lshl_add_u64 v[10:11], v[8:9], 0, v[4:5]
	v_add_u32_e32 v4, 0x200, v14
	s_barrier
	ds_read_b128 v[0:3], v0
	v_ashrrev_i32_e32 v12, 5, v4
	v_mad_u64_u32 v[4:5], s[20:21], v12, s37, v[184:185]
	ds_read_b128 v[4:7], v4
	v_ashrrev_i32_e32 v13, 31, v12
	s_waitcnt lgkmcnt(1)
	global_store_dwordx4 v[10:11], v[0:3], off
	s_nop 1
	v_lshlrev_b64 v[0:1], 11, v[12:13]
	v_lshl_add_u64 v[0:1], v[8:9], 0, v[0:1]
	s_waitcnt lgkmcnt(0)
	global_store_dwordx4 v[0:1], v[4:7], off
	v_add_u32_e32 v0, 0x400, v14
	s_nop 0
	v_ashrrev_i32_e32 v4, 5, v0
	v_ashrrev_i32_e32 v5, 31, v4
	v_mad_u64_u32 v[0:1], s[20:21], v4, s37, v[184:185]
	v_lshlrev_b64 v[4:5], 11, v[4:5]
	v_lshl_add_u64 v[10:11], v[8:9], 0, v[4:5]
	v_add_u32_e32 v4, 0x600, v14
	ds_read_b128 v[0:3], v0
	v_ashrrev_i32_e32 v12, 5, v4
	v_mad_u64_u32 v[4:5], s[20:21], v12, s37, v[184:185]
	ds_read_b128 v[4:7], v4
	v_ashrrev_i32_e32 v13, 31, v12
	s_waitcnt lgkmcnt(1)
	global_store_dwordx4 v[10:11], v[0:3], off
	s_nop 1
	v_lshlrev_b64 v[0:1], 11, v[12:13]
	v_lshl_add_u64 v[0:1], v[8:9], 0, v[0:1]
	s_waitcnt lgkmcnt(0)
	global_store_dwordx4 v[0:1], v[4:7], off
	v_add_u32_e32 v0, 0x800, v14
	s_nop 0
	v_ashrrev_i32_e32 v4, 5, v0
	v_ashrrev_i32_e32 v5, 31, v4
	v_mad_u64_u32 v[0:1], s[20:21], v4, s37, v[184:185]
	v_lshlrev_b64 v[4:5], 11, v[4:5]
	v_lshl_add_u64 v[10:11], v[8:9], 0, v[4:5]
	v_add_u32_e32 v4, 0xa00, v14
	ds_read_b128 v[0:3], v0
	v_ashrrev_i32_e32 v12, 5, v4
	v_mad_u64_u32 v[4:5], s[20:21], v12, s37, v[184:185]
	ds_read_b128 v[4:7], v4
	v_ashrrev_i32_e32 v13, 31, v12
	s_waitcnt lgkmcnt(1)
	global_store_dwordx4 v[10:11], v[0:3], off
	s_nop 1
	v_lshlrev_b64 v[0:1], 11, v[12:13]
	v_lshl_add_u64 v[0:1], v[8:9], 0, v[0:1]
	s_waitcnt lgkmcnt(0)
	global_store_dwordx4 v[0:1], v[4:7], off
	v_add_u32_e32 v0, 0xc00, v14
	s_nop 0
	v_ashrrev_i32_e32 v4, 5, v0
	v_ashrrev_i32_e32 v5, 31, v4
	v_mad_u64_u32 v[0:1], s[20:21], v4, s37, v[184:185]
	v_lshlrev_b64 v[4:5], 11, v[4:5]
	v_lshl_add_u64 v[10:11], v[8:9], 0, v[4:5]
	v_add_u32_e32 v4, 0xe00, v14
	ds_read_b128 v[0:3], v0
	v_ashrrev_i32_e32 v12, 5, v4
	v_mad_u64_u32 v[4:5], s[20:21], v12, s37, v[184:185]
	ds_read_b128 v[4:7], v4
	v_ashrrev_i32_e32 v13, 31, v12
	s_waitcnt lgkmcnt(1)
	global_store_dwordx4 v[10:11], v[0:3], off
	s_nop 1
	v_lshlrev_b64 v[0:1], 11, v[12:13]
	v_lshl_add_u64 v[0:1], v[8:9], 0, v[0:1]
	s_waitcnt lgkmcnt(0)
	global_store_dwordx4 v[0:1], v[4:7], off
	v_add_u32_e32 v0, 0x1000, v14
	s_nop 0
	v_ashrrev_i32_e32 v4, 5, v0
	v_ashrrev_i32_e32 v5, 31, v4
	v_mad_u64_u32 v[0:1], s[20:21], v4, s37, v[184:185]
	v_lshlrev_b64 v[4:5], 11, v[4:5]
	v_lshl_add_u64 v[10:11], v[8:9], 0, v[4:5]
	v_add_u32_e32 v4, 0x1200, v14
	ds_read_b128 v[0:3], v0
	v_ashrrev_i32_e32 v12, 5, v4
	v_mad_u64_u32 v[4:5], s[20:21], v12, s37, v[184:185]
	ds_read_b128 v[4:7], v4
	v_ashrrev_i32_e32 v13, 31, v12
	s_waitcnt lgkmcnt(1)
	global_store_dwordx4 v[10:11], v[0:3], off
	s_nop 1
	v_lshlrev_b64 v[0:1], 11, v[12:13]
	v_lshl_add_u64 v[0:1], v[8:9], 0, v[0:1]
	s_waitcnt lgkmcnt(0)
	global_store_dwordx4 v[0:1], v[4:7], off
	v_add_u32_e32 v0, 0x1400, v14
	s_nop 0
	v_ashrrev_i32_e32 v4, 5, v0
	v_ashrrev_i32_e32 v5, 31, v4
	v_mad_u64_u32 v[0:1], s[20:21], v4, s37, v[184:185]
	v_lshlrev_b64 v[4:5], 11, v[4:5]
	v_lshl_add_u64 v[10:11], v[8:9], 0, v[4:5]
	v_add_u32_e32 v4, 0x1600, v14
	ds_read_b128 v[0:3], v0
	v_ashrrev_i32_e32 v12, 5, v4
	v_mad_u64_u32 v[4:5], s[20:21], v12, s37, v[184:185]
	ds_read_b128 v[4:7], v4
	v_ashrrev_i32_e32 v13, 31, v12
	s_waitcnt lgkmcnt(1)
	global_store_dwordx4 v[10:11], v[0:3], off
	s_nop 1
	v_lshlrev_b64 v[0:1], 11, v[12:13]
	v_lshl_add_u64 v[0:1], v[8:9], 0, v[0:1]
	s_waitcnt lgkmcnt(0)
	global_store_dwordx4 v[0:1], v[4:7], off
	v_add_u32_e32 v0, 0x1800, v14
	s_nop 0
	v_ashrrev_i32_e32 v4, 5, v0
	v_ashrrev_i32_e32 v5, 31, v4
	v_mad_u64_u32 v[0:1], s[20:21], v4, s37, v[184:185]
	v_lshlrev_b64 v[4:5], 11, v[4:5]
	v_lshl_add_u64 v[10:11], v[8:9], 0, v[4:5]
	v_add_u32_e32 v4, 0x1a00, v14
	ds_read_b128 v[0:3], v0
	v_ashrrev_i32_e32 v12, 5, v4
	v_mad_u64_u32 v[4:5], s[20:21], v12, s37, v[184:185]
	ds_read_b128 v[4:7], v4
	v_ashrrev_i32_e32 v13, 31, v12
	s_waitcnt lgkmcnt(1)
	global_store_dwordx4 v[10:11], v[0:3], off
	s_nop 1
	v_lshlrev_b64 v[0:1], 11, v[12:13]
	v_lshl_add_u64 v[0:1], v[8:9], 0, v[0:1]
	s_waitcnt lgkmcnt(0)
	global_store_dwordx4 v[0:1], v[4:7], off
	v_add_u32_e32 v0, 0x1c00, v14
	s_nop 0
	v_ashrrev_i32_e32 v4, 5, v0
	v_ashrrev_i32_e32 v5, 31, v4
	v_mad_u64_u32 v[0:1], s[20:21], v4, s37, v[184:185]
	v_lshlrev_b64 v[4:5], 11, v[4:5]
	v_lshl_add_u64 v[10:11], v[8:9], 0, v[4:5]
	v_add_u32_e32 v4, 0x1e00, v14
	ds_read_b128 v[0:3], v0
	v_ashrrev_i32_e32 v12, 5, v4
	v_mad_u64_u32 v[4:5], s[20:21], v12, s37, v[184:185]
	ds_read_b128 v[4:7], v4
	v_ashrrev_i32_e32 v13, 31, v12
	s_waitcnt lgkmcnt(1)
	global_store_dwordx4 v[10:11], v[0:3], off
	s_nop 1
	v_lshlrev_b64 v[0:1], 11, v[12:13]
	v_lshl_add_u64 v[0:1], v[8:9], 0, v[0:1]
	s_waitcnt lgkmcnt(0)
	global_store_dwordx4 v[0:1], v[4:7], off
	s_barrier
	s_cbranch_scc1 .LBB0_1393
